# K-loop critical path: s_setprio 1 moved in front of the barrier that opens each MFMA segment (wave raises priority while parked; first instruction after the release is the MFMA)
# baseline (speedup 1.0000x reference)
.LBB0_143:
	ds_read_b128 v[168:171], v163
	ds_read_b128 v[172:175], v163 offset:1024
	ds_read_b128 v[176:179], v163 offset:2048
	ds_read_b128 v[180:183], v163 offset:3072
	ds_read_b128 v[184:187], v164
	ds_read_b128 v[188:191], v164 offset:1024
	ds_read_b128 v[192:195], v164 offset:2048
	ds_read_b128 v[196:199], v164 offset:3072
	s_add_u32 s26, s24, 0xfff80080
	s_addc_u32 s27, s25, -1
	s_cmp_eq_u32 s62, 28
	s_cselect_b32 s31, s15, s27
	s_cselect_b32 s30, s23, s26
	s_cselect_b32 s27, s13, s61
	s_cselect_b32 s26, s59, s60
	v_lshl_add_u64 v[154:155], s[24:25], 0, v[144:145]
	s_add_i32 m0, s43, 0xc000
	ds_read_b128 v[200:203], v165
	ds_read_b128 v[204:207], v165 offset:1024
	ds_read_b128 v[208:211], v165 offset:2048
	ds_read_b128 v[212:215], v165 offset:3072
	ds_read_b128 v[216:219], v165 offset:4096
	ds_read_b128 v[220:223], v165 offset:5120
	ds_read_b128 v[224:227], v165 offset:6144
	ds_read_b128 v[228:231], v165 offset:7168
	global_load_lds_dwordx4 v[154:155], off
	v_lshl_add_u64 v[154:155], s[24:25], 0, v[142:143]
	s_add_i32 m0, s43, 0xe000
	s_nop 0
	global_load_lds_dwordx4 v[154:155], off
	s_waitcnt vmcnt(8)
	s_waitcnt lgkmcnt(0)
	s_setprio 1
	s_barrier
	v_mfma_f32_16x16x32_bf16 v[126:129], v[168:171], v[200:203], v[126:129]
	v_mfma_f32_16x16x32_bf16 v[122:125], v[176:179], v[200:203], v[122:125]
	v_mfma_f32_16x16x32_bf16 v[114:117], v[168:171], v[208:211], v[114:117]
	v_mfma_f32_16x16x32_bf16 v[106:109], v[176:179], v[208:211], v[106:109]
	v_mfma_f32_16x16x32_bf16 v[98:101], v[168:171], v[216:219], v[98:101]
	v_mfma_f32_16x16x32_bf16 v[90:93], v[176:179], v[216:219], v[90:93]
	v_mfma_f32_16x16x32_bf16 v[82:85], v[168:171], v[224:227], v[82:85]
	v_mfma_f32_16x16x32_bf16 v[74:77], v[176:179], v[224:227], v[74:77]
	v_mfma_f32_16x16x32_bf16 v[126:129], v[172:175], v[204:207], v[126:129]
	v_mfma_f32_16x16x32_bf16 v[122:125], v[180:183], v[204:207], v[122:125]
	v_mfma_f32_16x16x32_bf16 v[114:117], v[172:175], v[212:215], v[114:117]
	v_mfma_f32_16x16x32_bf16 v[106:109], v[180:183], v[212:215], v[106:109]
	v_mfma_f32_16x16x32_bf16 v[98:101], v[172:175], v[220:223], v[98:101]
	v_mfma_f32_16x16x32_bf16 v[90:93], v[180:183], v[220:223], v[90:93]
	v_mfma_f32_16x16x32_bf16 v[82:85], v[172:175], v[228:231], v[82:85]
	v_mfma_f32_16x16x32_bf16 v[74:77], v[180:183], v[228:231], v[74:77]
	s_setprio 0
	s_setprio 1
	v_mfma_f32_16x16x32_bf16 v[118:121], v[184:187], v[200:203], v[118:121]
	v_mfma_f32_16x16x32_bf16 v[110:113], v[192:195], v[200:203], v[110:113]
	v_mfma_f32_16x16x32_bf16 v[102:105], v[184:187], v[208:211], v[102:105]
	v_mfma_f32_16x16x32_bf16 v[94:97], v[192:195], v[208:211], v[94:97]
	v_mfma_f32_16x16x32_bf16 v[86:89], v[184:187], v[216:219], v[86:89]
	v_mfma_f32_16x16x32_bf16 v[78:81], v[192:195], v[216:219], v[78:81]
	v_mfma_f32_16x16x32_bf16 v[70:73], v[184:187], v[224:227], v[70:73]
	v_mfma_f32_16x16x32_bf16 v[66:69], v[192:195], v[224:227], v[66:69]
	v_mfma_f32_16x16x32_bf16 v[118:121], v[188:191], v[204:207], v[118:121]
	v_mfma_f32_16x16x32_bf16 v[110:113], v[196:199], v[204:207], v[110:113]
	v_mfma_f32_16x16x32_bf16 v[102:105], v[188:191], v[212:215], v[102:105]
	v_mfma_f32_16x16x32_bf16 v[94:97], v[196:199], v[212:215], v[94:97]
	v_mfma_f32_16x16x32_bf16 v[86:89], v[188:191], v[220:223], v[86:89]
	v_mfma_f32_16x16x32_bf16 v[78:81], v[196:199], v[220:223], v[78:81]
	v_mfma_f32_16x16x32_bf16 v[70:73], v[188:191], v[228:231], v[70:73]
	v_mfma_f32_16x16x32_bf16 v[66:69], v[196:199], v[228:231], v[66:69]
	s_barrier
	s_setprio 0
	s_add_i32 s63, s55, s42
	v_lshl_add_u64 v[154:155], s[26:27], 0, v[132:133]
	s_mov_b32 m0, s63
	ds_read_b128 v[200:203], v165 offset:16384
	ds_read_b128 v[204:207], v165 offset:17408
	ds_read_b128 v[208:211], v165 offset:18432
	ds_read_b128 v[212:215], v165 offset:19456
	ds_read_b128 v[216:219], v165 offset:20480
	ds_read_b128 v[220:223], v165 offset:21504
	ds_read_b128 v[224:227], v165 offset:22528
	ds_read_b128 v[228:231], v165 offset:23552
	global_load_lds_dwordx4 v[154:155], off
	s_add_i32 m0, s63, 0x2000
	s_add_u32 s64, s26, 0x80000
	v_lshl_add_u64 v[232:233], s[26:27], 0, v[136:137]
	s_addc_u32 s65, s27, 0
	s_add_i32 s63, s56, s42
	global_load_lds_dwordx4 v[232:233], off
	v_lshl_add_u64 v[234:235], s[64:65], 0, v[132:133]
	s_mov_b32 m0, s63
	v_lshl_add_u64 v[236:237], s[30:31], 0, v[134:135]
	global_load_lds_dwordx4 v[234:235], off
	v_lshl_add_u64 v[234:235], s[64:65], 0, v[136:137]
	s_add_i32 m0, s63, 0x2000
	s_nop 0
	global_load_lds_dwordx4 v[234:235], off
	v_lshl_add_u64 v[234:235], s[30:31], 0, v[130:131]
	s_mov_b32 m0, s43
	s_nop 0
	global_load_lds_dwordx4 v[234:235], off
	s_mov_b32 m0, s44
	s_nop 0
	global_load_lds_dwordx4 v[236:237], off
	s_waitcnt vmcnt(8)
	s_waitcnt lgkmcnt(0)
	s_setprio 1
	s_barrier
	v_mfma_f32_16x16x32_bf16 v[62:65], v[168:171], v[200:203], v[62:65]
	v_mfma_f32_16x16x32_bf16 v[58:61], v[176:179], v[200:203], v[58:61]
	v_mfma_f32_16x16x32_bf16 v[50:53], v[168:171], v[208:211], v[50:53]
	v_mfma_f32_16x16x32_bf16 v[42:45], v[176:179], v[208:211], v[42:45]
	v_mfma_f32_16x16x32_bf16 v[34:37], v[168:171], v[216:219], v[34:37]
	v_mfma_f32_16x16x32_bf16 v[26:29], v[176:179], v[216:219], v[26:29]
	v_mfma_f32_16x16x32_bf16 v[18:21], v[168:171], v[224:227], v[18:21]
	v_mfma_f32_16x16x32_bf16 v[10:13], v[176:179], v[224:227], v[10:13]
	v_mfma_f32_16x16x32_bf16 v[62:65], v[172:175], v[204:207], v[62:65]
	v_mfma_f32_16x16x32_bf16 v[58:61], v[180:183], v[204:207], v[58:61]
	v_mfma_f32_16x16x32_bf16 v[50:53], v[172:175], v[212:215], v[50:53]
	v_mfma_f32_16x16x32_bf16 v[42:45], v[180:183], v[212:215], v[42:45]
	v_mfma_f32_16x16x32_bf16 v[34:37], v[172:175], v[220:223], v[34:37]
	v_mfma_f32_16x16x32_bf16 v[26:29], v[180:183], v[220:223], v[26:29]
	v_mfma_f32_16x16x32_bf16 v[18:21], v[172:175], v[228:231], v[18:21]
	v_mfma_f32_16x16x32_bf16 v[10:13], v[180:183], v[228:231], v[10:13]
	s_setprio 0
	s_setprio 1
	v_mfma_f32_16x16x32_bf16 v[54:57], v[184:187], v[200:203], v[54:57]
	v_mfma_f32_16x16x32_bf16 v[46:49], v[192:195], v[200:203], v[46:49]
	v_mfma_f32_16x16x32_bf16 v[38:41], v[184:187], v[208:211], v[38:41]
	v_mfma_f32_16x16x32_bf16 v[30:33], v[192:195], v[208:211], v[30:33]
	v_mfma_f32_16x16x32_bf16 v[22:25], v[184:187], v[216:219], v[22:25]
	v_mfma_f32_16x16x32_bf16 v[14:17], v[192:195], v[216:219], v[14:17]
	v_mfma_f32_16x16x32_bf16 v[6:9], v[184:187], v[224:227], v[6:9]
	v_mfma_f32_16x16x32_bf16 v[2:5], v[192:195], v[224:227], v[2:5]
	v_mfma_f32_16x16x32_bf16 v[54:57], v[188:191], v[204:207], v[54:57]
	v_mfma_f32_16x16x32_bf16 v[46:49], v[196:199], v[204:207], v[46:49]
	v_mfma_f32_16x16x32_bf16 v[38:41], v[188:191], v[212:215], v[38:41]
	v_mfma_f32_16x16x32_bf16 v[30:33], v[196:199], v[212:215], v[30:33]
	v_mfma_f32_16x16x32_bf16 v[22:25], v[188:191], v[220:223], v[22:25]
	v_mfma_f32_16x16x32_bf16 v[14:17], v[196:199], v[220:223], v[14:17]
	v_mfma_f32_16x16x32_bf16 v[6:9], v[188:191], v[228:231], v[6:9]
	v_mfma_f32_16x16x32_bf16 v[2:5], v[196:199], v[228:231], v[2:5]
	s_barrier
	s_setprio 0
	s_add_i32 s63, 0, 0x18000
	v_add_u32_e32 v138, s63, v159
	s_add_i32 s64, 0, 0x1c000
	ds_read_b128 v[168:171], v138
	ds_read_b128 v[172:175], v138 offset:1024
	ds_read_b128 v[176:179], v138 offset:2048
	ds_read_b128 v[180:183], v138 offset:3072
	v_add_u32_e32 v138, s64, v159
	ds_read_b128 v[184:187], v138
	ds_read_b128 v[188:191], v138 offset:1024
	ds_read_b128 v[192:195], v138 offset:2048
	ds_read_b128 v[196:199], v138 offset:3072
	s_add_u32 s30, s30, 0x80000
	s_addc_u32 s31, s31, 0
	s_mov_b32 m0, s45
	v_lshl_add_u64 v[238:239], s[30:31], 0, v[130:131]
	ds_read_b128 v[200:203], v165 offset:32768
	ds_read_b128 v[204:207], v165 offset:33792
	ds_read_b128 v[208:211], v165 offset:34816
	ds_read_b128 v[212:215], v165 offset:35840
	ds_read_b128 v[216:219], v165 offset:36864
	ds_read_b128 v[220:223], v165 offset:37888
	ds_read_b128 v[224:227], v165 offset:38912
	ds_read_b128 v[228:231], v165 offset:39936
	global_load_lds_dwordx4 v[238:239], off
	v_lshl_add_u64 v[238:239], s[30:31], 0, v[134:135]
	s_mov_b32 m0, s46
	s_nop 0
	global_load_lds_dwordx4 v[238:239], off
	s_waitcnt vmcnt(8)
	s_waitcnt lgkmcnt(0)
	s_setprio 1
	s_barrier
	v_mfma_f32_16x16x32_bf16 v[126:129], v[168:171], v[200:203], v[126:129]
	v_mfma_f32_16x16x32_bf16 v[122:125], v[176:179], v[200:203], v[122:125]
	v_mfma_f32_16x16x32_bf16 v[114:117], v[168:171], v[208:211], v[114:117]
	v_mfma_f32_16x16x32_bf16 v[106:109], v[176:179], v[208:211], v[106:109]
	v_mfma_f32_16x16x32_bf16 v[98:101], v[168:171], v[216:219], v[98:101]
	v_mfma_f32_16x16x32_bf16 v[90:93], v[176:179], v[216:219], v[90:93]
	v_mfma_f32_16x16x32_bf16 v[82:85], v[168:171], v[224:227], v[82:85]
	v_mfma_f32_16x16x32_bf16 v[74:77], v[176:179], v[224:227], v[74:77]
	v_mfma_f32_16x16x32_bf16 v[126:129], v[172:175], v[204:207], v[126:129]
	v_mfma_f32_16x16x32_bf16 v[122:125], v[180:183], v[204:207], v[122:125]
	v_mfma_f32_16x16x32_bf16 v[114:117], v[172:175], v[212:215], v[114:117]
	v_mfma_f32_16x16x32_bf16 v[106:109], v[180:183], v[212:215], v[106:109]
	v_mfma_f32_16x16x32_bf16 v[98:101], v[172:175], v[220:223], v[98:101]
	v_mfma_f32_16x16x32_bf16 v[90:93], v[180:183], v[220:223], v[90:93]
	v_mfma_f32_16x16x32_bf16 v[82:85], v[172:175], v[228:231], v[82:85]
	v_mfma_f32_16x16x32_bf16 v[74:77], v[180:183], v[228:231], v[74:77]
	s_setprio 0
	s_setprio 1
	v_mfma_f32_16x16x32_bf16 v[118:121], v[184:187], v[200:203], v[118:121]
	v_mfma_f32_16x16x32_bf16 v[110:113], v[192:195], v[200:203], v[110:113]
	v_mfma_f32_16x16x32_bf16 v[102:105], v[184:187], v[208:211], v[102:105]
	v_mfma_f32_16x16x32_bf16 v[94:97], v[192:195], v[208:211], v[94:97]
	v_mfma_f32_16x16x32_bf16 v[86:89], v[184:187], v[216:219], v[86:89]
	v_mfma_f32_16x16x32_bf16 v[78:81], v[192:195], v[216:219], v[78:81]
	v_mfma_f32_16x16x32_bf16 v[70:73], v[184:187], v[224:227], v[70:73]
	v_mfma_f32_16x16x32_bf16 v[66:69], v[192:195], v[224:227], v[66:69]
	v_mfma_f32_16x16x32_bf16 v[118:121], v[188:191], v[204:207], v[118:121]
	v_mfma_f32_16x16x32_bf16 v[110:113], v[196:199], v[204:207], v[110:113]
	v_mfma_f32_16x16x32_bf16 v[102:105], v[188:191], v[212:215], v[102:105]
	v_mfma_f32_16x16x32_bf16 v[94:97], v[196:199], v[212:215], v[94:97]
	v_mfma_f32_16x16x32_bf16 v[86:89], v[188:191], v[220:223], v[86:89]
	v_mfma_f32_16x16x32_bf16 v[78:81], v[196:199], v[220:223], v[78:81]
	v_mfma_f32_16x16x32_bf16 v[70:73], v[188:191], v[228:231], v[70:73]
	v_mfma_f32_16x16x32_bf16 v[66:69], v[196:199], v[228:231], v[66:69]
	s_barrier
	s_setprio 0
	s_add_i32 s30, s63, s42
	v_lshl_add_u64 v[154:155], v[154:155], 0, s[8:9]
	s_mov_b32 m0, s30
	ds_read_b128 v[200:203], v165 offset:49152
	ds_read_b128 v[204:207], v165 offset:50176
	ds_read_b128 v[208:211], v165 offset:51200
	ds_read_b128 v[212:215], v165 offset:52224
	ds_read_b128 v[216:219], v165 offset:53248
	ds_read_b128 v[220:223], v165 offset:54272
	ds_read_b128 v[224:227], v165 offset:55296
	ds_read_b128 v[228:231], v165 offset:56320
	global_load_lds_dwordx4 v[154:155], off
	s_add_i32 m0, s30, 0x2000
	s_add_u32 s26, s26, 0x80080
	v_lshl_add_u64 v[154:155], v[232:233], 0, s[8:9]
	s_addc_u32 s27, s27, 0
	s_add_i32 s30, s64, s42
	global_load_lds_dwordx4 v[154:155], off
	v_lshl_add_u64 v[154:155], s[26:27], 0, v[132:133]
	s_mov_b32 m0, s30
	s_nop 0
	global_load_lds_dwordx4 v[154:155], off
	v_lshl_add_u64 v[154:155], s[26:27], 0, v[136:137]
	s_add_i32 m0, s30, 0x2000
	s_nop 0
	global_load_lds_dwordx4 v[154:155], off
	v_lshl_add_u64 v[154:155], v[234:235], 0, s[8:9]
	s_mov_b32 m0, s51
	s_nop 0
	global_load_lds_dwordx4 v[154:155], off
	v_lshl_add_u64 v[154:155], v[236:237], 0, s[8:9]
	s_mov_b32 m0, s53
	s_nop 0
	global_load_lds_dwordx4 v[154:155], off
	s_waitcnt vmcnt(8)
	s_waitcnt lgkmcnt(0)
	s_setprio 1
	s_barrier
	v_mfma_f32_16x16x32_bf16 v[62:65], v[168:171], v[200:203], v[62:65]
	v_mfma_f32_16x16x32_bf16 v[58:61], v[176:179], v[200:203], v[58:61]
	v_mfma_f32_16x16x32_bf16 v[50:53], v[168:171], v[208:211], v[50:53]
	v_mfma_f32_16x16x32_bf16 v[42:45], v[176:179], v[208:211], v[42:45]
	v_mfma_f32_16x16x32_bf16 v[34:37], v[168:171], v[216:219], v[34:37]
	v_mfma_f32_16x16x32_bf16 v[26:29], v[176:179], v[216:219], v[26:29]
	v_mfma_f32_16x16x32_bf16 v[18:21], v[168:171], v[224:227], v[18:21]
	v_mfma_f32_16x16x32_bf16 v[10:13], v[176:179], v[224:227], v[10:13]
	v_mfma_f32_16x16x32_bf16 v[62:65], v[172:175], v[204:207], v[62:65]
	v_mfma_f32_16x16x32_bf16 v[58:61], v[180:183], v[204:207], v[58:61]
	v_mfma_f32_16x16x32_bf16 v[50:53], v[172:175], v[212:215], v[50:53]
	v_mfma_f32_16x16x32_bf16 v[42:45], v[180:183], v[212:215], v[42:45]
	v_mfma_f32_16x16x32_bf16 v[34:37], v[172:175], v[220:223], v[34:37]
	v_mfma_f32_16x16x32_bf16 v[26:29], v[180:183], v[220:223], v[26:29]
	v_mfma_f32_16x16x32_bf16 v[18:21], v[172:175], v[228:231], v[18:21]
	v_mfma_f32_16x16x32_bf16 v[10:13], v[180:183], v[228:231], v[10:13]
	s_setprio 0
	s_setprio 1
	v_mfma_f32_16x16x32_bf16 v[54:57], v[184:187], v[200:203], v[54:57]
	v_mfma_f32_16x16x32_bf16 v[46:49], v[192:195], v[200:203], v[46:49]
	v_mfma_f32_16x16x32_bf16 v[38:41], v[184:187], v[208:211], v[38:41]
	v_mfma_f32_16x16x32_bf16 v[30:33], v[192:195], v[208:211], v[30:33]
	v_mfma_f32_16x16x32_bf16 v[22:25], v[184:187], v[216:219], v[22:25]
	v_mfma_f32_16x16x32_bf16 v[14:17], v[192:195], v[216:219], v[14:17]
	v_mfma_f32_16x16x32_bf16 v[6:9], v[184:187], v[224:227], v[6:9]
	v_mfma_f32_16x16x32_bf16 v[2:5], v[192:195], v[224:227], v[2:5]
	v_mfma_f32_16x16x32_bf16 v[54:57], v[188:191], v[204:207], v[54:57]
	v_mfma_f32_16x16x32_bf16 v[46:49], v[196:199], v[204:207], v[46:49]
	v_mfma_f32_16x16x32_bf16 v[38:41], v[188:191], v[212:215], v[38:41]
	v_mfma_f32_16x16x32_bf16 v[30:33], v[196:199], v[212:215], v[30:33]
	v_mfma_f32_16x16x32_bf16 v[22:25], v[188:191], v[220:223], v[22:25]
	v_mfma_f32_16x16x32_bf16 v[14:17], v[196:199], v[220:223], v[14:17]
	v_mfma_f32_16x16x32_bf16 v[6:9], v[188:191], v[228:231], v[6:9]
	v_mfma_f32_16x16x32_bf16 v[2:5], v[196:199], v[228:231], v[2:5]
	s_barrier
	s_setprio 0
	s_add_i32 s62, s62, 2
	s_add_u32 s60, s60, 0x100
	s_addc_u32 s61, s61, 0
	s_add_u32 s24, s24, 0x100
	s_addc_u32 s25, s25, 0
	s_cmp_gt_u32 s62, 29
	s_cbranch_scc0 .LBB0_143
	s_and_b64 vcc, exec, s[10:11]
	s_cbranch_vccz .LBB0_146
	s_barrier

.LBB0_268:
	ds_read_b128 v[150:153], v139
	ds_read_b128 v[154:157], v139 offset:1024
	ds_read_b128 v[158:161], v139 offset:2048
	ds_read_b128 v[162:165], v139 offset:3072
	ds_read_b128 v[166:169], v146
	ds_read_b128 v[170:173], v146 offset:1024
	ds_read_b128 v[174:177], v146 offset:2048
	ds_read_b128 v[178:181], v146 offset:3072
	s_add_u32 s18, s14, s16
	s_addc_u32 s19, s15, s17
	s_add_u32 s18, s18, 0x28300100
	s_addc_u32 s19, s19, 0
	s_add_u32 s55, s41, s16
	s_addc_u32 s56, s42, s17
	s_cmpk_eq_i32 s16, 0x300
	s_cselect_b32 s23, s11, s19
	s_cselect_b32 s22, s10, s18
	s_cselect_b32 s19, s9, s56
	s_cselect_b32 s18, s8, s55
	s_mov_b32 m0, s44
	v_lshl_add_u64 v[214:215], v[142:143], 0, s[16:17]
	ds_read_b128 v[182:185], v147
	ds_read_b128 v[186:189], v147 offset:1024
	ds_read_b128 v[190:193], v147 offset:2048
	ds_read_b128 v[194:197], v147 offset:3072
	ds_read_b128 v[198:201], v147 offset:4096
	ds_read_b128 v[202:205], v147 offset:5120
	ds_read_b128 v[206:209], v147 offset:6144
	ds_read_b128 v[210:213], v147 offset:7168
	global_load_lds_dwordx4 v[214:215], off
	v_lshl_add_u64 v[214:215], v[140:141], 0, s[16:17]
	s_mov_b32 m0, s45
	s_nop 0
	global_load_lds_dwordx4 v[214:215], off
	s_waitcnt vmcnt(8)
	s_waitcnt lgkmcnt(0)
	s_setprio 1
	s_barrier
	v_mfma_f32_16x16x32_bf16 v[126:129], v[150:153], v[182:185], v[126:129]
	v_mfma_f32_16x16x32_bf16 v[122:125], v[158:161], v[182:185], v[122:125]
	v_mfma_f32_16x16x32_bf16 v[118:121], v[150:153], v[190:193], v[118:121]
	v_mfma_f32_16x16x32_bf16 v[110:113], v[158:161], v[190:193], v[110:113]
	v_mfma_f32_16x16x32_bf16 v[102:105], v[150:153], v[198:201], v[102:105]
	v_mfma_f32_16x16x32_bf16 v[94:97], v[158:161], v[198:201], v[94:97]
	v_mfma_f32_16x16x32_bf16 v[86:89], v[150:153], v[206:209], v[86:89]
	v_mfma_f32_16x16x32_bf16 v[78:81], v[158:161], v[206:209], v[78:81]
	v_mfma_f32_16x16x32_bf16 v[126:129], v[154:157], v[186:189], v[126:129]
	v_mfma_f32_16x16x32_bf16 v[122:125], v[162:165], v[186:189], v[122:125]
	v_mfma_f32_16x16x32_bf16 v[118:121], v[154:157], v[194:197], v[118:121]
	v_mfma_f32_16x16x32_bf16 v[110:113], v[162:165], v[194:197], v[110:113]
	v_mfma_f32_16x16x32_bf16 v[102:105], v[154:157], v[202:205], v[102:105]
	v_mfma_f32_16x16x32_bf16 v[94:97], v[162:165], v[202:205], v[94:97]
	v_mfma_f32_16x16x32_bf16 v[86:89], v[154:157], v[210:213], v[86:89]
	v_mfma_f32_16x16x32_bf16 v[78:81], v[162:165], v[210:213], v[78:81]
	s_setprio 0
	s_setprio 1
	v_mfma_f32_16x16x32_bf16 v[114:117], v[166:169], v[182:185], v[114:117]
	v_mfma_f32_16x16x32_bf16 v[106:109], v[174:177], v[182:185], v[106:109]
	v_mfma_f32_16x16x32_bf16 v[98:101], v[166:169], v[190:193], v[98:101]
	v_mfma_f32_16x16x32_bf16 v[90:93], v[174:177], v[190:193], v[90:93]
	v_mfma_f32_16x16x32_bf16 v[82:85], v[166:169], v[198:201], v[82:85]
	v_mfma_f32_16x16x32_bf16 v[74:77], v[174:177], v[198:201], v[74:77]
	v_mfma_f32_16x16x32_bf16 v[70:73], v[166:169], v[206:209], v[70:73]
	v_mfma_f32_16x16x32_bf16 v[66:69], v[174:177], v[206:209], v[66:69]
	v_mfma_f32_16x16x32_bf16 v[114:117], v[170:173], v[186:189], v[114:117]
	v_mfma_f32_16x16x32_bf16 v[106:109], v[178:181], v[186:189], v[106:109]
	v_mfma_f32_16x16x32_bf16 v[98:101], v[170:173], v[194:197], v[98:101]
	v_mfma_f32_16x16x32_bf16 v[90:93], v[178:181], v[194:197], v[90:93]
	v_mfma_f32_16x16x32_bf16 v[82:85], v[170:173], v[202:205], v[82:85]
	v_mfma_f32_16x16x32_bf16 v[74:77], v[178:181], v[202:205], v[74:77]
	v_mfma_f32_16x16x32_bf16 v[70:73], v[170:173], v[210:213], v[70:73]
	v_mfma_f32_16x16x32_bf16 v[66:69], v[178:181], v[210:213], v[66:69]
	s_barrier
	s_setprio 0
	s_mov_b32 m0, s46
	v_lshl_add_u64 v[214:215], s[18:19], 0, v[132:133]
	s_add_u32 s56, s18, 0x20000
	ds_read_b128 v[182:185], v147 offset:16384
	ds_read_b128 v[186:189], v147 offset:17408
	ds_read_b128 v[190:193], v147 offset:18432
	ds_read_b128 v[194:197], v147 offset:19456
	ds_read_b128 v[198:201], v147 offset:20480
	ds_read_b128 v[202:205], v147 offset:21504
	ds_read_b128 v[206:209], v147 offset:22528
	ds_read_b128 v[210:213], v147 offset:23552
	global_load_lds_dwordx4 v[214:215], off
	v_lshl_add_u64 v[216:217], s[18:19], 0, v[136:137]
	s_mov_b32 m0, s47
	s_addc_u32 s57, s19, 0
	global_load_lds_dwordx4 v[216:217], off
	v_lshl_add_u64 v[218:219], s[56:57], 0, v[132:133]
	s_mov_b32 m0, s48
	v_lshl_add_u64 v[220:221], s[22:23], 0, v[134:135]
	global_load_lds_dwordx4 v[218:219], off
	v_lshl_add_u64 v[218:219], s[56:57], 0, v[136:137]
	s_mov_b32 m0, s49
	s_nop 0
	global_load_lds_dwordx4 v[218:219], off
	v_lshl_add_u64 v[218:219], s[22:23], 0, v[130:131]
	s_mov_b32 m0, s7
	s_nop 0
	global_load_lds_dwordx4 v[218:219], off
	s_mov_b32 m0, s36
	s_nop 0
	global_load_lds_dwordx4 v[220:221], off
	s_waitcnt vmcnt(8)
	s_waitcnt lgkmcnt(0)
	s_setprio 1
	s_barrier
	v_mfma_f32_16x16x32_bf16 v[62:65], v[150:153], v[182:185], v[62:65]
	v_mfma_f32_16x16x32_bf16 v[58:61], v[158:161], v[182:185], v[58:61]
	v_mfma_f32_16x16x32_bf16 v[54:57], v[150:153], v[190:193], v[54:57]
	v_mfma_f32_16x16x32_bf16 v[46:49], v[158:161], v[190:193], v[46:49]
	v_mfma_f32_16x16x32_bf16 v[38:41], v[150:153], v[198:201], v[38:41]
	v_mfma_f32_16x16x32_bf16 v[30:33], v[158:161], v[198:201], v[30:33]
	v_mfma_f32_16x16x32_bf16 v[22:25], v[150:153], v[206:209], v[22:25]
	v_mfma_f32_16x16x32_bf16 v[14:17], v[158:161], v[206:209], v[14:17]
	v_mfma_f32_16x16x32_bf16 v[62:65], v[154:157], v[186:189], v[62:65]
	v_mfma_f32_16x16x32_bf16 v[58:61], v[162:165], v[186:189], v[58:61]
	v_mfma_f32_16x16x32_bf16 v[54:57], v[154:157], v[194:197], v[54:57]
	v_mfma_f32_16x16x32_bf16 v[46:49], v[162:165], v[194:197], v[46:49]
	v_mfma_f32_16x16x32_bf16 v[38:41], v[154:157], v[202:205], v[38:41]
	v_mfma_f32_16x16x32_bf16 v[30:33], v[162:165], v[202:205], v[30:33]
	v_mfma_f32_16x16x32_bf16 v[22:25], v[154:157], v[210:213], v[22:25]
	v_mfma_f32_16x16x32_bf16 v[14:17], v[162:165], v[210:213], v[14:17]
	s_setprio 0
	s_setprio 1
	v_mfma_f32_16x16x32_bf16 v[50:53], v[166:169], v[182:185], v[50:53]
	v_mfma_f32_16x16x32_bf16 v[42:45], v[174:177], v[182:185], v[42:45]
	v_mfma_f32_16x16x32_bf16 v[34:37], v[166:169], v[190:193], v[34:37]
	v_mfma_f32_16x16x32_bf16 v[26:29], v[174:177], v[190:193], v[26:29]
	v_mfma_f32_16x16x32_bf16 v[18:21], v[166:169], v[198:201], v[18:21]
	v_mfma_f32_16x16x32_bf16 v[10:13], v[174:177], v[198:201], v[10:13]
	v_mfma_f32_16x16x32_bf16 v[6:9], v[166:169], v[206:209], v[6:9]
	v_mfma_f32_16x16x32_bf16 v[2:5], v[174:177], v[206:209], v[2:5]
	v_mfma_f32_16x16x32_bf16 v[50:53], v[170:173], v[186:189], v[50:53]
	v_mfma_f32_16x16x32_bf16 v[42:45], v[178:181], v[186:189], v[42:45]
	v_mfma_f32_16x16x32_bf16 v[34:37], v[170:173], v[194:197], v[34:37]
	v_mfma_f32_16x16x32_bf16 v[26:29], v[178:181], v[194:197], v[26:29]
	v_mfma_f32_16x16x32_bf16 v[18:21], v[170:173], v[202:205], v[18:21]
	v_mfma_f32_16x16x32_bf16 v[10:13], v[178:181], v[202:205], v[10:13]
	v_mfma_f32_16x16x32_bf16 v[6:9], v[170:173], v[210:213], v[6:9]
	v_mfma_f32_16x16x32_bf16 v[2:5], v[178:181], v[210:213], v[2:5]
	s_barrier
	s_setprio 0
	ds_read_b128 v[150:153], v148
	ds_read_b128 v[154:157], v148 offset:1024
	ds_read_b128 v[158:161], v148 offset:2048
	ds_read_b128 v[162:165], v148 offset:3072
	ds_read_b128 v[166:169], v149
	ds_read_b128 v[170:173], v149 offset:1024
	ds_read_b128 v[174:177], v149 offset:2048
	ds_read_b128 v[178:181], v149 offset:3072
	s_add_u32 s22, s22, 0x20000
	s_addc_u32 s23, s23, 0
	s_mov_b32 m0, s37
	v_lshl_add_u64 v[222:223], s[22:23], 0, v[130:131]
	ds_read_b128 v[182:185], v147 offset:32768
	ds_read_b128 v[186:189], v147 offset:33792
	ds_read_b128 v[190:193], v147 offset:34816
	ds_read_b128 v[194:197], v147 offset:35840
	ds_read_b128 v[198:201], v147 offset:36864
	ds_read_b128 v[202:205], v147 offset:37888
	ds_read_b128 v[206:209], v147 offset:38912
	ds_read_b128 v[210:213], v147 offset:39936
	global_load_lds_dwordx4 v[222:223], off
	v_lshl_add_u64 v[222:223], s[22:23], 0, v[134:135]
	s_mov_b32 m0, s38
	s_nop 0
	global_load_lds_dwordx4 v[222:223], off
	s_waitcnt vmcnt(8)
	s_waitcnt lgkmcnt(0)
	s_setprio 1
	s_barrier
	v_mfma_f32_16x16x32_bf16 v[126:129], v[150:153], v[182:185], v[126:129]
	v_mfma_f32_16x16x32_bf16 v[122:125], v[158:161], v[182:185], v[122:125]
	v_mfma_f32_16x16x32_bf16 v[118:121], v[150:153], v[190:193], v[118:121]
	v_mfma_f32_16x16x32_bf16 v[110:113], v[158:161], v[190:193], v[110:113]
	v_mfma_f32_16x16x32_bf16 v[102:105], v[150:153], v[198:201], v[102:105]
	v_mfma_f32_16x16x32_bf16 v[94:97], v[158:161], v[198:201], v[94:97]
	v_mfma_f32_16x16x32_bf16 v[86:89], v[150:153], v[206:209], v[86:89]
	v_mfma_f32_16x16x32_bf16 v[78:81], v[158:161], v[206:209], v[78:81]
	v_mfma_f32_16x16x32_bf16 v[126:129], v[154:157], v[186:189], v[126:129]
	v_mfma_f32_16x16x32_bf16 v[122:125], v[162:165], v[186:189], v[122:125]
	v_mfma_f32_16x16x32_bf16 v[118:121], v[154:157], v[194:197], v[118:121]
	v_mfma_f32_16x16x32_bf16 v[110:113], v[162:165], v[194:197], v[110:113]
	v_mfma_f32_16x16x32_bf16 v[102:105], v[154:157], v[202:205], v[102:105]
	v_mfma_f32_16x16x32_bf16 v[94:97], v[162:165], v[202:205], v[94:97]
	v_mfma_f32_16x16x32_bf16 v[86:89], v[154:157], v[210:213], v[86:89]
	v_mfma_f32_16x16x32_bf16 v[78:81], v[162:165], v[210:213], v[78:81]
	s_setprio 0
	s_setprio 1
	v_mfma_f32_16x16x32_bf16 v[114:117], v[166:169], v[182:185], v[114:117]
	v_mfma_f32_16x16x32_bf16 v[106:109], v[174:177], v[182:185], v[106:109]
	v_mfma_f32_16x16x32_bf16 v[98:101], v[166:169], v[190:193], v[98:101]
	v_mfma_f32_16x16x32_bf16 v[90:93], v[174:177], v[190:193], v[90:93]
	v_mfma_f32_16x16x32_bf16 v[82:85], v[166:169], v[198:201], v[82:85]
	v_mfma_f32_16x16x32_bf16 v[74:77], v[174:177], v[198:201], v[74:77]
	v_mfma_f32_16x16x32_bf16 v[70:73], v[166:169], v[206:209], v[70:73]
	v_mfma_f32_16x16x32_bf16 v[66:69], v[174:177], v[206:209], v[66:69]
	v_mfma_f32_16x16x32_bf16 v[114:117], v[170:173], v[186:189], v[114:117]
	v_mfma_f32_16x16x32_bf16 v[106:109], v[178:181], v[186:189], v[106:109]
	v_mfma_f32_16x16x32_bf16 v[98:101], v[170:173], v[194:197], v[98:101]
	v_mfma_f32_16x16x32_bf16 v[90:93], v[178:181], v[194:197], v[90:93]
	v_mfma_f32_16x16x32_bf16 v[82:85], v[170:173], v[202:205], v[82:85]
	v_mfma_f32_16x16x32_bf16 v[74:77], v[178:181], v[202:205], v[74:77]
	v_mfma_f32_16x16x32_bf16 v[70:73], v[170:173], v[210:213], v[70:73]
	v_mfma_f32_16x16x32_bf16 v[66:69], v[178:181], v[210:213], v[66:69]
	s_barrier
	s_setprio 0
	s_mov_b32 m0, s50
	v_lshl_add_u64 v[214:215], v[214:215], 0, s[12:13]
	s_add_u32 s18, s18, 0x20080
	ds_read_b128 v[182:185], v147 offset:49152
	ds_read_b128 v[186:189], v147 offset:50176
	ds_read_b128 v[190:193], v147 offset:51200
	ds_read_b128 v[194:197], v147 offset:52224
	ds_read_b128 v[198:201], v147 offset:53248
	ds_read_b128 v[202:205], v147 offset:54272
	ds_read_b128 v[206:209], v147 offset:55296
	ds_read_b128 v[210:213], v147 offset:56320
	global_load_lds_dwordx4 v[214:215], off
	v_lshl_add_u64 v[214:215], v[216:217], 0, s[12:13]
	s_mov_b32 m0, s51
	s_addc_u32 s19, s19, 0
	global_load_lds_dwordx4 v[214:215], off
	v_lshl_add_u64 v[214:215], s[18:19], 0, v[132:133]
	s_mov_b32 m0, s53
	s_nop 0
	global_load_lds_dwordx4 v[214:215], off
	v_lshl_add_u64 v[214:215], s[18:19], 0, v[136:137]
	s_mov_b32 m0, s54
	s_nop 0
	global_load_lds_dwordx4 v[214:215], off
	v_lshl_add_u64 v[214:215], v[218:219], 0, s[12:13]
	s_mov_b32 m0, s39
	s_nop 0
	global_load_lds_dwordx4 v[214:215], off
	v_lshl_add_u64 v[214:215], v[220:221], 0, s[12:13]
	s_mov_b32 m0, s40
	s_nop 0
	global_load_lds_dwordx4 v[214:215], off
	s_waitcnt vmcnt(8)
	s_waitcnt lgkmcnt(0)
	s_setprio 1
	s_barrier
	v_mfma_f32_16x16x32_bf16 v[62:65], v[150:153], v[182:185], v[62:65]
	v_mfma_f32_16x16x32_bf16 v[58:61], v[158:161], v[182:185], v[58:61]
	v_mfma_f32_16x16x32_bf16 v[54:57], v[150:153], v[190:193], v[54:57]
	v_mfma_f32_16x16x32_bf16 v[46:49], v[158:161], v[190:193], v[46:49]
	v_mfma_f32_16x16x32_bf16 v[38:41], v[150:153], v[198:201], v[38:41]
	v_mfma_f32_16x16x32_bf16 v[30:33], v[158:161], v[198:201], v[30:33]
	v_mfma_f32_16x16x32_bf16 v[22:25], v[150:153], v[206:209], v[22:25]
	v_mfma_f32_16x16x32_bf16 v[14:17], v[158:161], v[206:209], v[14:17]
	v_mfma_f32_16x16x32_bf16 v[62:65], v[154:157], v[186:189], v[62:65]
	v_mfma_f32_16x16x32_bf16 v[58:61], v[162:165], v[186:189], v[58:61]
	v_mfma_f32_16x16x32_bf16 v[54:57], v[154:157], v[194:197], v[54:57]
	v_mfma_f32_16x16x32_bf16 v[46:49], v[162:165], v[194:197], v[46:49]
	v_mfma_f32_16x16x32_bf16 v[38:41], v[154:157], v[202:205], v[38:41]
	v_mfma_f32_16x16x32_bf16 v[30:33], v[162:165], v[202:205], v[30:33]
	v_mfma_f32_16x16x32_bf16 v[22:25], v[154:157], v[210:213], v[22:25]
	v_mfma_f32_16x16x32_bf16 v[14:17], v[162:165], v[210:213], v[14:17]
	s_setprio 0
	s_setprio 1
	v_mfma_f32_16x16x32_bf16 v[50:53], v[166:169], v[182:185], v[50:53]
	v_mfma_f32_16x16x32_bf16 v[42:45], v[174:177], v[182:185], v[42:45]
	v_mfma_f32_16x16x32_bf16 v[34:37], v[166:169], v[190:193], v[34:37]
	v_mfma_f32_16x16x32_bf16 v[26:29], v[174:177], v[190:193], v[26:29]
	v_mfma_f32_16x16x32_bf16 v[18:21], v[166:169], v[198:201], v[18:21]
	v_mfma_f32_16x16x32_bf16 v[10:13], v[174:177], v[198:201], v[10:13]
	v_mfma_f32_16x16x32_bf16 v[6:9], v[166:169], v[206:209], v[6:9]
	v_mfma_f32_16x16x32_bf16 v[2:5], v[174:177], v[206:209], v[2:5]
	v_mfma_f32_16x16x32_bf16 v[50:53], v[170:173], v[186:189], v[50:53]
	v_mfma_f32_16x16x32_bf16 v[42:45], v[178:181], v[186:189], v[42:45]
	v_mfma_f32_16x16x32_bf16 v[34:37], v[170:173], v[194:197], v[34:37]
	v_mfma_f32_16x16x32_bf16 v[26:29], v[178:181], v[194:197], v[26:29]
	v_mfma_f32_16x16x32_bf16 v[18:21], v[170:173], v[202:205], v[18:21]
	v_mfma_f32_16x16x32_bf16 v[10:13], v[178:181], v[202:205], v[10:13]
	v_mfma_f32_16x16x32_bf16 v[6:9], v[170:173], v[210:213], v[6:9]
	v_mfma_f32_16x16x32_bf16 v[2:5], v[178:181], v[210:213], v[2:5]
	s_barrier
	s_setprio 0
	s_add_i32 s43, s43, 2
	s_add_u32 s16, s16, 0x100
	s_addc_u32 s17, s17, 0
	s_cmp_gt_u32 s43, 5
	s_cbranch_scc0 .LBB0_268
	s_cmpk_lt_u32 s33, 0x100
	s_cbranch_scc0 .LBB0_271
	s_barrier

.LBB0_274:
	ds_read_b128 v[150:153], v144
	ds_read_b128 v[154:157], v144 offset:1024
	ds_read_b128 v[158:161], v144 offset:2048
	ds_read_b128 v[162:165], v144 offset:3072
	ds_read_b128 v[166:169], v145
	ds_read_b128 v[170:173], v145 offset:1024
	ds_read_b128 v[174:177], v145 offset:2048
	ds_read_b128 v[178:181], v145 offset:3072
	s_add_u32 s18, s14, s16
	s_addc_u32 s19, s15, s17
	s_add_u32 s18, s18, 0xf900100
	s_addc_u32 s19, s19, 0
	s_add_u32 s49, s40, s16
	s_addc_u32 s50, s41, s17
	s_cmpk_eq_i32 s16, 0x300
	s_cselect_b32 s23, s11, s19
	s_cselect_b32 s22, s10, s18
	s_cselect_b32 s19, s9, s50
	s_cselect_b32 s18, s8, s49
	s_mov_b32 m0, s43
	v_lshl_add_u64 v[214:215], v[140:141], 0, s[16:17]
	ds_read_b128 v[182:185], v146
	ds_read_b128 v[186:189], v146 offset:1024
	ds_read_b128 v[190:193], v146 offset:2048
	ds_read_b128 v[194:197], v146 offset:3072
	ds_read_b128 v[198:201], v146 offset:4096
	ds_read_b128 v[202:205], v146 offset:5120
	ds_read_b128 v[206:209], v146 offset:6144
	ds_read_b128 v[210:213], v146 offset:7168
	global_load_lds_dwordx4 v[214:215], off
	v_lshl_add_u64 v[214:215], v[138:139], 0, s[16:17]
	s_mov_b32 m0, s44
	s_nop 0
	global_load_lds_dwordx4 v[214:215], off
	s_waitcnt vmcnt(8)
	s_waitcnt lgkmcnt(0)
	s_setprio 1
	s_barrier
	v_mfma_f32_16x16x32_bf16 v[126:129], v[150:153], v[182:185], v[126:129]
	v_mfma_f32_16x16x32_bf16 v[122:125], v[158:161], v[182:185], v[122:125]
	v_mfma_f32_16x16x32_bf16 v[118:121], v[150:153], v[190:193], v[118:121]
	v_mfma_f32_16x16x32_bf16 v[110:113], v[158:161], v[190:193], v[110:113]
	v_mfma_f32_16x16x32_bf16 v[102:105], v[150:153], v[198:201], v[102:105]
	v_mfma_f32_16x16x32_bf16 v[94:97], v[158:161], v[198:201], v[94:97]
	v_mfma_f32_16x16x32_bf16 v[86:89], v[150:153], v[206:209], v[86:89]
	v_mfma_f32_16x16x32_bf16 v[78:81], v[158:161], v[206:209], v[78:81]
	v_mfma_f32_16x16x32_bf16 v[126:129], v[154:157], v[186:189], v[126:129]
	v_mfma_f32_16x16x32_bf16 v[122:125], v[162:165], v[186:189], v[122:125]
	v_mfma_f32_16x16x32_bf16 v[118:121], v[154:157], v[194:197], v[118:121]
	v_mfma_f32_16x16x32_bf16 v[110:113], v[162:165], v[194:197], v[110:113]
	v_mfma_f32_16x16x32_bf16 v[102:105], v[154:157], v[202:205], v[102:105]
	v_mfma_f32_16x16x32_bf16 v[94:97], v[162:165], v[202:205], v[94:97]
	v_mfma_f32_16x16x32_bf16 v[86:89], v[154:157], v[210:213], v[86:89]
	v_mfma_f32_16x16x32_bf16 v[78:81], v[162:165], v[210:213], v[78:81]
	s_setprio 0
	s_setprio 1
	v_mfma_f32_16x16x32_bf16 v[114:117], v[166:169], v[182:185], v[114:117]
	v_mfma_f32_16x16x32_bf16 v[106:109], v[174:177], v[182:185], v[106:109]
	v_mfma_f32_16x16x32_bf16 v[98:101], v[166:169], v[190:193], v[98:101]
	v_mfma_f32_16x16x32_bf16 v[90:93], v[174:177], v[190:193], v[90:93]
	v_mfma_f32_16x16x32_bf16 v[82:85], v[166:169], v[198:201], v[82:85]
	v_mfma_f32_16x16x32_bf16 v[74:77], v[174:177], v[198:201], v[74:77]
	v_mfma_f32_16x16x32_bf16 v[70:73], v[166:169], v[206:209], v[70:73]
	v_mfma_f32_16x16x32_bf16 v[66:69], v[174:177], v[206:209], v[66:69]
	v_mfma_f32_16x16x32_bf16 v[114:117], v[170:173], v[186:189], v[114:117]
	v_mfma_f32_16x16x32_bf16 v[106:109], v[178:181], v[186:189], v[106:109]
	v_mfma_f32_16x16x32_bf16 v[98:101], v[170:173], v[194:197], v[98:101]
	v_mfma_f32_16x16x32_bf16 v[90:93], v[178:181], v[194:197], v[90:93]
	v_mfma_f32_16x16x32_bf16 v[82:85], v[170:173], v[202:205], v[82:85]
	v_mfma_f32_16x16x32_bf16 v[74:77], v[178:181], v[202:205], v[74:77]
	v_mfma_f32_16x16x32_bf16 v[70:73], v[170:173], v[210:213], v[70:73]
	v_mfma_f32_16x16x32_bf16 v[66:69], v[178:181], v[210:213], v[66:69]
	s_barrier
	s_setprio 0
	s_mov_b32 m0, s25
	v_lshl_add_u64 v[214:215], s[18:19], 0, v[130:131]
	s_add_u32 s50, s18, 0x20000
	ds_read_b128 v[182:185], v146 offset:16384
	ds_read_b128 v[186:189], v146 offset:17408
	ds_read_b128 v[190:193], v146 offset:18432
	ds_read_b128 v[194:197], v146 offset:19456
	ds_read_b128 v[198:201], v146 offset:20480
	ds_read_b128 v[202:205], v146 offset:21504
	ds_read_b128 v[206:209], v146 offset:22528
	ds_read_b128 v[210:213], v146 offset:23552
	global_load_lds_dwordx4 v[214:215], off
	v_lshl_add_u64 v[216:217], s[18:19], 0, v[136:137]
	s_mov_b32 m0, s45
	s_addc_u32 s51, s19, 0
	global_load_lds_dwordx4 v[216:217], off
	v_lshl_add_u64 v[218:219], s[50:51], 0, v[130:131]
	s_mov_b32 m0, s26
	v_lshl_add_u64 v[220:221], s[22:23], 0, v[134:135]
	global_load_lds_dwordx4 v[218:219], off
	v_lshl_add_u64 v[218:219], s[50:51], 0, v[136:137]
	s_mov_b32 m0, s46
	s_nop 0
	global_load_lds_dwordx4 v[218:219], off
	v_lshl_add_u64 v[218:219], s[22:23], 0, v[132:133]
	s_mov_b32 m0, s7
	s_nop 0
	global_load_lds_dwordx4 v[218:219], off
	s_mov_b32 m0, s34
	s_nop 0
	global_load_lds_dwordx4 v[220:221], off
	s_waitcnt vmcnt(8)
	s_waitcnt lgkmcnt(0)
	s_setprio 1
	s_barrier
	v_mfma_f32_16x16x32_bf16 v[62:65], v[150:153], v[182:185], v[62:65]
	v_mfma_f32_16x16x32_bf16 v[58:61], v[158:161], v[182:185], v[58:61]
	v_mfma_f32_16x16x32_bf16 v[54:57], v[150:153], v[190:193], v[54:57]
	v_mfma_f32_16x16x32_bf16 v[46:49], v[158:161], v[190:193], v[46:49]
	v_mfma_f32_16x16x32_bf16 v[38:41], v[150:153], v[198:201], v[38:41]
	v_mfma_f32_16x16x32_bf16 v[30:33], v[158:161], v[198:201], v[30:33]
	v_mfma_f32_16x16x32_bf16 v[22:25], v[150:153], v[206:209], v[22:25]
	v_mfma_f32_16x16x32_bf16 v[14:17], v[158:161], v[206:209], v[14:17]
	v_mfma_f32_16x16x32_bf16 v[62:65], v[154:157], v[186:189], v[62:65]
	v_mfma_f32_16x16x32_bf16 v[58:61], v[162:165], v[186:189], v[58:61]
	v_mfma_f32_16x16x32_bf16 v[54:57], v[154:157], v[194:197], v[54:57]
	v_mfma_f32_16x16x32_bf16 v[46:49], v[162:165], v[194:197], v[46:49]
	v_mfma_f32_16x16x32_bf16 v[38:41], v[154:157], v[202:205], v[38:41]
	v_mfma_f32_16x16x32_bf16 v[30:33], v[162:165], v[202:205], v[30:33]
	v_mfma_f32_16x16x32_bf16 v[22:25], v[154:157], v[210:213], v[22:25]
	v_mfma_f32_16x16x32_bf16 v[14:17], v[162:165], v[210:213], v[14:17]
	s_setprio 0
	s_setprio 1
	v_mfma_f32_16x16x32_bf16 v[50:53], v[166:169], v[182:185], v[50:53]
	v_mfma_f32_16x16x32_bf16 v[42:45], v[174:177], v[182:185], v[42:45]
	v_mfma_f32_16x16x32_bf16 v[34:37], v[166:169], v[190:193], v[34:37]
	v_mfma_f32_16x16x32_bf16 v[26:29], v[174:177], v[190:193], v[26:29]
	v_mfma_f32_16x16x32_bf16 v[18:21], v[166:169], v[198:201], v[18:21]
	v_mfma_f32_16x16x32_bf16 v[10:13], v[174:177], v[198:201], v[10:13]
	v_mfma_f32_16x16x32_bf16 v[6:9], v[166:169], v[206:209], v[6:9]
	v_mfma_f32_16x16x32_bf16 v[2:5], v[174:177], v[206:209], v[2:5]
	v_mfma_f32_16x16x32_bf16 v[50:53], v[170:173], v[186:189], v[50:53]
	v_mfma_f32_16x16x32_bf16 v[42:45], v[178:181], v[186:189], v[42:45]
	v_mfma_f32_16x16x32_bf16 v[34:37], v[170:173], v[194:197], v[34:37]
	v_mfma_f32_16x16x32_bf16 v[26:29], v[178:181], v[194:197], v[26:29]
	v_mfma_f32_16x16x32_bf16 v[18:21], v[170:173], v[202:205], v[18:21]
	v_mfma_f32_16x16x32_bf16 v[10:13], v[178:181], v[202:205], v[10:13]
	v_mfma_f32_16x16x32_bf16 v[6:9], v[170:173], v[210:213], v[6:9]
	v_mfma_f32_16x16x32_bf16 v[2:5], v[178:181], v[210:213], v[2:5]
	s_barrier
	s_setprio 0
	ds_read_b128 v[150:153], v147
	ds_read_b128 v[154:157], v147 offset:1024
	ds_read_b128 v[158:161], v147 offset:2048
	ds_read_b128 v[162:165], v147 offset:3072
	ds_read_b128 v[166:169], v148
	ds_read_b128 v[170:173], v148 offset:1024
	ds_read_b128 v[174:177], v148 offset:2048
	ds_read_b128 v[178:181], v148 offset:3072
	s_add_u32 s22, s22, 0x20000
	s_addc_u32 s23, s23, 0
	s_mov_b32 m0, s35
	v_lshl_add_u64 v[222:223], s[22:23], 0, v[132:133]
	ds_read_b128 v[182:185], v146 offset:32768
	ds_read_b128 v[186:189], v146 offset:33792
	ds_read_b128 v[190:193], v146 offset:34816
	ds_read_b128 v[194:197], v146 offset:35840
	ds_read_b128 v[198:201], v146 offset:36864
	ds_read_b128 v[202:205], v146 offset:37888
	ds_read_b128 v[206:209], v146 offset:38912
	ds_read_b128 v[210:213], v146 offset:39936
	global_load_lds_dwordx4 v[222:223], off
	v_lshl_add_u64 v[222:223], s[22:23], 0, v[134:135]
	s_mov_b32 m0, s36
	s_nop 0
	global_load_lds_dwordx4 v[222:223], off
	s_waitcnt vmcnt(8)
	s_waitcnt lgkmcnt(0)
	s_setprio 1
	s_barrier
	v_mfma_f32_16x16x32_bf16 v[126:129], v[150:153], v[182:185], v[126:129]
	v_mfma_f32_16x16x32_bf16 v[122:125], v[158:161], v[182:185], v[122:125]
	v_mfma_f32_16x16x32_bf16 v[118:121], v[150:153], v[190:193], v[118:121]
	v_mfma_f32_16x16x32_bf16 v[110:113], v[158:161], v[190:193], v[110:113]
	v_mfma_f32_16x16x32_bf16 v[102:105], v[150:153], v[198:201], v[102:105]
	v_mfma_f32_16x16x32_bf16 v[94:97], v[158:161], v[198:201], v[94:97]
	v_mfma_f32_16x16x32_bf16 v[86:89], v[150:153], v[206:209], v[86:89]
	v_mfma_f32_16x16x32_bf16 v[78:81], v[158:161], v[206:209], v[78:81]
	v_mfma_f32_16x16x32_bf16 v[126:129], v[154:157], v[186:189], v[126:129]
	v_mfma_f32_16x16x32_bf16 v[122:125], v[162:165], v[186:189], v[122:125]
	v_mfma_f32_16x16x32_bf16 v[118:121], v[154:157], v[194:197], v[118:121]
	v_mfma_f32_16x16x32_bf16 v[110:113], v[162:165], v[194:197], v[110:113]
	v_mfma_f32_16x16x32_bf16 v[102:105], v[154:157], v[202:205], v[102:105]
	v_mfma_f32_16x16x32_bf16 v[94:97], v[162:165], v[202:205], v[94:97]
	v_mfma_f32_16x16x32_bf16 v[86:89], v[154:157], v[210:213], v[86:89]
	v_mfma_f32_16x16x32_bf16 v[78:81], v[162:165], v[210:213], v[78:81]
	s_setprio 0
	s_setprio 1
	v_mfma_f32_16x16x32_bf16 v[114:117], v[166:169], v[182:185], v[114:117]
	v_mfma_f32_16x16x32_bf16 v[106:109], v[174:177], v[182:185], v[106:109]
	v_mfma_f32_16x16x32_bf16 v[98:101], v[166:169], v[190:193], v[98:101]
	v_mfma_f32_16x16x32_bf16 v[90:93], v[174:177], v[190:193], v[90:93]
	v_mfma_f32_16x16x32_bf16 v[82:85], v[166:169], v[198:201], v[82:85]
	v_mfma_f32_16x16x32_bf16 v[74:77], v[174:177], v[198:201], v[74:77]
	v_mfma_f32_16x16x32_bf16 v[70:73], v[166:169], v[206:209], v[70:73]
	v_mfma_f32_16x16x32_bf16 v[66:69], v[174:177], v[206:209], v[66:69]
	v_mfma_f32_16x16x32_bf16 v[114:117], v[170:173], v[186:189], v[114:117]
	v_mfma_f32_16x16x32_bf16 v[106:109], v[178:181], v[186:189], v[106:109]
	v_mfma_f32_16x16x32_bf16 v[98:101], v[170:173], v[194:197], v[98:101]
	v_mfma_f32_16x16x32_bf16 v[90:93], v[178:181], v[194:197], v[90:93]
	v_mfma_f32_16x16x32_bf16 v[82:85], v[170:173], v[202:205], v[82:85]
	v_mfma_f32_16x16x32_bf16 v[74:77], v[178:181], v[202:205], v[74:77]
	v_mfma_f32_16x16x32_bf16 v[70:73], v[170:173], v[210:213], v[70:73]
	v_mfma_f32_16x16x32_bf16 v[66:69], v[178:181], v[210:213], v[66:69]
	s_barrier
	s_setprio 0
	s_mov_b32 m0, s27
	v_lshl_add_u64 v[214:215], v[214:215], 0, s[12:13]
	s_add_u32 s18, s18, 0x20080
	ds_read_b128 v[182:185], v146 offset:49152
	ds_read_b128 v[186:189], v146 offset:50176
	ds_read_b128 v[190:193], v146 offset:51200
	ds_read_b128 v[194:197], v146 offset:52224
	ds_read_b128 v[198:201], v146 offset:53248
	ds_read_b128 v[202:205], v146 offset:54272
	ds_read_b128 v[206:209], v146 offset:55296
	ds_read_b128 v[210:213], v146 offset:56320
	global_load_lds_dwordx4 v[214:215], off
	v_lshl_add_u64 v[214:215], v[216:217], 0, s[12:13]
	s_mov_b32 m0, s47
	s_addc_u32 s19, s19, 0
	global_load_lds_dwordx4 v[214:215], off
	v_lshl_add_u64 v[214:215], s[18:19], 0, v[130:131]
	s_mov_b32 m0, s30
	s_nop 0
	global_load_lds_dwordx4 v[214:215], off
	v_lshl_add_u64 v[214:215], s[18:19], 0, v[136:137]
	s_mov_b32 m0, s48
	s_nop 0
	global_load_lds_dwordx4 v[214:215], off
	v_lshl_add_u64 v[214:215], v[218:219], 0, s[12:13]
	s_mov_b32 m0, s38
	s_nop 0
	global_load_lds_dwordx4 v[214:215], off
	v_lshl_add_u64 v[214:215], v[220:221], 0, s[12:13]
	s_mov_b32 m0, s39
	s_nop 0
	global_load_lds_dwordx4 v[214:215], off
	s_waitcnt vmcnt(8)
	s_waitcnt lgkmcnt(0)
	s_setprio 1
	s_barrier
	v_mfma_f32_16x16x32_bf16 v[62:65], v[150:153], v[182:185], v[62:65]
	v_mfma_f32_16x16x32_bf16 v[58:61], v[158:161], v[182:185], v[58:61]
	v_mfma_f32_16x16x32_bf16 v[54:57], v[150:153], v[190:193], v[54:57]
	v_mfma_f32_16x16x32_bf16 v[46:49], v[158:161], v[190:193], v[46:49]
	v_mfma_f32_16x16x32_bf16 v[38:41], v[150:153], v[198:201], v[38:41]
	v_mfma_f32_16x16x32_bf16 v[30:33], v[158:161], v[198:201], v[30:33]
	v_mfma_f32_16x16x32_bf16 v[22:25], v[150:153], v[206:209], v[22:25]
	v_mfma_f32_16x16x32_bf16 v[14:17], v[158:161], v[206:209], v[14:17]
	v_mfma_f32_16x16x32_bf16 v[62:65], v[154:157], v[186:189], v[62:65]
	v_mfma_f32_16x16x32_bf16 v[58:61], v[162:165], v[186:189], v[58:61]
	v_mfma_f32_16x16x32_bf16 v[54:57], v[154:157], v[194:197], v[54:57]
	v_mfma_f32_16x16x32_bf16 v[46:49], v[162:165], v[194:197], v[46:49]
	v_mfma_f32_16x16x32_bf16 v[38:41], v[154:157], v[202:205], v[38:41]
	v_mfma_f32_16x16x32_bf16 v[30:33], v[162:165], v[202:205], v[30:33]
	v_mfma_f32_16x16x32_bf16 v[22:25], v[154:157], v[210:213], v[22:25]
	v_mfma_f32_16x16x32_bf16 v[14:17], v[162:165], v[210:213], v[14:17]
	s_setprio 0
	s_setprio 1
	v_mfma_f32_16x16x32_bf16 v[50:53], v[166:169], v[182:185], v[50:53]
	v_mfma_f32_16x16x32_bf16 v[42:45], v[174:177], v[182:185], v[42:45]
	v_mfma_f32_16x16x32_bf16 v[34:37], v[166:169], v[190:193], v[34:37]
	v_mfma_f32_16x16x32_bf16 v[26:29], v[174:177], v[190:193], v[26:29]
	v_mfma_f32_16x16x32_bf16 v[18:21], v[166:169], v[198:201], v[18:21]
	v_mfma_f32_16x16x32_bf16 v[10:13], v[174:177], v[198:201], v[10:13]
	v_mfma_f32_16x16x32_bf16 v[6:9], v[166:169], v[206:209], v[6:9]
	v_mfma_f32_16x16x32_bf16 v[2:5], v[174:177], v[206:209], v[2:5]
	v_mfma_f32_16x16x32_bf16 v[50:53], v[170:173], v[186:189], v[50:53]
	v_mfma_f32_16x16x32_bf16 v[42:45], v[178:181], v[186:189], v[42:45]
	v_mfma_f32_16x16x32_bf16 v[34:37], v[170:173], v[194:197], v[34:37]
	v_mfma_f32_16x16x32_bf16 v[26:29], v[178:181], v[194:197], v[26:29]
	v_mfma_f32_16x16x32_bf16 v[18:21], v[170:173], v[202:205], v[18:21]
	v_mfma_f32_16x16x32_bf16 v[10:13], v[178:181], v[202:205], v[10:13]
	v_mfma_f32_16x16x32_bf16 v[6:9], v[170:173], v[210:213], v[6:9]
	v_mfma_f32_16x16x32_bf16 v[2:5], v[178:181], v[210:213], v[2:5]
	s_barrier
	s_setprio 0
	s_add_i32 s42, s42, 2
	s_add_u32 s16, s16, 0x100
	s_addc_u32 s17, s17, 0
	s_cmp_gt_u32 s42, 5
	s_cbranch_scc0 .LBB0_274
	s_cmpk_lt_u32 s31, 0x100
	s_cbranch_scc0 .LBB0_277
	s_barrier

.Lpj_skip1_p:
	s_waitcnt lgkmcnt(0)
	s_setprio 1
	s_barrier
	v_mfma_f32_16x16x32_bf16 v[128:131], v[154:157], v[196:199], 0
	v_mfma_f32_16x16x32_bf16 v[124:127], v[172:175], v[196:199], 0
	v_mfma_f32_16x16x32_bf16 v[116:119], v[154:157], v[204:207], 0
	v_mfma_f32_16x16x32_bf16 v[108:111], v[172:175], v[204:207], 0
	v_mfma_f32_16x16x32_bf16 v[100:103], v[154:157], v[212:215], 0
	v_mfma_f32_16x16x32_bf16 v[92:95], v[172:175], v[212:215], 0
	v_mfma_f32_16x16x32_bf16 v[84:87], v[154:157], v[220:223], 0
	v_mfma_f32_16x16x32_bf16 v[76:79], v[172:175], v[220:223], 0
	v_mfma_f32_16x16x32_bf16 v[128:131], v[168:171], v[200:203], v[128:131]
	v_mfma_f32_16x16x32_bf16 v[124:127], v[176:179], v[200:203], v[124:127]
	v_mfma_f32_16x16x32_bf16 v[116:119], v[168:171], v[208:211], v[116:119]
	v_mfma_f32_16x16x32_bf16 v[108:111], v[176:179], v[208:211], v[108:111]
	v_mfma_f32_16x16x32_bf16 v[100:103], v[168:171], v[216:219], v[100:103]
	v_mfma_f32_16x16x32_bf16 v[92:95], v[176:179], v[216:219], v[92:95]
	v_mfma_f32_16x16x32_bf16 v[84:87], v[168:171], v[224:227], v[84:87]
	v_mfma_f32_16x16x32_bf16 v[76:79], v[176:179], v[224:227], v[76:79]
	v_mfma_f32_16x16x32_bf16 v[120:123], v[180:183], v[196:199], 0
	v_mfma_f32_16x16x32_bf16 v[112:115], v[188:191], v[196:199], 0
	v_mfma_f32_16x16x32_bf16 v[104:107], v[180:183], v[204:207], 0
	v_mfma_f32_16x16x32_bf16 v[96:99], v[188:191], v[204:207], 0
	v_mfma_f32_16x16x32_bf16 v[88:91], v[180:183], v[212:215], 0
	v_mfma_f32_16x16x32_bf16 v[80:83], v[188:191], v[212:215], 0
	v_mfma_f32_16x16x32_bf16 v[72:75], v[180:183], v[220:223], 0
	v_mfma_f32_16x16x32_bf16 v[68:71], v[188:191], v[220:223], 0
	v_mfma_f32_16x16x32_bf16 v[120:123], v[184:187], v[200:203], v[120:123]
	v_mfma_f32_16x16x32_bf16 v[112:115], v[192:195], v[200:203], v[112:115]
	v_mfma_f32_16x16x32_bf16 v[104:107], v[184:187], v[208:211], v[104:107]
	v_mfma_f32_16x16x32_bf16 v[96:99], v[192:195], v[208:211], v[96:99]
	v_mfma_f32_16x16x32_bf16 v[88:91], v[184:187], v[216:219], v[88:91]
	v_mfma_f32_16x16x32_bf16 v[80:83], v[192:195], v[216:219], v[80:83]
	v_mfma_f32_16x16x32_bf16 v[72:75], v[184:187], v[224:227], v[72:75]
	v_mfma_f32_16x16x32_bf16 v[68:71], v[192:195], v[224:227], v[68:71]
	s_barrier
	s_setprio 0
	s_add_i32 s43, s50, s10
	s_mov_b32 m0, s43
	ds_read_b128 v[196:199], v167 offset:16384
	ds_read_b128 v[200:203], v167 offset:17408
	ds_read_b128 v[204:207], v167 offset:18432
	ds_read_b128 v[208:211], v167 offset:19456
	ds_read_b128 v[212:215], v167 offset:20480
	ds_read_b128 v[216:219], v167 offset:21504
	ds_read_b128 v[220:223], v167 offset:22528
	ds_read_b128 v[224:227], v167 offset:23552
	global_load_lds_dwordx4 v2, s[46:47]
	s_add_i32 m0, s43, 0x2000
	s_add_u32 s50, s46, 0x80000
	s_addc_u32 s51, s47, 0
	s_add_i32 s33, s33, s10
	global_load_lds_dwordx4 v0, s[46:47]
	s_mov_b32 m0, s33
	s_nop 0
	global_load_lds_dwordx4 v2, s[50:51]
	s_add_i32 m0, s33, 0x2000
	s_nop 0
	global_load_lds_dwordx4 v0, s[50:51]
	s_mov_b32 m0, s12
	s_nop 0
	global_load_lds_dwordx4 v134, s[48:49]
	s_mov_b32 m0, s13
	s_nop 0
	global_load_lds_dwordx4 v132, s[48:49]
	s_cmp_lg_u32 s32, 0
	s_cbranch_scc1 .Lpj_skip2_p
	s_waitcnt vmcnt(8)
.Lpj_skip2_p:
	s_mov_b32 s32, 0
	s_waitcnt lgkmcnt(0)
	s_setprio 1
	s_barrier
	v_mfma_f32_16x16x32_bf16 v[64:67], v[154:157], v[196:199], 0
	v_mfma_f32_16x16x32_bf16 v[60:63], v[172:175], v[196:199], 0
	v_mfma_f32_16x16x32_bf16 v[52:55], v[154:157], v[204:207], 0
	v_mfma_f32_16x16x32_bf16 v[44:47], v[172:175], v[204:207], 0
	v_mfma_f32_16x16x32_bf16 v[36:39], v[154:157], v[212:215], 0
	v_mfma_f32_16x16x32_bf16 v[28:31], v[172:175], v[212:215], 0
	v_mfma_f32_16x16x32_bf16 v[20:23], v[154:157], v[220:223], 0
	v_mfma_f32_16x16x32_bf16 v[12:15], v[172:175], v[220:223], 0
	v_mfma_f32_16x16x32_bf16 v[64:67], v[168:171], v[200:203], v[64:67]
	v_mfma_f32_16x16x32_bf16 v[60:63], v[176:179], v[200:203], v[60:63]
	v_mfma_f32_16x16x32_bf16 v[52:55], v[168:171], v[208:211], v[52:55]
	v_mfma_f32_16x16x32_bf16 v[44:47], v[176:179], v[208:211], v[44:47]
	v_mfma_f32_16x16x32_bf16 v[36:39], v[168:171], v[216:219], v[36:39]
	v_mfma_f32_16x16x32_bf16 v[28:31], v[176:179], v[216:219], v[28:31]
	v_mfma_f32_16x16x32_bf16 v[20:23], v[168:171], v[224:227], v[20:23]
	v_mfma_f32_16x16x32_bf16 v[12:15], v[176:179], v[224:227], v[12:15]
	v_mfma_f32_16x16x32_bf16 v[56:59], v[180:183], v[196:199], 0
	v_mfma_f32_16x16x32_bf16 v[48:51], v[188:191], v[196:199], 0
	v_mfma_f32_16x16x32_bf16 v[40:43], v[180:183], v[204:207], 0
	v_mfma_f32_16x16x32_bf16 v[32:35], v[188:191], v[204:207], 0
	v_mfma_f32_16x16x32_bf16 v[24:27], v[180:183], v[212:215], 0
	v_mfma_f32_16x16x32_bf16 v[16:19], v[188:191], v[212:215], 0
	v_mfma_f32_16x16x32_bf16 v[8:11], v[180:183], v[220:223], 0
	v_mfma_f32_16x16x32_bf16 v[4:7], v[188:191], v[220:223], 0
	v_mfma_f32_16x16x32_bf16 v[56:59], v[184:187], v[200:203], v[56:59]
	v_mfma_f32_16x16x32_bf16 v[48:51], v[192:195], v[200:203], v[48:51]
	v_mfma_f32_16x16x32_bf16 v[40:43], v[184:187], v[208:211], v[40:43]
	v_mfma_f32_16x16x32_bf16 v[32:35], v[192:195], v[208:211], v[32:35]
	v_mfma_f32_16x16x32_bf16 v[24:27], v[184:187], v[216:219], v[24:27]
	v_mfma_f32_16x16x32_bf16 v[16:19], v[192:195], v[216:219], v[16:19]
	v_mfma_f32_16x16x32_bf16 v[8:11], v[184:187], v[224:227], v[8:11]
	v_mfma_f32_16x16x32_bf16 v[4:7], v[192:195], v[224:227], v[4:7]
	s_barrier
	s_setprio 0
	s_add_i32 s33, 0, 0x18000
	v_add_u32_e32 v144, s33, v149
	s_add_i32 s43, 0, 0x1c000
	ds_read_b128 v[154:157], v144
	ds_read_b128 v[168:171], v144 offset:1024
	ds_read_b128 v[172:175], v144 offset:2048
	ds_read_b128 v[176:179], v144 offset:3072
	v_add_u32_e32 v144, s43, v149
	ds_read_b128 v[180:183], v144
	ds_read_b128 v[184:187], v144 offset:1024
	ds_read_b128 v[188:191], v144 offset:2048
	ds_read_b128 v[192:195], v144 offset:3072
	s_add_u32 s48, s48, 0x80000
	s_addc_u32 s49, s49, 0
	s_mov_b32 m0, s14
	ds_read_b128 v[196:199], v167 offset:32768
	ds_read_b128 v[200:203], v167 offset:33792
	ds_read_b128 v[204:207], v167 offset:34816
	ds_read_b128 v[208:211], v167 offset:35840
	ds_read_b128 v[212:215], v167 offset:36864
	ds_read_b128 v[216:219], v167 offset:37888
	ds_read_b128 v[220:223], v167 offset:38912
	ds_read_b128 v[224:227], v167 offset:39936
	global_load_lds_dwordx4 v134, s[48:49]
	s_mov_b32 m0, s15
	s_nop 0
	global_load_lds_dwordx4 v132, s[48:49]
	s_waitcnt vmcnt(8)
	s_waitcnt lgkmcnt(0)
	s_setprio 1
	s_barrier
	v_mfma_f32_16x16x32_bf16 v[128:131], v[154:157], v[196:199], v[128:131]
	v_mfma_f32_16x16x32_bf16 v[124:127], v[172:175], v[196:199], v[124:127]
	v_mfma_f32_16x16x32_bf16 v[116:119], v[154:157], v[204:207], v[116:119]
	v_mfma_f32_16x16x32_bf16 v[108:111], v[172:175], v[204:207], v[108:111]
	v_mfma_f32_16x16x32_bf16 v[100:103], v[154:157], v[212:215], v[100:103]
	v_mfma_f32_16x16x32_bf16 v[92:95], v[172:175], v[212:215], v[92:95]
	v_mfma_f32_16x16x32_bf16 v[84:87], v[154:157], v[220:223], v[84:87]
	v_mfma_f32_16x16x32_bf16 v[76:79], v[172:175], v[220:223], v[76:79]
	v_mfma_f32_16x16x32_bf16 v[128:131], v[168:171], v[200:203], v[128:131]
	v_mfma_f32_16x16x32_bf16 v[124:127], v[176:179], v[200:203], v[124:127]
	v_mfma_f32_16x16x32_bf16 v[116:119], v[168:171], v[208:211], v[116:119]
	v_mfma_f32_16x16x32_bf16 v[108:111], v[176:179], v[208:211], v[108:111]
	v_mfma_f32_16x16x32_bf16 v[100:103], v[168:171], v[216:219], v[100:103]
	v_mfma_f32_16x16x32_bf16 v[92:95], v[176:179], v[216:219], v[92:95]
	v_mfma_f32_16x16x32_bf16 v[84:87], v[168:171], v[224:227], v[84:87]
	v_mfma_f32_16x16x32_bf16 v[76:79], v[176:179], v[224:227], v[76:79]
	v_mfma_f32_16x16x32_bf16 v[120:123], v[180:183], v[196:199], v[120:123]
	v_mfma_f32_16x16x32_bf16 v[112:115], v[188:191], v[196:199], v[112:115]
	v_mfma_f32_16x16x32_bf16 v[104:107], v[180:183], v[204:207], v[104:107]
	v_mfma_f32_16x16x32_bf16 v[96:99], v[188:191], v[204:207], v[96:99]
	v_mfma_f32_16x16x32_bf16 v[88:91], v[180:183], v[212:215], v[88:91]
	v_mfma_f32_16x16x32_bf16 v[80:83], v[188:191], v[212:215], v[80:83]
	v_mfma_f32_16x16x32_bf16 v[72:75], v[180:183], v[220:223], v[72:75]
	v_mfma_f32_16x16x32_bf16 v[68:71], v[188:191], v[220:223], v[68:71]
	v_mfma_f32_16x16x32_bf16 v[120:123], v[184:187], v[200:203], v[120:123]
	v_mfma_f32_16x16x32_bf16 v[112:115], v[192:195], v[200:203], v[112:115]
	v_mfma_f32_16x16x32_bf16 v[104:107], v[184:187], v[208:211], v[104:107]
	v_mfma_f32_16x16x32_bf16 v[96:99], v[192:195], v[208:211], v[96:99]
	v_mfma_f32_16x16x32_bf16 v[88:91], v[184:187], v[216:219], v[88:91]
	v_mfma_f32_16x16x32_bf16 v[80:83], v[192:195], v[216:219], v[80:83]
	v_mfma_f32_16x16x32_bf16 v[72:75], v[184:187], v[224:227], v[72:75]
	v_mfma_f32_16x16x32_bf16 v[68:71], v[192:195], v[224:227], v[68:71]
	s_barrier
	s_setprio 0
	s_add_i32 s33, s33, s10
	s_mov_b32 m0, s33
	ds_read_b128 v[196:199], v167 offset:49152
	ds_read_b128 v[200:203], v167 offset:50176
	ds_read_b128 v[204:207], v167 offset:51200
	ds_read_b128 v[208:211], v167 offset:52224
	ds_read_b128 v[212:215], v167 offset:53248
	ds_read_b128 v[216:219], v167 offset:54272
	ds_read_b128 v[220:223], v167 offset:55296
	ds_read_b128 v[224:227], v167 offset:56320
	s_add_u32 s100, s46, 0x80
	s_addc_u32 s101, s47, 0
	global_load_lds_dwordx4 v2, s[100:101]
	s_add_i32 m0, s33, 0x2000
	s_add_u32 s46, s46, 0x80080
	s_addc_u32 s47, s47, 0
	s_add_i32 s33, s43, s10
	s_add_u32 s100, s46, 0xfff80000
	s_addc_u32 s101, s47, -1
	global_load_lds_dwordx4 v0, s[100:101]
	s_mov_b32 m0, s33
	s_nop 0
	global_load_lds_dwordx4 v2, s[46:47]
	s_add_i32 m0, s33, 0x2000
	s_nop 0
	global_load_lds_dwordx4 v0, s[46:47]
	s_mov_b32 m0, s16
	s_nop 0
	s_add_u32 s100, s48, 0xfff80080
	s_addc_u32 s101, s49, -1
	global_load_lds_dwordx4 v134, s[100:101]
	s_mov_b32 m0, s17
	s_nop 0
	s_add_u32 s100, s48, 0xfff80080
	s_addc_u32 s101, s49, -1
	global_load_lds_dwordx4 v132, s[100:101]
	s_waitcnt vmcnt(8)
	s_waitcnt lgkmcnt(0)
	s_setprio 1
	s_barrier
	v_mfma_f32_16x16x32_bf16 v[64:67], v[154:157], v[196:199], v[64:67]
	v_mfma_f32_16x16x32_bf16 v[60:63], v[172:175], v[196:199], v[60:63]
	v_mfma_f32_16x16x32_bf16 v[52:55], v[154:157], v[204:207], v[52:55]
	v_mfma_f32_16x16x32_bf16 v[44:47], v[172:175], v[204:207], v[44:47]
	v_mfma_f32_16x16x32_bf16 v[36:39], v[154:157], v[212:215], v[36:39]
	v_mfma_f32_16x16x32_bf16 v[28:31], v[172:175], v[212:215], v[28:31]
	v_mfma_f32_16x16x32_bf16 v[20:23], v[154:157], v[220:223], v[20:23]
	v_mfma_f32_16x16x32_bf16 v[12:15], v[172:175], v[220:223], v[12:15]
	v_mfma_f32_16x16x32_bf16 v[64:67], v[168:171], v[200:203], v[64:67]
	v_mfma_f32_16x16x32_bf16 v[60:63], v[176:179], v[200:203], v[60:63]
	v_mfma_f32_16x16x32_bf16 v[52:55], v[168:171], v[208:211], v[52:55]
	v_mfma_f32_16x16x32_bf16 v[44:47], v[176:179], v[208:211], v[44:47]
	v_mfma_f32_16x16x32_bf16 v[36:39], v[168:171], v[216:219], v[36:39]
	v_mfma_f32_16x16x32_bf16 v[28:31], v[176:179], v[216:219], v[28:31]
	v_mfma_f32_16x16x32_bf16 v[20:23], v[168:171], v[224:227], v[20:23]
	v_mfma_f32_16x16x32_bf16 v[12:15], v[176:179], v[224:227], v[12:15]
	v_mfma_f32_16x16x32_bf16 v[56:59], v[180:183], v[196:199], v[56:59]
	v_mfma_f32_16x16x32_bf16 v[48:51], v[188:191], v[196:199], v[48:51]
	v_mfma_f32_16x16x32_bf16 v[40:43], v[180:183], v[204:207], v[40:43]
	v_mfma_f32_16x16x32_bf16 v[32:35], v[188:191], v[204:207], v[32:35]
	v_mfma_f32_16x16x32_bf16 v[24:27], v[180:183], v[212:215], v[24:27]
	v_mfma_f32_16x16x32_bf16 v[16:19], v[188:191], v[212:215], v[16:19]
	v_mfma_f32_16x16x32_bf16 v[8:11], v[180:183], v[220:223], v[8:11]
	v_mfma_f32_16x16x32_bf16 v[4:7], v[188:191], v[220:223], v[4:7]
	v_mfma_f32_16x16x32_bf16 v[56:59], v[184:187], v[200:203], v[56:59]
	v_mfma_f32_16x16x32_bf16 v[48:51], v[192:195], v[200:203], v[48:51]
	v_mfma_f32_16x16x32_bf16 v[40:43], v[184:187], v[208:211], v[40:43]
	v_mfma_f32_16x16x32_bf16 v[32:35], v[192:195], v[208:211], v[32:35]
	v_mfma_f32_16x16x32_bf16 v[24:27], v[184:187], v[216:219], v[24:27]
	v_mfma_f32_16x16x32_bf16 v[16:19], v[192:195], v[216:219], v[16:19]
	v_mfma_f32_16x16x32_bf16 v[8:11], v[184:187], v[224:227], v[8:11]
	v_mfma_f32_16x16x32_bf16 v[4:7], v[192:195], v[224:227], v[4:7]
	s_barrier
	s_setprio 0
	s_add_i32 s35, s35, 2
	s_add_u32 s31, s31, 0x100
	s_addc_u32 s34, s34, 0
	s_add_u32 s44, s44, 0x100
	s_addc_u32 s45, s45, 0
	s_cmp_gt_u32 s35, 29
.LBB0_342:
	s_add_u32 s33, s44, 0xfff80080
	s_addc_u32 s43, s45, -1
	s_add_i32 s50, 0, 0x10000
	s_cmp_eq_u32 s35, 28
	s_cselect_b32 s49, s27, s43
	s_cselect_b32 s48, s28, s33
	v_add_u32_e32 v142, s50, v149
	s_cselect_b32 s47, s25, s34
	s_cselect_b32 s46, s29, s31
	s_add_i32 s33, 0, 0x14000
	ds_read_b128 v[154:157], v142
	ds_read_b128 v[168:171], v142 offset:1024
	ds_read_b128 v[172:175], v142 offset:2048
	ds_read_b128 v[176:179], v142 offset:3072
	v_add_u32_e32 v142, s33, v149
	ds_read_b128 v[180:183], v142
	ds_read_b128 v[184:187], v142 offset:1024
	ds_read_b128 v[188:191], v142 offset:2048
	ds_read_b128 v[192:195], v142 offset:3072
	s_add_i32 m0, s12, 0xc000
	ds_read_b128 v[196:199], v167
	ds_read_b128 v[200:203], v167 offset:1024
	ds_read_b128 v[204:207], v167 offset:2048
	ds_read_b128 v[208:211], v167 offset:3072
	ds_read_b128 v[212:215], v167 offset:4096
	ds_read_b128 v[216:219], v167 offset:5120
	ds_read_b128 v[220:223], v167 offset:6144
	ds_read_b128 v[224:227], v167 offset:7168
	global_load_lds_dwordx4 v140, s[44:45]
	s_add_i32 m0, s12, 0xe000
	s_nop 0
	global_load_lds_dwordx4 v138, s[44:45]
	s_waitcnt vmcnt(8)
	s_waitcnt lgkmcnt(0)
	s_setprio 1
	s_barrier
	v_mfma_f32_16x16x32_bf16 v[128:131], v[154:157], v[196:199], v[128:131]
	v_mfma_f32_16x16x32_bf16 v[124:127], v[172:175], v[196:199], v[124:127]
	v_mfma_f32_16x16x32_bf16 v[116:119], v[154:157], v[204:207], v[116:119]
	v_mfma_f32_16x16x32_bf16 v[108:111], v[172:175], v[204:207], v[108:111]
	v_mfma_f32_16x16x32_bf16 v[100:103], v[154:157], v[212:215], v[100:103]
	v_mfma_f32_16x16x32_bf16 v[92:95], v[172:175], v[212:215], v[92:95]
	v_mfma_f32_16x16x32_bf16 v[84:87], v[154:157], v[220:223], v[84:87]
	v_mfma_f32_16x16x32_bf16 v[76:79], v[172:175], v[220:223], v[76:79]
	v_mfma_f32_16x16x32_bf16 v[128:131], v[168:171], v[200:203], v[128:131]
	v_mfma_f32_16x16x32_bf16 v[124:127], v[176:179], v[200:203], v[124:127]
	v_mfma_f32_16x16x32_bf16 v[116:119], v[168:171], v[208:211], v[116:119]
	v_mfma_f32_16x16x32_bf16 v[108:111], v[176:179], v[208:211], v[108:111]
	v_mfma_f32_16x16x32_bf16 v[100:103], v[168:171], v[216:219], v[100:103]
	v_mfma_f32_16x16x32_bf16 v[92:95], v[176:179], v[216:219], v[92:95]
	v_mfma_f32_16x16x32_bf16 v[84:87], v[168:171], v[224:227], v[84:87]
	v_mfma_f32_16x16x32_bf16 v[76:79], v[176:179], v[224:227], v[76:79]
	v_mfma_f32_16x16x32_bf16 v[120:123], v[180:183], v[196:199], v[120:123]
	v_mfma_f32_16x16x32_bf16 v[112:115], v[188:191], v[196:199], v[112:115]
	v_mfma_f32_16x16x32_bf16 v[104:107], v[180:183], v[204:207], v[104:107]
	v_mfma_f32_16x16x32_bf16 v[96:99], v[188:191], v[204:207], v[96:99]
	v_mfma_f32_16x16x32_bf16 v[88:91], v[180:183], v[212:215], v[88:91]
	v_mfma_f32_16x16x32_bf16 v[80:83], v[188:191], v[212:215], v[80:83]
	v_mfma_f32_16x16x32_bf16 v[72:75], v[180:183], v[220:223], v[72:75]
	v_mfma_f32_16x16x32_bf16 v[68:71], v[188:191], v[220:223], v[68:71]
	v_mfma_f32_16x16x32_bf16 v[120:123], v[184:187], v[200:203], v[120:123]
	v_mfma_f32_16x16x32_bf16 v[112:115], v[192:195], v[200:203], v[112:115]
	v_mfma_f32_16x16x32_bf16 v[104:107], v[184:187], v[208:211], v[104:107]
	v_mfma_f32_16x16x32_bf16 v[96:99], v[192:195], v[208:211], v[96:99]
	v_mfma_f32_16x16x32_bf16 v[88:91], v[184:187], v[216:219], v[88:91]
	v_mfma_f32_16x16x32_bf16 v[80:83], v[192:195], v[216:219], v[80:83]
	v_mfma_f32_16x16x32_bf16 v[72:75], v[184:187], v[224:227], v[72:75]
	v_mfma_f32_16x16x32_bf16 v[68:71], v[192:195], v[224:227], v[68:71]
	s_barrier
	s_setprio 0
	s_add_i32 s43, s50, s10
	s_mov_b32 m0, s43
	ds_read_b128 v[196:199], v167 offset:16384
	ds_read_b128 v[200:203], v167 offset:17408
	ds_read_b128 v[204:207], v167 offset:18432
	ds_read_b128 v[208:211], v167 offset:19456
	ds_read_b128 v[212:215], v167 offset:20480
	ds_read_b128 v[216:219], v167 offset:21504
	ds_read_b128 v[220:223], v167 offset:22528
	ds_read_b128 v[224:227], v167 offset:23552
	global_load_lds_dwordx4 v2, s[46:47]
	s_add_i32 m0, s43, 0x2000
	s_add_u32 s50, s46, 0x80000
	s_addc_u32 s51, s47, 0
	s_add_i32 s33, s33, s10
	global_load_lds_dwordx4 v0, s[46:47]
	s_mov_b32 m0, s33
	s_nop 0
	global_load_lds_dwordx4 v2, s[50:51]
	s_add_i32 m0, s33, 0x2000
	s_nop 0
	global_load_lds_dwordx4 v0, s[50:51]
	s_mov_b32 m0, s12
	s_nop 0
	global_load_lds_dwordx4 v134, s[48:49]
	s_mov_b32 m0, s13
	s_nop 0
	global_load_lds_dwordx4 v132, s[48:49]
	s_waitcnt vmcnt(8)
	s_waitcnt lgkmcnt(0)
	s_setprio 1
	s_barrier
	v_mfma_f32_16x16x32_bf16 v[64:67], v[154:157], v[196:199], v[64:67]
	v_mfma_f32_16x16x32_bf16 v[60:63], v[172:175], v[196:199], v[60:63]
	v_mfma_f32_16x16x32_bf16 v[52:55], v[154:157], v[204:207], v[52:55]
	v_mfma_f32_16x16x32_bf16 v[44:47], v[172:175], v[204:207], v[44:47]
	v_mfma_f32_16x16x32_bf16 v[36:39], v[154:157], v[212:215], v[36:39]
	v_mfma_f32_16x16x32_bf16 v[28:31], v[172:175], v[212:215], v[28:31]
	v_mfma_f32_16x16x32_bf16 v[20:23], v[154:157], v[220:223], v[20:23]
	v_mfma_f32_16x16x32_bf16 v[12:15], v[172:175], v[220:223], v[12:15]
	v_mfma_f32_16x16x32_bf16 v[64:67], v[168:171], v[200:203], v[64:67]
	v_mfma_f32_16x16x32_bf16 v[60:63], v[176:179], v[200:203], v[60:63]
	v_mfma_f32_16x16x32_bf16 v[52:55], v[168:171], v[208:211], v[52:55]
	v_mfma_f32_16x16x32_bf16 v[44:47], v[176:179], v[208:211], v[44:47]
	v_mfma_f32_16x16x32_bf16 v[36:39], v[168:171], v[216:219], v[36:39]
	v_mfma_f32_16x16x32_bf16 v[28:31], v[176:179], v[216:219], v[28:31]
	v_mfma_f32_16x16x32_bf16 v[20:23], v[168:171], v[224:227], v[20:23]
	v_mfma_f32_16x16x32_bf16 v[12:15], v[176:179], v[224:227], v[12:15]
	v_mfma_f32_16x16x32_bf16 v[56:59], v[180:183], v[196:199], v[56:59]
	v_mfma_f32_16x16x32_bf16 v[48:51], v[188:191], v[196:199], v[48:51]
	v_mfma_f32_16x16x32_bf16 v[40:43], v[180:183], v[204:207], v[40:43]
	v_mfma_f32_16x16x32_bf16 v[32:35], v[188:191], v[204:207], v[32:35]
	v_mfma_f32_16x16x32_bf16 v[24:27], v[180:183], v[212:215], v[24:27]
	v_mfma_f32_16x16x32_bf16 v[16:19], v[188:191], v[212:215], v[16:19]
	v_mfma_f32_16x16x32_bf16 v[8:11], v[180:183], v[220:223], v[8:11]
	v_mfma_f32_16x16x32_bf16 v[4:7], v[188:191], v[220:223], v[4:7]
	v_mfma_f32_16x16x32_bf16 v[56:59], v[184:187], v[200:203], v[56:59]
	v_mfma_f32_16x16x32_bf16 v[48:51], v[192:195], v[200:203], v[48:51]
	v_mfma_f32_16x16x32_bf16 v[40:43], v[184:187], v[208:211], v[40:43]
	v_mfma_f32_16x16x32_bf16 v[32:35], v[192:195], v[208:211], v[32:35]
	v_mfma_f32_16x16x32_bf16 v[24:27], v[184:187], v[216:219], v[24:27]
	v_mfma_f32_16x16x32_bf16 v[16:19], v[192:195], v[216:219], v[16:19]
	v_mfma_f32_16x16x32_bf16 v[8:11], v[184:187], v[224:227], v[8:11]
	v_mfma_f32_16x16x32_bf16 v[4:7], v[192:195], v[224:227], v[4:7]
	s_barrier
	s_setprio 0
	s_add_i32 s33, 0, 0x18000
	v_add_u32_e32 v144, s33, v149
	s_add_i32 s43, 0, 0x1c000
	ds_read_b128 v[154:157], v144
	ds_read_b128 v[168:171], v144 offset:1024
	ds_read_b128 v[172:175], v144 offset:2048
	ds_read_b128 v[176:179], v144 offset:3072
	v_add_u32_e32 v144, s43, v149
	ds_read_b128 v[180:183], v144
	ds_read_b128 v[184:187], v144 offset:1024
	ds_read_b128 v[188:191], v144 offset:2048
	ds_read_b128 v[192:195], v144 offset:3072
	s_add_u32 s48, s48, 0x80000
	s_addc_u32 s49, s49, 0
	s_mov_b32 m0, s14
	ds_read_b128 v[196:199], v167 offset:32768
	ds_read_b128 v[200:203], v167 offset:33792
	ds_read_b128 v[204:207], v167 offset:34816
	ds_read_b128 v[208:211], v167 offset:35840
	ds_read_b128 v[212:215], v167 offset:36864
	ds_read_b128 v[216:219], v167 offset:37888
	ds_read_b128 v[220:223], v167 offset:38912
	ds_read_b128 v[224:227], v167 offset:39936
	global_load_lds_dwordx4 v134, s[48:49]
	s_mov_b32 m0, s15
	s_nop 0
	global_load_lds_dwordx4 v132, s[48:49]
	s_waitcnt vmcnt(8)
	s_waitcnt lgkmcnt(0)
	s_setprio 1
	s_barrier
	v_mfma_f32_16x16x32_bf16 v[128:131], v[154:157], v[196:199], v[128:131]
	v_mfma_f32_16x16x32_bf16 v[124:127], v[172:175], v[196:199], v[124:127]
	v_mfma_f32_16x16x32_bf16 v[116:119], v[154:157], v[204:207], v[116:119]
	v_mfma_f32_16x16x32_bf16 v[108:111], v[172:175], v[204:207], v[108:111]
	v_mfma_f32_16x16x32_bf16 v[100:103], v[154:157], v[212:215], v[100:103]
	v_mfma_f32_16x16x32_bf16 v[92:95], v[172:175], v[212:215], v[92:95]
	v_mfma_f32_16x16x32_bf16 v[84:87], v[154:157], v[220:223], v[84:87]
	v_mfma_f32_16x16x32_bf16 v[76:79], v[172:175], v[220:223], v[76:79]
	v_mfma_f32_16x16x32_bf16 v[128:131], v[168:171], v[200:203], v[128:131]
	v_mfma_f32_16x16x32_bf16 v[124:127], v[176:179], v[200:203], v[124:127]
	v_mfma_f32_16x16x32_bf16 v[116:119], v[168:171], v[208:211], v[116:119]
	v_mfma_f32_16x16x32_bf16 v[108:111], v[176:179], v[208:211], v[108:111]
	v_mfma_f32_16x16x32_bf16 v[100:103], v[168:171], v[216:219], v[100:103]
	v_mfma_f32_16x16x32_bf16 v[92:95], v[176:179], v[216:219], v[92:95]
	v_mfma_f32_16x16x32_bf16 v[84:87], v[168:171], v[224:227], v[84:87]
	v_mfma_f32_16x16x32_bf16 v[76:79], v[176:179], v[224:227], v[76:79]
	v_mfma_f32_16x16x32_bf16 v[120:123], v[180:183], v[196:199], v[120:123]
	v_mfma_f32_16x16x32_bf16 v[112:115], v[188:191], v[196:199], v[112:115]
	v_mfma_f32_16x16x32_bf16 v[104:107], v[180:183], v[204:207], v[104:107]
	v_mfma_f32_16x16x32_bf16 v[96:99], v[188:191], v[204:207], v[96:99]
	v_mfma_f32_16x16x32_bf16 v[88:91], v[180:183], v[212:215], v[88:91]
	v_mfma_f32_16x16x32_bf16 v[80:83], v[188:191], v[212:215], v[80:83]
	v_mfma_f32_16x16x32_bf16 v[72:75], v[180:183], v[220:223], v[72:75]
	v_mfma_f32_16x16x32_bf16 v[68:71], v[188:191], v[220:223], v[68:71]
	v_mfma_f32_16x16x32_bf16 v[120:123], v[184:187], v[200:203], v[120:123]
	v_mfma_f32_16x16x32_bf16 v[112:115], v[192:195], v[200:203], v[112:115]
	v_mfma_f32_16x16x32_bf16 v[104:107], v[184:187], v[208:211], v[104:107]
	v_mfma_f32_16x16x32_bf16 v[96:99], v[192:195], v[208:211], v[96:99]
	v_mfma_f32_16x16x32_bf16 v[88:91], v[184:187], v[216:219], v[88:91]
	v_mfma_f32_16x16x32_bf16 v[80:83], v[192:195], v[216:219], v[80:83]
	v_mfma_f32_16x16x32_bf16 v[72:75], v[184:187], v[224:227], v[72:75]
	v_mfma_f32_16x16x32_bf16 v[68:71], v[192:195], v[224:227], v[68:71]
	s_barrier
	s_setprio 0
	s_add_i32 s33, s33, s10
	s_mov_b32 m0, s33
	ds_read_b128 v[196:199], v167 offset:49152
	ds_read_b128 v[200:203], v167 offset:50176
	ds_read_b128 v[204:207], v167 offset:51200
	ds_read_b128 v[208:211], v167 offset:52224
	ds_read_b128 v[212:215], v167 offset:53248
	ds_read_b128 v[216:219], v167 offset:54272
	ds_read_b128 v[220:223], v167 offset:55296
	ds_read_b128 v[224:227], v167 offset:56320
	s_add_u32 s100, s46, 0x80
	s_addc_u32 s101, s47, 0
	global_load_lds_dwordx4 v2, s[100:101]
	s_add_i32 m0, s33, 0x2000
	s_add_u32 s46, s46, 0x80080
	s_addc_u32 s47, s47, 0
	s_add_i32 s33, s43, s10
	s_add_u32 s100, s46, 0xfff80000
	s_addc_u32 s101, s47, -1
	global_load_lds_dwordx4 v0, s[100:101]
	s_mov_b32 m0, s33
	s_nop 0
	global_load_lds_dwordx4 v2, s[46:47]
	s_add_i32 m0, s33, 0x2000
	s_nop 0
	global_load_lds_dwordx4 v0, s[46:47]
	s_mov_b32 m0, s16
	s_nop 0
	s_add_u32 s100, s48, 0xfff80080
	s_addc_u32 s101, s49, -1
	global_load_lds_dwordx4 v134, s[100:101]
	s_mov_b32 m0, s17
	s_nop 0
	s_add_u32 s100, s48, 0xfff80080
	s_addc_u32 s101, s49, -1
	global_load_lds_dwordx4 v132, s[100:101]
	s_waitcnt vmcnt(8)
	s_waitcnt lgkmcnt(0)
	s_setprio 1
	s_barrier
	v_mfma_f32_16x16x32_bf16 v[64:67], v[154:157], v[196:199], v[64:67]
	v_mfma_f32_16x16x32_bf16 v[60:63], v[172:175], v[196:199], v[60:63]
	v_mfma_f32_16x16x32_bf16 v[52:55], v[154:157], v[204:207], v[52:55]
	v_mfma_f32_16x16x32_bf16 v[44:47], v[172:175], v[204:207], v[44:47]
	v_mfma_f32_16x16x32_bf16 v[36:39], v[154:157], v[212:215], v[36:39]
	v_mfma_f32_16x16x32_bf16 v[28:31], v[172:175], v[212:215], v[28:31]
	v_mfma_f32_16x16x32_bf16 v[20:23], v[154:157], v[220:223], v[20:23]
	v_mfma_f32_16x16x32_bf16 v[12:15], v[172:175], v[220:223], v[12:15]
	v_mfma_f32_16x16x32_bf16 v[64:67], v[168:171], v[200:203], v[64:67]
	v_mfma_f32_16x16x32_bf16 v[60:63], v[176:179], v[200:203], v[60:63]
	v_mfma_f32_16x16x32_bf16 v[52:55], v[168:171], v[208:211], v[52:55]
	v_mfma_f32_16x16x32_bf16 v[44:47], v[176:179], v[208:211], v[44:47]
	v_mfma_f32_16x16x32_bf16 v[36:39], v[168:171], v[216:219], v[36:39]
	v_mfma_f32_16x16x32_bf16 v[28:31], v[176:179], v[216:219], v[28:31]
	v_mfma_f32_16x16x32_bf16 v[20:23], v[168:171], v[224:227], v[20:23]
	v_mfma_f32_16x16x32_bf16 v[12:15], v[176:179], v[224:227], v[12:15]
	v_mfma_f32_16x16x32_bf16 v[56:59], v[180:183], v[196:199], v[56:59]
	v_mfma_f32_16x16x32_bf16 v[48:51], v[188:191], v[196:199], v[48:51]
	v_mfma_f32_16x16x32_bf16 v[40:43], v[180:183], v[204:207], v[40:43]
	v_mfma_f32_16x16x32_bf16 v[32:35], v[188:191], v[204:207], v[32:35]
	v_mfma_f32_16x16x32_bf16 v[24:27], v[180:183], v[212:215], v[24:27]
	v_mfma_f32_16x16x32_bf16 v[16:19], v[188:191], v[212:215], v[16:19]
	v_mfma_f32_16x16x32_bf16 v[8:11], v[180:183], v[220:223], v[8:11]
	v_mfma_f32_16x16x32_bf16 v[4:7], v[188:191], v[220:223], v[4:7]
	v_mfma_f32_16x16x32_bf16 v[56:59], v[184:187], v[200:203], v[56:59]
	v_mfma_f32_16x16x32_bf16 v[48:51], v[192:195], v[200:203], v[48:51]
	v_mfma_f32_16x16x32_bf16 v[40:43], v[184:187], v[208:211], v[40:43]
	v_mfma_f32_16x16x32_bf16 v[32:35], v[192:195], v[208:211], v[32:35]
	v_mfma_f32_16x16x32_bf16 v[24:27], v[184:187], v[216:219], v[24:27]
	v_mfma_f32_16x16x32_bf16 v[16:19], v[192:195], v[216:219], v[16:19]
	v_mfma_f32_16x16x32_bf16 v[8:11], v[184:187], v[224:227], v[8:11]
	v_mfma_f32_16x16x32_bf16 v[4:7], v[192:195], v[224:227], v[4:7]
	s_barrier
	s_setprio 0
	s_add_i32 s35, s35, 2
	s_add_u32 s31, s31, 0x100
	s_addc_u32 s34, s34, 0
	s_add_u32 s44, s44, 0x100
	s_addc_u32 s45, s45, 0
	s_cmp_gt_u32 s35, 29
	s_cbranch_scc0 .LBB0_342
	s_and_b64 vcc, exec, s[22:23]
	s_cbranch_vccz .LBB0_345
	s_nop 0

.LBB0_740:
	s_mov_b32 s48, s6
	s_ashr_i32 s49, s6, 31
	s_mov_b32 s94, s7
	s_lshl_b64 s[6:7], s[48:49], 20
	s_add_u32 s56, s70, s6
	s_addc_u32 s57, s71, s7
	s_and_b64 s[6:7], exec, s[52:53]
	s_mov_b32 s50, s5
	s_cselect_b32 s5, s57, s39
	s_cselect_b32 s6, s56, s38
	s_add_u32 s60, s80, s60
	s_addc_u32 s61, s81, s61
	s_mov_b32 s67, s8
	s_and_b64 s[8:9], exec, s[52:53]
	s_cselect_b32 s7, s61, s37
	s_cselect_b32 s8, s60, s36
	s_add_u32 s9, s36, 0x100
	s_addc_u32 s10, s37, 0
	s_add_u32 s36, s38, 0x80080
	s_addc_u32 s37, s39, 0
	s_mov_b32 s11, -2
	s_waitcnt lgkmcnt(0)
	s_add_u32 s12, s36, 0xfff80080
	s_addc_u32 s13, s37, -1
	s_add_i32 s14, 0, 0x10000
	s_cmp_eq_u32 s11, 28
	s_cselect_b32 s63, s5, s13
	s_cselect_b32 s62, s6, s12
	s_cselect_b32 s39, s7, s10
	s_cselect_b32 s38, s8, s9
	s_add_i32 s15, 0, 0x14000
	v_add_u32_e32 v144, s14, v230
	v_add_u32_e32 v160, s15, v230
	ds_read_b128 v[124:127], v144
	ds_read_b128 v[128:131], v144 offset:1024
	ds_read_b128 v[136:139], v144 offset:2048
	ds_read_b128 v[144:147], v144 offset:3072
	ds_read_b128 v[148:151], v160
	ds_read_b128 v[152:155], v160 offset:1024
	ds_read_b128 v[156:159], v160 offset:2048
	ds_read_b128 v[160:163], v160 offset:3072
	v_lshl_add_u64 v[196:197], s[36:37], 0, v[222:223]
	s_add_i32 m0, s21, 0xc000
	ds_read_b128 v[164:167], v243
	ds_read_b128 v[168:171], v243 offset:1024
	ds_read_b128 v[172:175], v243 offset:2048
	ds_read_b128 v[176:179], v243 offset:3072
	ds_read_b128 v[180:183], v243 offset:4096
	ds_read_b128 v[184:187], v243 offset:5120
	ds_read_b128 v[188:191], v243 offset:6144
	ds_read_b128 v[192:195], v243 offset:7168
	global_load_lds_dwordx4 v[196:197], off
	v_lshl_add_u64 v[196:197], s[36:37], 0, v[220:221]
	s_add_i32 m0, s21, 0xe000
	s_nop 0
	global_load_lds_dwordx4 v[196:197], off
	s_waitcnt vmcnt(8)
	s_waitcnt lgkmcnt(0)
	s_setprio 1
	s_barrier
	v_mfma_f32_16x16x32_bf16 v[140:143], v[124:127], v[164:167], 0
	v_mfma_f32_16x16x32_bf16 v[132:135], v[136:139], v[164:167], 0
	v_mfma_f32_16x16x32_bf16 v[112:115], v[124:127], v[172:175], 0
	v_mfma_f32_16x16x32_bf16 v[108:111], v[136:139], v[172:175], 0
	v_mfma_f32_16x16x32_bf16 v[96:99], v[124:127], v[180:183], 0
	v_mfma_f32_16x16x32_bf16 v[92:95], v[136:139], v[180:183], 0
	v_mfma_f32_16x16x32_bf16 v[80:83], v[124:127], v[188:191], 0
	v_mfma_f32_16x16x32_bf16 v[76:79], v[136:139], v[188:191], 0
	v_mfma_f32_16x16x32_bf16 v[140:143], v[128:131], v[168:171], v[140:143]
	v_mfma_f32_16x16x32_bf16 v[132:135], v[144:147], v[168:171], v[132:135]
	v_mfma_f32_16x16x32_bf16 v[112:115], v[128:131], v[176:179], v[112:115]
	v_mfma_f32_16x16x32_bf16 v[108:111], v[144:147], v[176:179], v[108:111]
	v_mfma_f32_16x16x32_bf16 v[96:99], v[128:131], v[184:187], v[96:99]
	v_mfma_f32_16x16x32_bf16 v[92:95], v[144:147], v[184:187], v[92:95]
	v_mfma_f32_16x16x32_bf16 v[80:83], v[128:131], v[192:195], v[80:83]
	v_mfma_f32_16x16x32_bf16 v[76:79], v[144:147], v[192:195], v[76:79]
	s_setprio 0
	s_setprio 1
	v_mfma_f32_16x16x32_bf16 v[120:123], v[148:151], v[164:167], 0
	v_mfma_f32_16x16x32_bf16 v[116:119], v[156:159], v[164:167], 0
	v_mfma_f32_16x16x32_bf16 v[104:107], v[148:151], v[172:175], 0
	v_mfma_f32_16x16x32_bf16 v[100:103], v[156:159], v[172:175], 0
	v_mfma_f32_16x16x32_bf16 v[88:91], v[148:151], v[180:183], 0
	v_mfma_f32_16x16x32_bf16 v[84:87], v[156:159], v[180:183], 0
	v_mfma_f32_16x16x32_bf16 v[72:75], v[148:151], v[188:191], 0
	v_mfma_f32_16x16x32_bf16 v[68:71], v[156:159], v[188:191], 0
	v_mfma_f32_16x16x32_bf16 v[120:123], v[152:155], v[168:171], v[120:123]
	v_mfma_f32_16x16x32_bf16 v[116:119], v[160:163], v[168:171], v[116:119]
	v_mfma_f32_16x16x32_bf16 v[104:107], v[152:155], v[176:179], v[104:107]
	v_mfma_f32_16x16x32_bf16 v[100:103], v[160:163], v[176:179], v[100:103]
	v_mfma_f32_16x16x32_bf16 v[88:91], v[152:155], v[184:187], v[88:91]
	v_mfma_f32_16x16x32_bf16 v[84:87], v[160:163], v[184:187], v[84:87]
	v_mfma_f32_16x16x32_bf16 v[72:75], v[152:155], v[192:195], v[72:75]
	v_mfma_f32_16x16x32_bf16 v[68:71], v[160:163], v[192:195], v[68:71]
	s_barrier
	s_setprio 0
	s_add_i32 s12, s14, s82
	v_lshl_add_u64 v[196:197], s[38:39], 0, v[2:3]
	s_mov_b32 m0, s12
	ds_read_b128 v[164:167], v243 offset:16384
	ds_read_b128 v[168:171], v243 offset:17408
	ds_read_b128 v[172:175], v243 offset:18432
	ds_read_b128 v[176:179], v243 offset:19456
	ds_read_b128 v[180:183], v243 offset:20480
	ds_read_b128 v[184:187], v243 offset:21504
	ds_read_b128 v[188:191], v243 offset:22528
	ds_read_b128 v[192:195], v243 offset:23552
	global_load_lds_dwordx4 v[196:197], off
	s_add_i32 m0, s12, 0x2000
	s_add_u32 s12, s38, 0x80000
	v_lshl_add_u64 v[198:199], s[38:39], 0, v[218:219]
	s_addc_u32 s13, s39, 0
	s_add_i32 s14, s15, s82
	global_load_lds_dwordx4 v[198:199], off
	v_lshl_add_u64 v[200:201], s[12:13], 0, v[2:3]
	s_mov_b32 m0, s14
	v_lshl_add_u64 v[202:203], s[62:63], 0, v[216:217]
	global_load_lds_dwordx4 v[200:201], off
	v_lshl_add_u64 v[200:201], s[12:13], 0, v[218:219]
	s_add_i32 m0, s14, 0x2000
	s_nop 0
	global_load_lds_dwordx4 v[200:201], off
	v_lshl_add_u64 v[200:201], s[62:63], 0, v[0:1]
	s_mov_b32 m0, s21
	s_nop 0
	global_load_lds_dwordx4 v[200:201], off
	s_mov_b32 m0, s83
	s_nop 0
	global_load_lds_dwordx4 v[202:203], off
	s_waitcnt vmcnt(8)
	s_waitcnt lgkmcnt(0)
	s_setprio 1
	s_barrier
	v_mfma_f32_16x16x32_bf16 v[64:67], v[124:127], v[164:167], 0
	v_mfma_f32_16x16x32_bf16 v[60:63], v[136:139], v[164:167], 0
	v_mfma_f32_16x16x32_bf16 v[48:51], v[124:127], v[172:175], 0
	v_mfma_f32_16x16x32_bf16 v[44:47], v[136:139], v[172:175], 0
	v_mfma_f32_16x16x32_bf16 v[32:35], v[124:127], v[180:183], 0
	v_mfma_f32_16x16x32_bf16 v[28:31], v[136:139], v[180:183], 0
	v_mfma_f32_16x16x32_bf16 v[16:19], v[124:127], v[188:191], 0
	v_mfma_f32_16x16x32_bf16 v[12:15], v[136:139], v[188:191], 0
	v_mfma_f32_16x16x32_bf16 v[64:67], v[128:131], v[168:171], v[64:67]
	v_mfma_f32_16x16x32_bf16 v[60:63], v[144:147], v[168:171], v[60:63]
	v_mfma_f32_16x16x32_bf16 v[48:51], v[128:131], v[176:179], v[48:51]
	v_mfma_f32_16x16x32_bf16 v[44:47], v[144:147], v[176:179], v[44:47]
	v_mfma_f32_16x16x32_bf16 v[32:35], v[128:131], v[184:187], v[32:35]
	v_mfma_f32_16x16x32_bf16 v[28:31], v[144:147], v[184:187], v[28:31]
	v_mfma_f32_16x16x32_bf16 v[16:19], v[128:131], v[192:195], v[16:19]
	v_mfma_f32_16x16x32_bf16 v[12:15], v[144:147], v[192:195], v[12:15]
	s_setprio 0
	s_setprio 1
	v_mfma_f32_16x16x32_bf16 v[56:59], v[148:151], v[164:167], 0
	v_mfma_f32_16x16x32_bf16 v[52:55], v[156:159], v[164:167], 0
	v_mfma_f32_16x16x32_bf16 v[40:43], v[148:151], v[172:175], 0
	v_mfma_f32_16x16x32_bf16 v[36:39], v[156:159], v[172:175], 0
	v_mfma_f32_16x16x32_bf16 v[24:27], v[148:151], v[180:183], 0
	v_mfma_f32_16x16x32_bf16 v[20:23], v[156:159], v[180:183], 0
	v_mfma_f32_16x16x32_bf16 v[8:11], v[148:151], v[188:191], 0
	v_mfma_f32_16x16x32_bf16 v[4:7], v[156:159], v[188:191], 0
	v_mfma_f32_16x16x32_bf16 v[56:59], v[152:155], v[168:171], v[56:59]
	v_mfma_f32_16x16x32_bf16 v[52:55], v[160:163], v[168:171], v[52:55]
	v_mfma_f32_16x16x32_bf16 v[40:43], v[152:155], v[176:179], v[40:43]
	v_mfma_f32_16x16x32_bf16 v[36:39], v[160:163], v[176:179], v[36:39]
	v_mfma_f32_16x16x32_bf16 v[24:27], v[152:155], v[184:187], v[24:27]
	v_mfma_f32_16x16x32_bf16 v[20:23], v[160:163], v[184:187], v[20:23]
	v_mfma_f32_16x16x32_bf16 v[8:11], v[152:155], v[192:195], v[8:11]
	v_mfma_f32_16x16x32_bf16 v[4:7], v[160:163], v[192:195], v[4:7]
	s_barrier
	s_setprio 0
	s_add_i32 s14, 0, 0x18000
	s_add_i32 s15, 0, 0x1c000
	v_add_u32_e32 v144, s14, v230
	v_add_u32_e32 v160, s15, v230
	ds_read_b128 v[124:127], v144
	ds_read_b128 v[128:131], v144 offset:1024
	ds_read_b128 v[136:139], v144 offset:2048
	ds_read_b128 v[144:147], v144 offset:3072
	ds_read_b128 v[148:151], v160
	ds_read_b128 v[152:155], v160 offset:1024
	ds_read_b128 v[156:159], v160 offset:2048
	ds_read_b128 v[160:163], v160 offset:3072
	s_add_u32 s12, s62, 0x80000
	s_addc_u32 s13, s63, 0
	s_mov_b32 m0, s84
	v_lshl_add_u64 v[204:205], s[12:13], 0, v[0:1]
	ds_read_b128 v[164:167], v243 offset:32768
	ds_read_b128 v[168:171], v243 offset:33792
	ds_read_b128 v[172:175], v243 offset:34816
	ds_read_b128 v[176:179], v243 offset:35840
	ds_read_b128 v[180:183], v243 offset:36864
	ds_read_b128 v[184:187], v243 offset:37888
	ds_read_b128 v[188:191], v243 offset:38912
	ds_read_b128 v[192:195], v243 offset:39936
	global_load_lds_dwordx4 v[204:205], off
	v_lshl_add_u64 v[204:205], s[12:13], 0, v[216:217]
	s_mov_b32 m0, s85
	s_nop 0
	global_load_lds_dwordx4 v[204:205], off
	s_waitcnt vmcnt(8)
	s_waitcnt lgkmcnt(0)
	s_setprio 1
	s_barrier
	v_mfma_f32_16x16x32_bf16 v[140:143], v[124:127], v[164:167], v[140:143]
	v_mfma_f32_16x16x32_bf16 v[132:135], v[136:139], v[164:167], v[132:135]
	v_mfma_f32_16x16x32_bf16 v[112:115], v[124:127], v[172:175], v[112:115]
	v_mfma_f32_16x16x32_bf16 v[108:111], v[136:139], v[172:175], v[108:111]
	v_mfma_f32_16x16x32_bf16 v[96:99], v[124:127], v[180:183], v[96:99]
	v_mfma_f32_16x16x32_bf16 v[92:95], v[136:139], v[180:183], v[92:95]
	v_mfma_f32_16x16x32_bf16 v[80:83], v[124:127], v[188:191], v[80:83]
	v_mfma_f32_16x16x32_bf16 v[76:79], v[136:139], v[188:191], v[76:79]
	v_mfma_f32_16x16x32_bf16 v[140:143], v[128:131], v[168:171], v[140:143]
	v_mfma_f32_16x16x32_bf16 v[132:135], v[144:147], v[168:171], v[132:135]
	v_mfma_f32_16x16x32_bf16 v[112:115], v[128:131], v[176:179], v[112:115]
	v_mfma_f32_16x16x32_bf16 v[108:111], v[144:147], v[176:179], v[108:111]
	v_mfma_f32_16x16x32_bf16 v[96:99], v[128:131], v[184:187], v[96:99]
	v_mfma_f32_16x16x32_bf16 v[92:95], v[144:147], v[184:187], v[92:95]
	v_mfma_f32_16x16x32_bf16 v[80:83], v[128:131], v[192:195], v[80:83]
	v_mfma_f32_16x16x32_bf16 v[76:79], v[144:147], v[192:195], v[76:79]
	s_setprio 0
	s_setprio 1
	v_mfma_f32_16x16x32_bf16 v[120:123], v[148:151], v[164:167], v[120:123]
	v_mfma_f32_16x16x32_bf16 v[116:119], v[156:159], v[164:167], v[116:119]
	v_mfma_f32_16x16x32_bf16 v[104:107], v[148:151], v[172:175], v[104:107]
	v_mfma_f32_16x16x32_bf16 v[100:103], v[156:159], v[172:175], v[100:103]
	v_mfma_f32_16x16x32_bf16 v[88:91], v[148:151], v[180:183], v[88:91]
	v_mfma_f32_16x16x32_bf16 v[84:87], v[156:159], v[180:183], v[84:87]
	v_mfma_f32_16x16x32_bf16 v[72:75], v[148:151], v[188:191], v[72:75]
	v_mfma_f32_16x16x32_bf16 v[68:71], v[156:159], v[188:191], v[68:71]
	v_mfma_f32_16x16x32_bf16 v[120:123], v[152:155], v[168:171], v[120:123]
	v_mfma_f32_16x16x32_bf16 v[116:119], v[160:163], v[168:171], v[116:119]
	v_mfma_f32_16x16x32_bf16 v[104:107], v[152:155], v[176:179], v[104:107]
	v_mfma_f32_16x16x32_bf16 v[100:103], v[160:163], v[176:179], v[100:103]
	v_mfma_f32_16x16x32_bf16 v[88:91], v[152:155], v[184:187], v[88:91]
	v_mfma_f32_16x16x32_bf16 v[84:87], v[160:163], v[184:187], v[84:87]
	v_mfma_f32_16x16x32_bf16 v[72:75], v[152:155], v[192:195], v[72:75]
	v_mfma_f32_16x16x32_bf16 v[68:71], v[160:163], v[192:195], v[68:71]
	s_barrier
	s_setprio 0
	s_add_i32 s12, s14, s82
	v_lshl_add_u64 v[196:197], v[196:197], 0, s[68:69]
	s_mov_b32 m0, s12
	ds_read_b128 v[164:167], v243 offset:49152
	ds_read_b128 v[168:171], v243 offset:50176
	ds_read_b128 v[172:175], v243 offset:51200
	ds_read_b128 v[176:179], v243 offset:52224
	ds_read_b128 v[180:183], v243 offset:53248
	ds_read_b128 v[184:187], v243 offset:54272
	ds_read_b128 v[188:191], v243 offset:55296
	ds_read_b128 v[192:195], v243 offset:56320
	global_load_lds_dwordx4 v[196:197], off
	s_add_i32 m0, s12, 0x2000
	s_add_u32 s12, s38, 0x80080
	v_lshl_add_u64 v[196:197], v[198:199], 0, s[68:69]
	s_addc_u32 s13, s39, 0
	s_add_i32 s14, s15, s82
	global_load_lds_dwordx4 v[196:197], off
	v_lshl_add_u64 v[196:197], s[12:13], 0, v[2:3]
	s_mov_b32 m0, s14
	s_nop 0
	global_load_lds_dwordx4 v[196:197], off
	v_lshl_add_u64 v[196:197], s[12:13], 0, v[218:219]
	s_add_i32 m0, s14, 0x2000
	s_nop 0
	global_load_lds_dwordx4 v[196:197], off
	v_lshl_add_u64 v[196:197], v[200:201], 0, s[68:69]
	s_mov_b32 m0, s89
	s_nop 0
	global_load_lds_dwordx4 v[196:197], off
	v_lshl_add_u64 v[196:197], v[202:203], 0, s[68:69]
	s_mov_b32 m0, s90
	s_nop 0
	global_load_lds_dwordx4 v[196:197], off
	s_waitcnt vmcnt(8)
	s_waitcnt lgkmcnt(0)
	s_setprio 1
	s_barrier
	v_mfma_f32_16x16x32_bf16 v[64:67], v[124:127], v[164:167], v[64:67]
	v_mfma_f32_16x16x32_bf16 v[60:63], v[136:139], v[164:167], v[60:63]
	v_mfma_f32_16x16x32_bf16 v[48:51], v[124:127], v[172:175], v[48:51]
	v_mfma_f32_16x16x32_bf16 v[44:47], v[136:139], v[172:175], v[44:47]
	v_mfma_f32_16x16x32_bf16 v[32:35], v[124:127], v[180:183], v[32:35]
	v_mfma_f32_16x16x32_bf16 v[28:31], v[136:139], v[180:183], v[28:31]
	v_mfma_f32_16x16x32_bf16 v[16:19], v[124:127], v[188:191], v[16:19]
	v_mfma_f32_16x16x32_bf16 v[12:15], v[136:139], v[188:191], v[12:15]
	v_mfma_f32_16x16x32_bf16 v[64:67], v[128:131], v[168:171], v[64:67]
	v_mfma_f32_16x16x32_bf16 v[60:63], v[144:147], v[168:171], v[60:63]
	v_mfma_f32_16x16x32_bf16 v[48:51], v[128:131], v[176:179], v[48:51]
	v_mfma_f32_16x16x32_bf16 v[44:47], v[144:147], v[176:179], v[44:47]
	v_mfma_f32_16x16x32_bf16 v[32:35], v[128:131], v[184:187], v[32:35]
	v_mfma_f32_16x16x32_bf16 v[28:31], v[144:147], v[184:187], v[28:31]
	v_mfma_f32_16x16x32_bf16 v[16:19], v[128:131], v[192:195], v[16:19]
	v_mfma_f32_16x16x32_bf16 v[12:15], v[144:147], v[192:195], v[12:15]
	s_setprio 0
	s_setprio 1
	v_mfma_f32_16x16x32_bf16 v[56:59], v[148:151], v[164:167], v[56:59]
	v_mfma_f32_16x16x32_bf16 v[52:55], v[156:159], v[164:167], v[52:55]
	v_mfma_f32_16x16x32_bf16 v[40:43], v[148:151], v[172:175], v[40:43]
	v_mfma_f32_16x16x32_bf16 v[36:39], v[156:159], v[172:175], v[36:39]
	v_mfma_f32_16x16x32_bf16 v[24:27], v[148:151], v[180:183], v[24:27]
	v_mfma_f32_16x16x32_bf16 v[20:23], v[156:159], v[180:183], v[20:23]
	v_mfma_f32_16x16x32_bf16 v[8:11], v[148:151], v[188:191], v[8:11]
	v_mfma_f32_16x16x32_bf16 v[4:7], v[156:159], v[188:191], v[4:7]
	v_mfma_f32_16x16x32_bf16 v[56:59], v[152:155], v[168:171], v[56:59]
	v_mfma_f32_16x16x32_bf16 v[52:55], v[160:163], v[168:171], v[52:55]
	v_mfma_f32_16x16x32_bf16 v[40:43], v[152:155], v[176:179], v[40:43]
	v_mfma_f32_16x16x32_bf16 v[36:39], v[160:163], v[176:179], v[36:39]
	v_mfma_f32_16x16x32_bf16 v[24:27], v[152:155], v[184:187], v[24:27]
	v_mfma_f32_16x16x32_bf16 v[20:23], v[160:163], v[184:187], v[20:23]
	v_mfma_f32_16x16x32_bf16 v[8:11], v[152:155], v[192:195], v[8:11]
	v_mfma_f32_16x16x32_bf16 v[4:7], v[160:163], v[192:195], v[4:7]
	s_barrier
	s_setprio 0
	s_add_i32 s11, s11, 2
	s_add_u32 s9, s9, 0x100
	s_addc_u32 s10, s10, 0
	s_add_u32 s36, s36, 0x100
	s_addc_u32 s37, s37, 0
	s_cmp_gt_u32 s11, 29
.LBB0_741:
	s_add_u32 s12, s36, 0xfff80080
	s_addc_u32 s13, s37, -1
	s_add_i32 s14, 0, 0x10000
	s_cmp_eq_u32 s11, 28
	s_cselect_b32 s63, s5, s13
	s_cselect_b32 s62, s6, s12
	s_cselect_b32 s39, s7, s10
	s_cselect_b32 s38, s8, s9
	s_add_i32 s15, 0, 0x14000
	v_add_u32_e32 v144, s14, v230
	v_add_u32_e32 v160, s15, v230
	ds_read_b128 v[124:127], v144
	ds_read_b128 v[128:131], v144 offset:1024
	ds_read_b128 v[136:139], v144 offset:2048
	ds_read_b128 v[144:147], v144 offset:3072
	ds_read_b128 v[148:151], v160
	ds_read_b128 v[152:155], v160 offset:1024
	ds_read_b128 v[156:159], v160 offset:2048
	ds_read_b128 v[160:163], v160 offset:3072
	v_lshl_add_u64 v[196:197], s[36:37], 0, v[222:223]
	s_add_i32 m0, s21, 0xc000
	ds_read_b128 v[164:167], v243
	ds_read_b128 v[168:171], v243 offset:1024
	ds_read_b128 v[172:175], v243 offset:2048
	ds_read_b128 v[176:179], v243 offset:3072
	ds_read_b128 v[180:183], v243 offset:4096
	ds_read_b128 v[184:187], v243 offset:5120
	ds_read_b128 v[188:191], v243 offset:6144
	ds_read_b128 v[192:195], v243 offset:7168
	global_load_lds_dwordx4 v[196:197], off
	v_lshl_add_u64 v[196:197], s[36:37], 0, v[220:221]
	s_add_i32 m0, s21, 0xe000
	s_nop 0
	global_load_lds_dwordx4 v[196:197], off
	s_waitcnt vmcnt(8)
	s_waitcnt lgkmcnt(0)
	s_setprio 1
	s_barrier
	v_mfma_f32_16x16x32_bf16 v[140:143], v[124:127], v[164:167], v[140:143]
	v_mfma_f32_16x16x32_bf16 v[132:135], v[136:139], v[164:167], v[132:135]
	v_mfma_f32_16x16x32_bf16 v[112:115], v[124:127], v[172:175], v[112:115]
	v_mfma_f32_16x16x32_bf16 v[108:111], v[136:139], v[172:175], v[108:111]
	v_mfma_f32_16x16x32_bf16 v[96:99], v[124:127], v[180:183], v[96:99]
	v_mfma_f32_16x16x32_bf16 v[92:95], v[136:139], v[180:183], v[92:95]
	v_mfma_f32_16x16x32_bf16 v[80:83], v[124:127], v[188:191], v[80:83]
	v_mfma_f32_16x16x32_bf16 v[76:79], v[136:139], v[188:191], v[76:79]
	v_mfma_f32_16x16x32_bf16 v[140:143], v[128:131], v[168:171], v[140:143]
	v_mfma_f32_16x16x32_bf16 v[132:135], v[144:147], v[168:171], v[132:135]
	v_mfma_f32_16x16x32_bf16 v[112:115], v[128:131], v[176:179], v[112:115]
	v_mfma_f32_16x16x32_bf16 v[108:111], v[144:147], v[176:179], v[108:111]
	v_mfma_f32_16x16x32_bf16 v[96:99], v[128:131], v[184:187], v[96:99]
	v_mfma_f32_16x16x32_bf16 v[92:95], v[144:147], v[184:187], v[92:95]
	v_mfma_f32_16x16x32_bf16 v[80:83], v[128:131], v[192:195], v[80:83]
	v_mfma_f32_16x16x32_bf16 v[76:79], v[144:147], v[192:195], v[76:79]
	s_setprio 0
	s_setprio 1
	v_mfma_f32_16x16x32_bf16 v[120:123], v[148:151], v[164:167], v[120:123]
	v_mfma_f32_16x16x32_bf16 v[116:119], v[156:159], v[164:167], v[116:119]
	v_mfma_f32_16x16x32_bf16 v[104:107], v[148:151], v[172:175], v[104:107]
	v_mfma_f32_16x16x32_bf16 v[100:103], v[156:159], v[172:175], v[100:103]
	v_mfma_f32_16x16x32_bf16 v[88:91], v[148:151], v[180:183], v[88:91]
	v_mfma_f32_16x16x32_bf16 v[84:87], v[156:159], v[180:183], v[84:87]
	v_mfma_f32_16x16x32_bf16 v[72:75], v[148:151], v[188:191], v[72:75]
	v_mfma_f32_16x16x32_bf16 v[68:71], v[156:159], v[188:191], v[68:71]
	v_mfma_f32_16x16x32_bf16 v[120:123], v[152:155], v[168:171], v[120:123]
	v_mfma_f32_16x16x32_bf16 v[116:119], v[160:163], v[168:171], v[116:119]
	v_mfma_f32_16x16x32_bf16 v[104:107], v[152:155], v[176:179], v[104:107]
	v_mfma_f32_16x16x32_bf16 v[100:103], v[160:163], v[176:179], v[100:103]
	v_mfma_f32_16x16x32_bf16 v[88:91], v[152:155], v[184:187], v[88:91]
	v_mfma_f32_16x16x32_bf16 v[84:87], v[160:163], v[184:187], v[84:87]
	v_mfma_f32_16x16x32_bf16 v[72:75], v[152:155], v[192:195], v[72:75]
	v_mfma_f32_16x16x32_bf16 v[68:71], v[160:163], v[192:195], v[68:71]
	s_barrier
	s_setprio 0
	s_add_i32 s12, s14, s82
	v_lshl_add_u64 v[196:197], s[38:39], 0, v[2:3]
	s_mov_b32 m0, s12
	ds_read_b128 v[164:167], v243 offset:16384
	ds_read_b128 v[168:171], v243 offset:17408
	ds_read_b128 v[172:175], v243 offset:18432
	ds_read_b128 v[176:179], v243 offset:19456
	ds_read_b128 v[180:183], v243 offset:20480
	ds_read_b128 v[184:187], v243 offset:21504
	ds_read_b128 v[188:191], v243 offset:22528
	ds_read_b128 v[192:195], v243 offset:23552
	global_load_lds_dwordx4 v[196:197], off
	s_add_i32 m0, s12, 0x2000
	s_add_u32 s12, s38, 0x80000
	v_lshl_add_u64 v[198:199], s[38:39], 0, v[218:219]
	s_addc_u32 s13, s39, 0
	s_add_i32 s14, s15, s82
	global_load_lds_dwordx4 v[198:199], off
	v_lshl_add_u64 v[200:201], s[12:13], 0, v[2:3]
	s_mov_b32 m0, s14
	v_lshl_add_u64 v[202:203], s[62:63], 0, v[216:217]
	global_load_lds_dwordx4 v[200:201], off
	v_lshl_add_u64 v[200:201], s[12:13], 0, v[218:219]
	s_add_i32 m0, s14, 0x2000
	s_nop 0
	global_load_lds_dwordx4 v[200:201], off
	v_lshl_add_u64 v[200:201], s[62:63], 0, v[0:1]
	s_mov_b32 m0, s21
	s_nop 0
	global_load_lds_dwordx4 v[200:201], off
	s_mov_b32 m0, s83
	s_nop 0
	global_load_lds_dwordx4 v[202:203], off
	s_waitcnt vmcnt(8)
	s_waitcnt lgkmcnt(0)
	s_setprio 1
	s_barrier
	v_mfma_f32_16x16x32_bf16 v[64:67], v[124:127], v[164:167], v[64:67]
	v_mfma_f32_16x16x32_bf16 v[60:63], v[136:139], v[164:167], v[60:63]
	v_mfma_f32_16x16x32_bf16 v[48:51], v[124:127], v[172:175], v[48:51]
	v_mfma_f32_16x16x32_bf16 v[44:47], v[136:139], v[172:175], v[44:47]
	v_mfma_f32_16x16x32_bf16 v[32:35], v[124:127], v[180:183], v[32:35]
	v_mfma_f32_16x16x32_bf16 v[28:31], v[136:139], v[180:183], v[28:31]
	v_mfma_f32_16x16x32_bf16 v[16:19], v[124:127], v[188:191], v[16:19]
	v_mfma_f32_16x16x32_bf16 v[12:15], v[136:139], v[188:191], v[12:15]
	v_mfma_f32_16x16x32_bf16 v[64:67], v[128:131], v[168:171], v[64:67]
	v_mfma_f32_16x16x32_bf16 v[60:63], v[144:147], v[168:171], v[60:63]
	v_mfma_f32_16x16x32_bf16 v[48:51], v[128:131], v[176:179], v[48:51]
	v_mfma_f32_16x16x32_bf16 v[44:47], v[144:147], v[176:179], v[44:47]
	v_mfma_f32_16x16x32_bf16 v[32:35], v[128:131], v[184:187], v[32:35]
	v_mfma_f32_16x16x32_bf16 v[28:31], v[144:147], v[184:187], v[28:31]
	v_mfma_f32_16x16x32_bf16 v[16:19], v[128:131], v[192:195], v[16:19]
	v_mfma_f32_16x16x32_bf16 v[12:15], v[144:147], v[192:195], v[12:15]
	s_setprio 0
	s_setprio 1
	v_mfma_f32_16x16x32_bf16 v[56:59], v[148:151], v[164:167], v[56:59]
	v_mfma_f32_16x16x32_bf16 v[52:55], v[156:159], v[164:167], v[52:55]
	v_mfma_f32_16x16x32_bf16 v[40:43], v[148:151], v[172:175], v[40:43]
	v_mfma_f32_16x16x32_bf16 v[36:39], v[156:159], v[172:175], v[36:39]
	v_mfma_f32_16x16x32_bf16 v[24:27], v[148:151], v[180:183], v[24:27]
	v_mfma_f32_16x16x32_bf16 v[20:23], v[156:159], v[180:183], v[20:23]
	v_mfma_f32_16x16x32_bf16 v[8:11], v[148:151], v[188:191], v[8:11]
	v_mfma_f32_16x16x32_bf16 v[4:7], v[156:159], v[188:191], v[4:7]
	v_mfma_f32_16x16x32_bf16 v[56:59], v[152:155], v[168:171], v[56:59]
	v_mfma_f32_16x16x32_bf16 v[52:55], v[160:163], v[168:171], v[52:55]
	v_mfma_f32_16x16x32_bf16 v[40:43], v[152:155], v[176:179], v[40:43]
	v_mfma_f32_16x16x32_bf16 v[36:39], v[160:163], v[176:179], v[36:39]
	v_mfma_f32_16x16x32_bf16 v[24:27], v[152:155], v[184:187], v[24:27]
	v_mfma_f32_16x16x32_bf16 v[20:23], v[160:163], v[184:187], v[20:23]
	v_mfma_f32_16x16x32_bf16 v[8:11], v[152:155], v[192:195], v[8:11]
	v_mfma_f32_16x16x32_bf16 v[4:7], v[160:163], v[192:195], v[4:7]
	s_barrier
	s_setprio 0
	s_add_i32 s14, 0, 0x18000
	s_add_i32 s15, 0, 0x1c000
	v_add_u32_e32 v144, s14, v230
	v_add_u32_e32 v160, s15, v230
	ds_read_b128 v[124:127], v144
	ds_read_b128 v[128:131], v144 offset:1024
	ds_read_b128 v[136:139], v144 offset:2048
	ds_read_b128 v[144:147], v144 offset:3072
	ds_read_b128 v[148:151], v160
	ds_read_b128 v[152:155], v160 offset:1024
	ds_read_b128 v[156:159], v160 offset:2048
	ds_read_b128 v[160:163], v160 offset:3072
	s_add_u32 s12, s62, 0x80000
	s_addc_u32 s13, s63, 0
	s_mov_b32 m0, s84
	v_lshl_add_u64 v[204:205], s[12:13], 0, v[0:1]
	ds_read_b128 v[164:167], v243 offset:32768
	ds_read_b128 v[168:171], v243 offset:33792
	ds_read_b128 v[172:175], v243 offset:34816
	ds_read_b128 v[176:179], v243 offset:35840
	ds_read_b128 v[180:183], v243 offset:36864
	ds_read_b128 v[184:187], v243 offset:37888
	ds_read_b128 v[188:191], v243 offset:38912
	ds_read_b128 v[192:195], v243 offset:39936
	global_load_lds_dwordx4 v[204:205], off
	v_lshl_add_u64 v[204:205], s[12:13], 0, v[216:217]
	s_mov_b32 m0, s85
	s_nop 0
	global_load_lds_dwordx4 v[204:205], off
	s_waitcnt vmcnt(8)
	s_waitcnt lgkmcnt(0)
	s_setprio 1
	s_barrier
	v_mfma_f32_16x16x32_bf16 v[140:143], v[124:127], v[164:167], v[140:143]
	v_mfma_f32_16x16x32_bf16 v[132:135], v[136:139], v[164:167], v[132:135]
	v_mfma_f32_16x16x32_bf16 v[112:115], v[124:127], v[172:175], v[112:115]
	v_mfma_f32_16x16x32_bf16 v[108:111], v[136:139], v[172:175], v[108:111]
	v_mfma_f32_16x16x32_bf16 v[96:99], v[124:127], v[180:183], v[96:99]
	v_mfma_f32_16x16x32_bf16 v[92:95], v[136:139], v[180:183], v[92:95]
	v_mfma_f32_16x16x32_bf16 v[80:83], v[124:127], v[188:191], v[80:83]
	v_mfma_f32_16x16x32_bf16 v[76:79], v[136:139], v[188:191], v[76:79]
	v_mfma_f32_16x16x32_bf16 v[140:143], v[128:131], v[168:171], v[140:143]
	v_mfma_f32_16x16x32_bf16 v[132:135], v[144:147], v[168:171], v[132:135]
	v_mfma_f32_16x16x32_bf16 v[112:115], v[128:131], v[176:179], v[112:115]
	v_mfma_f32_16x16x32_bf16 v[108:111], v[144:147], v[176:179], v[108:111]
	v_mfma_f32_16x16x32_bf16 v[96:99], v[128:131], v[184:187], v[96:99]
	v_mfma_f32_16x16x32_bf16 v[92:95], v[144:147], v[184:187], v[92:95]
	v_mfma_f32_16x16x32_bf16 v[80:83], v[128:131], v[192:195], v[80:83]
	v_mfma_f32_16x16x32_bf16 v[76:79], v[144:147], v[192:195], v[76:79]
	s_setprio 0
	s_setprio 1
	v_mfma_f32_16x16x32_bf16 v[120:123], v[148:151], v[164:167], v[120:123]
	v_mfma_f32_16x16x32_bf16 v[116:119], v[156:159], v[164:167], v[116:119]
	v_mfma_f32_16x16x32_bf16 v[104:107], v[148:151], v[172:175], v[104:107]
	v_mfma_f32_16x16x32_bf16 v[100:103], v[156:159], v[172:175], v[100:103]
	v_mfma_f32_16x16x32_bf16 v[88:91], v[148:151], v[180:183], v[88:91]
	v_mfma_f32_16x16x32_bf16 v[84:87], v[156:159], v[180:183], v[84:87]
	v_mfma_f32_16x16x32_bf16 v[72:75], v[148:151], v[188:191], v[72:75]
	v_mfma_f32_16x16x32_bf16 v[68:71], v[156:159], v[188:191], v[68:71]
	v_mfma_f32_16x16x32_bf16 v[120:123], v[152:155], v[168:171], v[120:123]
	v_mfma_f32_16x16x32_bf16 v[116:119], v[160:163], v[168:171], v[116:119]
	v_mfma_f32_16x16x32_bf16 v[104:107], v[152:155], v[176:179], v[104:107]
	v_mfma_f32_16x16x32_bf16 v[100:103], v[160:163], v[176:179], v[100:103]
	v_mfma_f32_16x16x32_bf16 v[88:91], v[152:155], v[184:187], v[88:91]
	v_mfma_f32_16x16x32_bf16 v[84:87], v[160:163], v[184:187], v[84:87]
	v_mfma_f32_16x16x32_bf16 v[72:75], v[152:155], v[192:195], v[72:75]
	v_mfma_f32_16x16x32_bf16 v[68:71], v[160:163], v[192:195], v[68:71]
	s_barrier
	s_setprio 0
	s_add_i32 s12, s14, s82
	v_lshl_add_u64 v[196:197], v[196:197], 0, s[68:69]
	s_mov_b32 m0, s12
	ds_read_b128 v[164:167], v243 offset:49152
	ds_read_b128 v[168:171], v243 offset:50176
	ds_read_b128 v[172:175], v243 offset:51200
	ds_read_b128 v[176:179], v243 offset:52224
	ds_read_b128 v[180:183], v243 offset:53248
	ds_read_b128 v[184:187], v243 offset:54272
	ds_read_b128 v[188:191], v243 offset:55296
	ds_read_b128 v[192:195], v243 offset:56320
	global_load_lds_dwordx4 v[196:197], off
	s_add_i32 m0, s12, 0x2000
	s_add_u32 s12, s38, 0x80080
	v_lshl_add_u64 v[196:197], v[198:199], 0, s[68:69]
	s_addc_u32 s13, s39, 0
	s_add_i32 s14, s15, s82
	global_load_lds_dwordx4 v[196:197], off
	v_lshl_add_u64 v[196:197], s[12:13], 0, v[2:3]
	s_mov_b32 m0, s14
	s_nop 0
	global_load_lds_dwordx4 v[196:197], off
	v_lshl_add_u64 v[196:197], s[12:13], 0, v[218:219]
	s_add_i32 m0, s14, 0x2000
	s_nop 0
	global_load_lds_dwordx4 v[196:197], off
	v_lshl_add_u64 v[196:197], v[200:201], 0, s[68:69]
	s_mov_b32 m0, s89
	s_nop 0
	global_load_lds_dwordx4 v[196:197], off
	v_lshl_add_u64 v[196:197], v[202:203], 0, s[68:69]
	s_mov_b32 m0, s90
	s_nop 0
	global_load_lds_dwordx4 v[196:197], off
	s_waitcnt vmcnt(8)
	s_waitcnt lgkmcnt(0)
	s_setprio 1
	s_barrier
	v_mfma_f32_16x16x32_bf16 v[64:67], v[124:127], v[164:167], v[64:67]
	v_mfma_f32_16x16x32_bf16 v[60:63], v[136:139], v[164:167], v[60:63]
	v_mfma_f32_16x16x32_bf16 v[48:51], v[124:127], v[172:175], v[48:51]
	v_mfma_f32_16x16x32_bf16 v[44:47], v[136:139], v[172:175], v[44:47]
	v_mfma_f32_16x16x32_bf16 v[32:35], v[124:127], v[180:183], v[32:35]
	v_mfma_f32_16x16x32_bf16 v[28:31], v[136:139], v[180:183], v[28:31]
	v_mfma_f32_16x16x32_bf16 v[16:19], v[124:127], v[188:191], v[16:19]
	v_mfma_f32_16x16x32_bf16 v[12:15], v[136:139], v[188:191], v[12:15]
	v_mfma_f32_16x16x32_bf16 v[64:67], v[128:131], v[168:171], v[64:67]
	v_mfma_f32_16x16x32_bf16 v[60:63], v[144:147], v[168:171], v[60:63]
	v_mfma_f32_16x16x32_bf16 v[48:51], v[128:131], v[176:179], v[48:51]
	v_mfma_f32_16x16x32_bf16 v[44:47], v[144:147], v[176:179], v[44:47]
	v_mfma_f32_16x16x32_bf16 v[32:35], v[128:131], v[184:187], v[32:35]
	v_mfma_f32_16x16x32_bf16 v[28:31], v[144:147], v[184:187], v[28:31]
	v_mfma_f32_16x16x32_bf16 v[16:19], v[128:131], v[192:195], v[16:19]
	v_mfma_f32_16x16x32_bf16 v[12:15], v[144:147], v[192:195], v[12:15]
	s_setprio 0
	s_setprio 1
	v_mfma_f32_16x16x32_bf16 v[56:59], v[148:151], v[164:167], v[56:59]
	v_mfma_f32_16x16x32_bf16 v[52:55], v[156:159], v[164:167], v[52:55]
	v_mfma_f32_16x16x32_bf16 v[40:43], v[148:151], v[172:175], v[40:43]
	v_mfma_f32_16x16x32_bf16 v[36:39], v[156:159], v[172:175], v[36:39]
	v_mfma_f32_16x16x32_bf16 v[24:27], v[148:151], v[180:183], v[24:27]
	v_mfma_f32_16x16x32_bf16 v[20:23], v[156:159], v[180:183], v[20:23]
	v_mfma_f32_16x16x32_bf16 v[8:11], v[148:151], v[188:191], v[8:11]
	v_mfma_f32_16x16x32_bf16 v[4:7], v[156:159], v[188:191], v[4:7]
	v_mfma_f32_16x16x32_bf16 v[56:59], v[152:155], v[168:171], v[56:59]
	v_mfma_f32_16x16x32_bf16 v[52:55], v[160:163], v[168:171], v[52:55]
	v_mfma_f32_16x16x32_bf16 v[40:43], v[152:155], v[176:179], v[40:43]
	v_mfma_f32_16x16x32_bf16 v[36:39], v[160:163], v[176:179], v[36:39]
	v_mfma_f32_16x16x32_bf16 v[24:27], v[152:155], v[184:187], v[24:27]
	v_mfma_f32_16x16x32_bf16 v[20:23], v[160:163], v[184:187], v[20:23]
	v_mfma_f32_16x16x32_bf16 v[8:11], v[152:155], v[192:195], v[8:11]
	v_mfma_f32_16x16x32_bf16 v[4:7], v[160:163], v[192:195], v[4:7]
	s_barrier
	s_setprio 0
	s_add_i32 s11, s11, 2
	s_add_u32 s9, s9, 0x100
	s_addc_u32 s10, s10, 0
	s_add_u32 s36, s36, 0x100
	s_addc_u32 s37, s37, 0
	s_cmp_gt_u32 s11, 29
	s_cbranch_scc0 .LBB0_741
	s_and_b64 vcc, exec, s[46:47]
	s_cbranch_vccz .LBB0_744
	s_barrier

.LBB0_853:
	v_and_b32_e32 v203, 15, v16
	v_bfe_u32 v201, v16, 4, 2
	s_and_b32 s5, s5, 3
	v_lshlrev_b32_e32 v16, 4, v201
	v_lshlrev_b32_e32 v202, 2, v203
	v_lshl_or_b32 v16, v203, 6, v16
	v_and_b32_e32 v19, 32, v202
	s_lshl_b32 s14, s8, 13
	s_lshl_b32 s15, s5, 12
	s_add_i32 m0, s10, 0x18000
	v_lshl_add_u64 v[10:11], v[10:11], 0, s[68:69]
	v_bitop3_b32 v140, v16, s15, v19 bitop3:0xde
	v_bitop3_b32 v16, v16, s14, v19 bitop3:0xde
	s_nop 0
	global_load_lds_dwordx4 v[10:11], off
	v_lshl_add_u64 v[8:9], v[8:9], 0, s[68:69]
	s_add_i32 m0, s10, 0x1a000
	s_add_i32 s14, s10, 0x8000
	s_add_i32 s15, s10, 0xa000
	global_load_lds_dwordx4 v[8:9], off
	v_lshl_add_u64 v[6:7], v[6:7], 0, s[68:69]
	s_mov_b32 m0, s14
	s_add_u32 s16, s20, 0x80080
	global_load_lds_dwordx4 v[6:7], off
	v_lshl_add_u64 v[4:5], v[4:5], 0, s[68:69]
	s_mov_b32 m0, s15
	s_addc_u32 s17, s21, 0
	global_load_lds_dwordx4 v[4:5], off
	s_add_i32 m0, s10, 0x1c000
	v_lshl_add_u64 v[4:5], s[16:17], 0, v[2:3]
	global_load_lds_dwordx4 v[4:5], off
	v_lshl_add_u64 v[4:5], s[16:17], 0, v[134:135]
	s_add_i32 m0, s10, 0x1e000
	v_readlane_b32 s16, v254, 25
	global_load_lds_dwordx4 v[4:5], off
	v_readlane_b32 s17, v254, 26
	s_add_u32 s16, s16, s24
	s_addc_u32 s17, s17, s25
	s_add_u32 s16, s2, s16
	s_addc_u32 s17, s3, s17
	s_and_b32 s18, s18, 7
	s_lshl_b32 s18, s18, 23
	s_lshl_b32 s19, s19, 20
	v_lshlrev_b32_e32 v4, 15, v15
	s_or_b32 s18, s18, s19
	v_and_b32_e32 v4, 0xffff0000, v4
	s_add_u32 s18, s2, s18
	v_lshl_add_u32 v4, v17, 12, v4
	v_and_b32_e32 v5, 1, v15
	s_addc_u32 s19, s3, 0
	v_lshl_or_b32 v4, v5, 6, v4
	s_add_u32 s24, s18, 0x22180080
	v_lshl_add_u32 v4, v18, 1, v4
	v_mov_b32_e32 v5, v3
	s_addc_u32 s25, s19, 0
	v_lshl_add_u64 v[136:137], s[24:25], 0, v[4:5]
	v_lshlrev_b32_e32 v4, 15, v12
	v_and_b32_e32 v4, 0xffff0000, v4
	v_lshl_add_u32 v4, v13, 12, v4
	v_and_b32_e32 v5, 1, v12
	v_lshl_or_b32 v4, v5, 6, v4
	s_waitcnt vmcnt(8)
	s_barrier
	s_waitcnt vmcnt(6)
	v_lshl_add_u32 v4, v14, 1, v4
	v_mov_b32_e32 v5, v3
	v_lshl_add_u64 v[138:139], s[24:25], 0, v[4:5]
	v_lshl_or_b32 v200, s8, 6, v203
	s_mov_b32 s28, -2
	s_mov_b64 s[24:25], 0
	v_add_u32_e32 v141, 0, v16
	s_barrier
	s_add_u32 s26, s18, s24
	s_addc_u32 s27, s19, s25
	s_add_u32 s26, s26, 0x22100100
	s_addc_u32 s27, s27, 0
	s_add_u32 s29, s16, s24
	s_addc_u32 s30, s17, s25
	s_add_i32 s31, 0, 0x10000
	s_cmpk_eq_i32 s24, 0xf00
	s_cselect_b32 s37, s23, s27
	s_cselect_b32 s36, s22, s26
	s_cselect_b32 s27, s21, s30
	s_cselect_b32 s26, s20, s29
	s_add_i32 s29, 0, 0x14000
	v_add_u32_e32 v154, s31, v140
	v_add_u32_e32 v170, s29, v140
	ds_read_b128 v[142:145], v154
	ds_read_b128 v[146:149], v154 offset:1024
	ds_read_b128 v[150:153], v154 offset:2048
	ds_read_b128 v[154:157], v154 offset:3072
	ds_read_b128 v[158:161], v170
	ds_read_b128 v[162:165], v170 offset:1024
	ds_read_b128 v[166:169], v170 offset:2048
	ds_read_b128 v[170:173], v170 offset:3072
	v_lshl_add_u64 v[198:199], v[138:139], 0, s[24:25]
	s_add_i32 m0, s10, 0xc000
	ds_read_b128 v[174:177], v141
	ds_read_b128 v[178:181], v141 offset:1024
	ds_read_b128 v[182:185], v141 offset:2048
	ds_read_b128 v[186:189], v141 offset:3072
	ds_read_b128 v[190:193], v141 offset:4096
	ds_read_b128 v[194:197], v141 offset:5120
	ds_read_b128 v[204:207], v141 offset:6144
	ds_read_b128 v[208:211], v141 offset:7168
	global_load_lds_dwordx4 v[198:199], off
	v_lshl_add_u64 v[198:199], v[136:137], 0, s[24:25]
	s_add_i32 m0, s10, 0xe000
	s_nop 0
	global_load_lds_dwordx4 v[198:199], off
	s_waitcnt vmcnt(8)
	s_waitcnt lgkmcnt(0)
	s_setprio 1
	s_barrier
	v_mfma_f32_16x16x32_bf16 v[128:131], v[142:145], v[174:177], 0
	v_mfma_f32_16x16x32_bf16 v[124:127], v[150:153], v[174:177], 0
	v_mfma_f32_16x16x32_bf16 v[112:115], v[142:145], v[182:185], 0
	v_mfma_f32_16x16x32_bf16 v[108:111], v[150:153], v[182:185], 0
	v_mfma_f32_16x16x32_bf16 v[96:99], v[142:145], v[190:193], 0
	v_mfma_f32_16x16x32_bf16 v[92:95], v[150:153], v[190:193], 0
	v_mfma_f32_16x16x32_bf16 v[80:83], v[142:145], v[204:207], 0
	v_mfma_f32_16x16x32_bf16 v[76:79], v[150:153], v[204:207], 0
	v_mfma_f32_16x16x32_bf16 v[128:131], v[146:149], v[178:181], v[128:131]
	v_mfma_f32_16x16x32_bf16 v[124:127], v[154:157], v[178:181], v[124:127]
	v_mfma_f32_16x16x32_bf16 v[112:115], v[146:149], v[186:189], v[112:115]
	v_mfma_f32_16x16x32_bf16 v[108:111], v[154:157], v[186:189], v[108:111]
	v_mfma_f32_16x16x32_bf16 v[96:99], v[146:149], v[194:197], v[96:99]
	v_mfma_f32_16x16x32_bf16 v[92:95], v[154:157], v[194:197], v[92:95]
	v_mfma_f32_16x16x32_bf16 v[80:83], v[146:149], v[208:211], v[80:83]
	v_mfma_f32_16x16x32_bf16 v[76:79], v[154:157], v[208:211], v[76:79]
	s_setprio 0
	s_setprio 1
	v_mfma_f32_16x16x32_bf16 v[120:123], v[158:161], v[174:177], 0
	v_mfma_f32_16x16x32_bf16 v[116:119], v[166:169], v[174:177], 0
	v_mfma_f32_16x16x32_bf16 v[104:107], v[158:161], v[182:185], 0
	v_mfma_f32_16x16x32_bf16 v[100:103], v[166:169], v[182:185], 0
	v_mfma_f32_16x16x32_bf16 v[88:91], v[158:161], v[190:193], 0
	v_mfma_f32_16x16x32_bf16 v[84:87], v[166:169], v[190:193], 0
	v_mfma_f32_16x16x32_bf16 v[72:75], v[158:161], v[204:207], 0
	v_mfma_f32_16x16x32_bf16 v[68:71], v[166:169], v[204:207], 0
	v_mfma_f32_16x16x32_bf16 v[120:123], v[162:165], v[178:181], v[120:123]
	v_mfma_f32_16x16x32_bf16 v[116:119], v[170:173], v[178:181], v[116:119]
	v_mfma_f32_16x16x32_bf16 v[104:107], v[162:165], v[186:189], v[104:107]
	v_mfma_f32_16x16x32_bf16 v[100:103], v[170:173], v[186:189], v[100:103]
	v_mfma_f32_16x16x32_bf16 v[88:91], v[162:165], v[194:197], v[88:91]
	v_mfma_f32_16x16x32_bf16 v[84:87], v[170:173], v[194:197], v[84:87]
	v_mfma_f32_16x16x32_bf16 v[72:75], v[162:165], v[208:211], v[72:75]
	v_mfma_f32_16x16x32_bf16 v[68:71], v[170:173], v[208:211], v[68:71]
	s_barrier
	s_setprio 0
	s_add_i32 s30, s31, s9
	v_lshl_add_u64 v[198:199], s[26:27], 0, v[2:3]
	s_mov_b32 m0, s30
	ds_read_b128 v[174:177], v141 offset:16384
	ds_read_b128 v[178:181], v141 offset:17408
	ds_read_b128 v[182:185], v141 offset:18432
	ds_read_b128 v[186:189], v141 offset:19456
	ds_read_b128 v[190:193], v141 offset:20480
	ds_read_b128 v[194:197], v141 offset:21504
	ds_read_b128 v[204:207], v141 offset:22528
	ds_read_b128 v[208:211], v141 offset:23552
	global_load_lds_dwordx4 v[198:199], off
	s_add_i32 m0, s30, 0x2000
	s_add_u32 s30, s26, 0x80000
	v_lshl_add_u64 v[212:213], s[26:27], 0, v[134:135]
	s_addc_u32 s31, s27, 0
	s_add_i32 s29, s29, s9
	global_load_lds_dwordx4 v[212:213], off
	v_lshl_add_u64 v[214:215], s[30:31], 0, v[2:3]
	s_mov_b32 m0, s29
	v_lshl_add_u64 v[216:217], s[36:37], 0, v[132:133]
	global_load_lds_dwordx4 v[214:215], off
	v_lshl_add_u64 v[214:215], s[30:31], 0, v[134:135]
	s_add_i32 m0, s29, 0x2000
	s_nop 0
	global_load_lds_dwordx4 v[214:215], off
	v_lshl_add_u64 v[214:215], s[36:37], 0, v[0:1]
	s_mov_b32 m0, s10
	s_nop 0
	global_load_lds_dwordx4 v[214:215], off
	s_mov_b32 m0, s11
	s_nop 0
	global_load_lds_dwordx4 v[216:217], off
	s_waitcnt vmcnt(8)
	s_waitcnt lgkmcnt(0)
	s_setprio 1
	s_barrier
	v_mfma_f32_16x16x32_bf16 v[64:67], v[142:145], v[174:177], 0
	v_mfma_f32_16x16x32_bf16 v[60:63], v[150:153], v[174:177], 0
	v_mfma_f32_16x16x32_bf16 v[48:51], v[142:145], v[182:185], 0
	v_mfma_f32_16x16x32_bf16 v[44:47], v[150:153], v[182:185], 0
	v_mfma_f32_16x16x32_bf16 v[32:35], v[142:145], v[190:193], 0
	v_mfma_f32_16x16x32_bf16 v[28:31], v[150:153], v[190:193], 0
	v_mfma_f32_16x16x32_bf16 v[16:19], v[142:145], v[204:207], 0
	v_mfma_f32_16x16x32_bf16 v[12:15], v[150:153], v[204:207], 0
	v_mfma_f32_16x16x32_bf16 v[64:67], v[146:149], v[178:181], v[64:67]
	v_mfma_f32_16x16x32_bf16 v[60:63], v[154:157], v[178:181], v[60:63]
	v_mfma_f32_16x16x32_bf16 v[48:51], v[146:149], v[186:189], v[48:51]
	v_mfma_f32_16x16x32_bf16 v[44:47], v[154:157], v[186:189], v[44:47]
	v_mfma_f32_16x16x32_bf16 v[32:35], v[146:149], v[194:197], v[32:35]
	v_mfma_f32_16x16x32_bf16 v[28:31], v[154:157], v[194:197], v[28:31]
	v_mfma_f32_16x16x32_bf16 v[16:19], v[146:149], v[208:211], v[16:19]
	v_mfma_f32_16x16x32_bf16 v[12:15], v[154:157], v[208:211], v[12:15]
	s_setprio 0
	s_setprio 1
	v_mfma_f32_16x16x32_bf16 v[56:59], v[158:161], v[174:177], 0
	v_mfma_f32_16x16x32_bf16 v[52:55], v[166:169], v[174:177], 0
	v_mfma_f32_16x16x32_bf16 v[40:43], v[158:161], v[182:185], 0
	v_mfma_f32_16x16x32_bf16 v[36:39], v[166:169], v[182:185], 0
	v_mfma_f32_16x16x32_bf16 v[24:27], v[158:161], v[190:193], 0
	v_mfma_f32_16x16x32_bf16 v[20:23], v[166:169], v[190:193], 0
	v_mfma_f32_16x16x32_bf16 v[8:11], v[158:161], v[204:207], 0
	v_mfma_f32_16x16x32_bf16 v[4:7], v[166:169], v[204:207], 0
	v_mfma_f32_16x16x32_bf16 v[56:59], v[162:165], v[178:181], v[56:59]
	v_mfma_f32_16x16x32_bf16 v[52:55], v[170:173], v[178:181], v[52:55]
	v_mfma_f32_16x16x32_bf16 v[40:43], v[162:165], v[186:189], v[40:43]
	v_mfma_f32_16x16x32_bf16 v[36:39], v[170:173], v[186:189], v[36:39]
	v_mfma_f32_16x16x32_bf16 v[24:27], v[162:165], v[194:197], v[24:27]
	v_mfma_f32_16x16x32_bf16 v[20:23], v[170:173], v[194:197], v[20:23]
	v_mfma_f32_16x16x32_bf16 v[8:11], v[162:165], v[208:211], v[8:11]
	v_mfma_f32_16x16x32_bf16 v[4:7], v[170:173], v[208:211], v[4:7]
	s_barrier
	s_setprio 0
	s_add_i32 s29, 0, 0x18000
	s_add_i32 s33, 0, 0x1c000
	v_add_u32_e32 v154, s29, v140
	v_add_u32_e32 v170, s33, v140
	ds_read_b128 v[142:145], v154
	ds_read_b128 v[146:149], v154 offset:1024
	ds_read_b128 v[150:153], v154 offset:2048
	ds_read_b128 v[154:157], v154 offset:3072
	ds_read_b128 v[158:161], v170
	ds_read_b128 v[162:165], v170 offset:1024
	ds_read_b128 v[166:169], v170 offset:2048
	ds_read_b128 v[170:173], v170 offset:3072
	s_add_u32 s30, s36, 0x80000
	s_addc_u32 s31, s37, 0
	s_mov_b32 m0, s12
	v_lshl_add_u64 v[218:219], s[30:31], 0, v[0:1]
	ds_read_b128 v[174:177], v141 offset:32768
	ds_read_b128 v[178:181], v141 offset:33792
	ds_read_b128 v[182:185], v141 offset:34816
	ds_read_b128 v[186:189], v141 offset:35840
	ds_read_b128 v[190:193], v141 offset:36864
	ds_read_b128 v[194:197], v141 offset:37888
	ds_read_b128 v[204:207], v141 offset:38912
	ds_read_b128 v[208:211], v141 offset:39936
	global_load_lds_dwordx4 v[218:219], off
	v_lshl_add_u64 v[218:219], s[30:31], 0, v[132:133]
	s_mov_b32 m0, s13
	s_nop 0
	global_load_lds_dwordx4 v[218:219], off
	s_waitcnt vmcnt(8)
	s_waitcnt lgkmcnt(0)
	s_setprio 1
	s_barrier
	v_mfma_f32_16x16x32_bf16 v[128:131], v[142:145], v[174:177], v[128:131]
	v_mfma_f32_16x16x32_bf16 v[124:127], v[150:153], v[174:177], v[124:127]
	v_mfma_f32_16x16x32_bf16 v[112:115], v[142:145], v[182:185], v[112:115]
	v_mfma_f32_16x16x32_bf16 v[108:111], v[150:153], v[182:185], v[108:111]
	v_mfma_f32_16x16x32_bf16 v[96:99], v[142:145], v[190:193], v[96:99]
	v_mfma_f32_16x16x32_bf16 v[92:95], v[150:153], v[190:193], v[92:95]
	v_mfma_f32_16x16x32_bf16 v[80:83], v[142:145], v[204:207], v[80:83]
	v_mfma_f32_16x16x32_bf16 v[76:79], v[150:153], v[204:207], v[76:79]
	v_mfma_f32_16x16x32_bf16 v[128:131], v[146:149], v[178:181], v[128:131]
	v_mfma_f32_16x16x32_bf16 v[124:127], v[154:157], v[178:181], v[124:127]
	v_mfma_f32_16x16x32_bf16 v[112:115], v[146:149], v[186:189], v[112:115]
	v_mfma_f32_16x16x32_bf16 v[108:111], v[154:157], v[186:189], v[108:111]
	v_mfma_f32_16x16x32_bf16 v[96:99], v[146:149], v[194:197], v[96:99]
	v_mfma_f32_16x16x32_bf16 v[92:95], v[154:157], v[194:197], v[92:95]
	v_mfma_f32_16x16x32_bf16 v[80:83], v[146:149], v[208:211], v[80:83]
	v_mfma_f32_16x16x32_bf16 v[76:79], v[154:157], v[208:211], v[76:79]
	s_setprio 0
	s_setprio 1
	v_mfma_f32_16x16x32_bf16 v[120:123], v[158:161], v[174:177], v[120:123]
	v_mfma_f32_16x16x32_bf16 v[116:119], v[166:169], v[174:177], v[116:119]
	v_mfma_f32_16x16x32_bf16 v[104:107], v[158:161], v[182:185], v[104:107]
	v_mfma_f32_16x16x32_bf16 v[100:103], v[166:169], v[182:185], v[100:103]
	v_mfma_f32_16x16x32_bf16 v[88:91], v[158:161], v[190:193], v[88:91]
	v_mfma_f32_16x16x32_bf16 v[84:87], v[166:169], v[190:193], v[84:87]
	v_mfma_f32_16x16x32_bf16 v[72:75], v[158:161], v[204:207], v[72:75]
	v_mfma_f32_16x16x32_bf16 v[68:71], v[166:169], v[204:207], v[68:71]
	v_mfma_f32_16x16x32_bf16 v[120:123], v[162:165], v[178:181], v[120:123]
	v_mfma_f32_16x16x32_bf16 v[116:119], v[170:173], v[178:181], v[116:119]
	v_mfma_f32_16x16x32_bf16 v[104:107], v[162:165], v[186:189], v[104:107]
	v_mfma_f32_16x16x32_bf16 v[100:103], v[170:173], v[186:189], v[100:103]
	v_mfma_f32_16x16x32_bf16 v[88:91], v[162:165], v[194:197], v[88:91]
	v_mfma_f32_16x16x32_bf16 v[84:87], v[170:173], v[194:197], v[84:87]
	v_mfma_f32_16x16x32_bf16 v[72:75], v[162:165], v[208:211], v[72:75]
	v_mfma_f32_16x16x32_bf16 v[68:71], v[170:173], v[208:211], v[68:71]
	s_barrier
	s_setprio 0
	s_add_i32 s29, s29, s9
	v_lshl_add_u64 v[198:199], v[198:199], 0, s[68:69]
	s_mov_b32 m0, s29
	ds_read_b128 v[174:177], v141 offset:49152
	ds_read_b128 v[178:181], v141 offset:50176
	ds_read_b128 v[182:185], v141 offset:51200
	ds_read_b128 v[186:189], v141 offset:52224
	ds_read_b128 v[190:193], v141 offset:53248
	ds_read_b128 v[194:197], v141 offset:54272
	ds_read_b128 v[204:207], v141 offset:55296
	ds_read_b128 v[208:211], v141 offset:56320
	global_load_lds_dwordx4 v[198:199], off
	s_add_i32 m0, s29, 0x2000
	s_add_u32 s26, s26, 0x80080
	v_lshl_add_u64 v[198:199], v[212:213], 0, s[68:69]
	s_addc_u32 s27, s27, 0
	s_add_i32 s29, s33, s9
	global_load_lds_dwordx4 v[198:199], off
	v_lshl_add_u64 v[198:199], s[26:27], 0, v[2:3]
	s_mov_b32 m0, s29
	s_nop 0
	global_load_lds_dwordx4 v[198:199], off
	v_lshl_add_u64 v[198:199], s[26:27], 0, v[134:135]
	s_add_i32 m0, s29, 0x2000
	s_nop 0
	global_load_lds_dwordx4 v[198:199], off
	v_lshl_add_u64 v[198:199], v[214:215], 0, s[68:69]
	s_mov_b32 m0, s14
	s_nop 0
	global_load_lds_dwordx4 v[198:199], off
	v_lshl_add_u64 v[198:199], v[216:217], 0, s[68:69]
	s_mov_b32 m0, s15
	s_nop 0
	global_load_lds_dwordx4 v[198:199], off
	s_waitcnt vmcnt(8)
	s_waitcnt lgkmcnt(0)
	s_setprio 1
	s_barrier
	v_mfma_f32_16x16x32_bf16 v[64:67], v[142:145], v[174:177], v[64:67]
	v_mfma_f32_16x16x32_bf16 v[60:63], v[150:153], v[174:177], v[60:63]
	v_mfma_f32_16x16x32_bf16 v[48:51], v[142:145], v[182:185], v[48:51]
	v_mfma_f32_16x16x32_bf16 v[44:47], v[150:153], v[182:185], v[44:47]
	v_mfma_f32_16x16x32_bf16 v[32:35], v[142:145], v[190:193], v[32:35]
	v_mfma_f32_16x16x32_bf16 v[28:31], v[150:153], v[190:193], v[28:31]
	v_mfma_f32_16x16x32_bf16 v[16:19], v[142:145], v[204:207], v[16:19]
	v_mfma_f32_16x16x32_bf16 v[12:15], v[150:153], v[204:207], v[12:15]
	v_mfma_f32_16x16x32_bf16 v[64:67], v[146:149], v[178:181], v[64:67]
	v_mfma_f32_16x16x32_bf16 v[60:63], v[154:157], v[178:181], v[60:63]
	v_mfma_f32_16x16x32_bf16 v[48:51], v[146:149], v[186:189], v[48:51]
	v_mfma_f32_16x16x32_bf16 v[44:47], v[154:157], v[186:189], v[44:47]
	v_mfma_f32_16x16x32_bf16 v[32:35], v[146:149], v[194:197], v[32:35]
	v_mfma_f32_16x16x32_bf16 v[28:31], v[154:157], v[194:197], v[28:31]
	v_mfma_f32_16x16x32_bf16 v[16:19], v[146:149], v[208:211], v[16:19]
	v_mfma_f32_16x16x32_bf16 v[12:15], v[154:157], v[208:211], v[12:15]
	s_setprio 0
	s_setprio 1
	v_mfma_f32_16x16x32_bf16 v[56:59], v[158:161], v[174:177], v[56:59]
	v_mfma_f32_16x16x32_bf16 v[52:55], v[166:169], v[174:177], v[52:55]
	v_mfma_f32_16x16x32_bf16 v[40:43], v[158:161], v[182:185], v[40:43]
	v_mfma_f32_16x16x32_bf16 v[36:39], v[166:169], v[182:185], v[36:39]
	v_mfma_f32_16x16x32_bf16 v[24:27], v[158:161], v[190:193], v[24:27]
	v_mfma_f32_16x16x32_bf16 v[20:23], v[166:169], v[190:193], v[20:23]
	v_mfma_f32_16x16x32_bf16 v[8:11], v[158:161], v[204:207], v[8:11]
	v_mfma_f32_16x16x32_bf16 v[4:7], v[166:169], v[204:207], v[4:7]
	v_mfma_f32_16x16x32_bf16 v[56:59], v[162:165], v[178:181], v[56:59]
	v_mfma_f32_16x16x32_bf16 v[52:55], v[170:173], v[178:181], v[52:55]
	v_mfma_f32_16x16x32_bf16 v[40:43], v[162:165], v[186:189], v[40:43]
	v_mfma_f32_16x16x32_bf16 v[36:39], v[170:173], v[186:189], v[36:39]
	v_mfma_f32_16x16x32_bf16 v[24:27], v[162:165], v[194:197], v[24:27]
	v_mfma_f32_16x16x32_bf16 v[20:23], v[170:173], v[194:197], v[20:23]
	v_mfma_f32_16x16x32_bf16 v[8:11], v[162:165], v[208:211], v[8:11]
	v_mfma_f32_16x16x32_bf16 v[4:7], v[170:173], v[208:211], v[4:7]
	s_barrier
	s_setprio 0
	s_add_i32 s28, s28, 2
	s_add_u32 s24, s24, 0x100
	s_addc_u32 s25, s25, 0
	s_cmp_lt_u32 s28, 30
.LBB0_854:
	s_add_u32 s26, s18, s24
	s_addc_u32 s27, s19, s25
	s_add_u32 s26, s26, 0x22100100
	s_addc_u32 s27, s27, 0
	s_add_u32 s29, s16, s24
	s_addc_u32 s30, s17, s25
	s_add_i32 s31, 0, 0x10000
	s_cmpk_eq_i32 s24, 0xf00
	s_cselect_b32 s37, s23, s27
	s_cselect_b32 s36, s22, s26
	s_cselect_b32 s27, s21, s30
	s_cselect_b32 s26, s20, s29
	s_add_i32 s29, 0, 0x14000
	v_add_u32_e32 v154, s31, v140
	v_add_u32_e32 v170, s29, v140
	ds_read_b128 v[142:145], v154
	ds_read_b128 v[146:149], v154 offset:1024
	ds_read_b128 v[150:153], v154 offset:2048
	ds_read_b128 v[154:157], v154 offset:3072
	ds_read_b128 v[158:161], v170
	ds_read_b128 v[162:165], v170 offset:1024
	ds_read_b128 v[166:169], v170 offset:2048
	ds_read_b128 v[170:173], v170 offset:3072
	v_lshl_add_u64 v[198:199], v[138:139], 0, s[24:25]
	s_add_i32 m0, s10, 0xc000
	ds_read_b128 v[174:177], v141
	ds_read_b128 v[178:181], v141 offset:1024
	ds_read_b128 v[182:185], v141 offset:2048
	ds_read_b128 v[186:189], v141 offset:3072
	ds_read_b128 v[190:193], v141 offset:4096
	ds_read_b128 v[194:197], v141 offset:5120
	ds_read_b128 v[204:207], v141 offset:6144
	ds_read_b128 v[208:211], v141 offset:7168
	global_load_lds_dwordx4 v[198:199], off
	v_lshl_add_u64 v[198:199], v[136:137], 0, s[24:25]
	s_add_i32 m0, s10, 0xe000
	s_nop 0
	global_load_lds_dwordx4 v[198:199], off
	s_waitcnt vmcnt(8)
	s_waitcnt lgkmcnt(0)
	s_setprio 1
	s_barrier
	v_mfma_f32_16x16x32_bf16 v[128:131], v[142:145], v[174:177], v[128:131]
	v_mfma_f32_16x16x32_bf16 v[124:127], v[150:153], v[174:177], v[124:127]
	v_mfma_f32_16x16x32_bf16 v[112:115], v[142:145], v[182:185], v[112:115]
	v_mfma_f32_16x16x32_bf16 v[108:111], v[150:153], v[182:185], v[108:111]
	v_mfma_f32_16x16x32_bf16 v[96:99], v[142:145], v[190:193], v[96:99]
	v_mfma_f32_16x16x32_bf16 v[92:95], v[150:153], v[190:193], v[92:95]
	v_mfma_f32_16x16x32_bf16 v[80:83], v[142:145], v[204:207], v[80:83]
	v_mfma_f32_16x16x32_bf16 v[76:79], v[150:153], v[204:207], v[76:79]
	v_mfma_f32_16x16x32_bf16 v[128:131], v[146:149], v[178:181], v[128:131]
	v_mfma_f32_16x16x32_bf16 v[124:127], v[154:157], v[178:181], v[124:127]
	v_mfma_f32_16x16x32_bf16 v[112:115], v[146:149], v[186:189], v[112:115]
	v_mfma_f32_16x16x32_bf16 v[108:111], v[154:157], v[186:189], v[108:111]
	v_mfma_f32_16x16x32_bf16 v[96:99], v[146:149], v[194:197], v[96:99]
	v_mfma_f32_16x16x32_bf16 v[92:95], v[154:157], v[194:197], v[92:95]
	v_mfma_f32_16x16x32_bf16 v[80:83], v[146:149], v[208:211], v[80:83]
	v_mfma_f32_16x16x32_bf16 v[76:79], v[154:157], v[208:211], v[76:79]
	s_setprio 0
	s_setprio 1
	v_mfma_f32_16x16x32_bf16 v[120:123], v[158:161], v[174:177], v[120:123]
	v_mfma_f32_16x16x32_bf16 v[116:119], v[166:169], v[174:177], v[116:119]
	v_mfma_f32_16x16x32_bf16 v[104:107], v[158:161], v[182:185], v[104:107]
	v_mfma_f32_16x16x32_bf16 v[100:103], v[166:169], v[182:185], v[100:103]
	v_mfma_f32_16x16x32_bf16 v[88:91], v[158:161], v[190:193], v[88:91]
	v_mfma_f32_16x16x32_bf16 v[84:87], v[166:169], v[190:193], v[84:87]
	v_mfma_f32_16x16x32_bf16 v[72:75], v[158:161], v[204:207], v[72:75]
	v_mfma_f32_16x16x32_bf16 v[68:71], v[166:169], v[204:207], v[68:71]
	v_mfma_f32_16x16x32_bf16 v[120:123], v[162:165], v[178:181], v[120:123]
	v_mfma_f32_16x16x32_bf16 v[116:119], v[170:173], v[178:181], v[116:119]
	v_mfma_f32_16x16x32_bf16 v[104:107], v[162:165], v[186:189], v[104:107]
	v_mfma_f32_16x16x32_bf16 v[100:103], v[170:173], v[186:189], v[100:103]
	v_mfma_f32_16x16x32_bf16 v[88:91], v[162:165], v[194:197], v[88:91]
	v_mfma_f32_16x16x32_bf16 v[84:87], v[170:173], v[194:197], v[84:87]
	v_mfma_f32_16x16x32_bf16 v[72:75], v[162:165], v[208:211], v[72:75]
	v_mfma_f32_16x16x32_bf16 v[68:71], v[170:173], v[208:211], v[68:71]
	s_barrier
	s_setprio 0
	s_add_i32 s30, s31, s9
	v_lshl_add_u64 v[198:199], s[26:27], 0, v[2:3]
	s_mov_b32 m0, s30
	ds_read_b128 v[174:177], v141 offset:16384
	ds_read_b128 v[178:181], v141 offset:17408
	ds_read_b128 v[182:185], v141 offset:18432
	ds_read_b128 v[186:189], v141 offset:19456
	ds_read_b128 v[190:193], v141 offset:20480
	ds_read_b128 v[194:197], v141 offset:21504
	ds_read_b128 v[204:207], v141 offset:22528
	ds_read_b128 v[208:211], v141 offset:23552
	global_load_lds_dwordx4 v[198:199], off
	s_add_i32 m0, s30, 0x2000
	s_add_u32 s30, s26, 0x80000
	v_lshl_add_u64 v[212:213], s[26:27], 0, v[134:135]
	s_addc_u32 s31, s27, 0
	s_add_i32 s29, s29, s9
	global_load_lds_dwordx4 v[212:213], off
	v_lshl_add_u64 v[214:215], s[30:31], 0, v[2:3]
	s_mov_b32 m0, s29
	v_lshl_add_u64 v[216:217], s[36:37], 0, v[132:133]
	global_load_lds_dwordx4 v[214:215], off
	v_lshl_add_u64 v[214:215], s[30:31], 0, v[134:135]
	s_add_i32 m0, s29, 0x2000
	s_nop 0
	global_load_lds_dwordx4 v[214:215], off
	v_lshl_add_u64 v[214:215], s[36:37], 0, v[0:1]
	s_mov_b32 m0, s10
	s_nop 0
	global_load_lds_dwordx4 v[214:215], off
	s_mov_b32 m0, s11
	s_nop 0
	global_load_lds_dwordx4 v[216:217], off
	s_waitcnt vmcnt(8)
	s_waitcnt lgkmcnt(0)
	s_setprio 1
	s_barrier
	v_mfma_f32_16x16x32_bf16 v[64:67], v[142:145], v[174:177], v[64:67]
	v_mfma_f32_16x16x32_bf16 v[60:63], v[150:153], v[174:177], v[60:63]
	v_mfma_f32_16x16x32_bf16 v[48:51], v[142:145], v[182:185], v[48:51]
	v_mfma_f32_16x16x32_bf16 v[44:47], v[150:153], v[182:185], v[44:47]
	v_mfma_f32_16x16x32_bf16 v[32:35], v[142:145], v[190:193], v[32:35]
	v_mfma_f32_16x16x32_bf16 v[28:31], v[150:153], v[190:193], v[28:31]
	v_mfma_f32_16x16x32_bf16 v[16:19], v[142:145], v[204:207], v[16:19]
	v_mfma_f32_16x16x32_bf16 v[12:15], v[150:153], v[204:207], v[12:15]
	v_mfma_f32_16x16x32_bf16 v[64:67], v[146:149], v[178:181], v[64:67]
	v_mfma_f32_16x16x32_bf16 v[60:63], v[154:157], v[178:181], v[60:63]
	v_mfma_f32_16x16x32_bf16 v[48:51], v[146:149], v[186:189], v[48:51]
	v_mfma_f32_16x16x32_bf16 v[44:47], v[154:157], v[186:189], v[44:47]
	v_mfma_f32_16x16x32_bf16 v[32:35], v[146:149], v[194:197], v[32:35]
	v_mfma_f32_16x16x32_bf16 v[28:31], v[154:157], v[194:197], v[28:31]
	v_mfma_f32_16x16x32_bf16 v[16:19], v[146:149], v[208:211], v[16:19]
	v_mfma_f32_16x16x32_bf16 v[12:15], v[154:157], v[208:211], v[12:15]
	s_setprio 0
	s_setprio 1
	v_mfma_f32_16x16x32_bf16 v[56:59], v[158:161], v[174:177], v[56:59]
	v_mfma_f32_16x16x32_bf16 v[52:55], v[166:169], v[174:177], v[52:55]
	v_mfma_f32_16x16x32_bf16 v[40:43], v[158:161], v[182:185], v[40:43]
	v_mfma_f32_16x16x32_bf16 v[36:39], v[166:169], v[182:185], v[36:39]
	v_mfma_f32_16x16x32_bf16 v[24:27], v[158:161], v[190:193], v[24:27]
	v_mfma_f32_16x16x32_bf16 v[20:23], v[166:169], v[190:193], v[20:23]
	v_mfma_f32_16x16x32_bf16 v[8:11], v[158:161], v[204:207], v[8:11]
	v_mfma_f32_16x16x32_bf16 v[4:7], v[166:169], v[204:207], v[4:7]
	v_mfma_f32_16x16x32_bf16 v[56:59], v[162:165], v[178:181], v[56:59]
	v_mfma_f32_16x16x32_bf16 v[52:55], v[170:173], v[178:181], v[52:55]
	v_mfma_f32_16x16x32_bf16 v[40:43], v[162:165], v[186:189], v[40:43]
	v_mfma_f32_16x16x32_bf16 v[36:39], v[170:173], v[186:189], v[36:39]
	v_mfma_f32_16x16x32_bf16 v[24:27], v[162:165], v[194:197], v[24:27]
	v_mfma_f32_16x16x32_bf16 v[20:23], v[170:173], v[194:197], v[20:23]
	v_mfma_f32_16x16x32_bf16 v[8:11], v[162:165], v[208:211], v[8:11]
	v_mfma_f32_16x16x32_bf16 v[4:7], v[170:173], v[208:211], v[4:7]
	s_barrier
	s_setprio 0
	s_add_i32 s29, 0, 0x18000
	s_add_i32 s33, 0, 0x1c000
	v_add_u32_e32 v154, s29, v140
	v_add_u32_e32 v170, s33, v140
	ds_read_b128 v[142:145], v154
	ds_read_b128 v[146:149], v154 offset:1024
	ds_read_b128 v[150:153], v154 offset:2048
	ds_read_b128 v[154:157], v154 offset:3072
	ds_read_b128 v[158:161], v170
	ds_read_b128 v[162:165], v170 offset:1024
	ds_read_b128 v[166:169], v170 offset:2048
	ds_read_b128 v[170:173], v170 offset:3072
	s_add_u32 s30, s36, 0x80000
	s_addc_u32 s31, s37, 0
	s_mov_b32 m0, s12
	v_lshl_add_u64 v[218:219], s[30:31], 0, v[0:1]
	ds_read_b128 v[174:177], v141 offset:32768
	ds_read_b128 v[178:181], v141 offset:33792
	ds_read_b128 v[182:185], v141 offset:34816
	ds_read_b128 v[186:189], v141 offset:35840
	ds_read_b128 v[190:193], v141 offset:36864
	ds_read_b128 v[194:197], v141 offset:37888
	ds_read_b128 v[204:207], v141 offset:38912
	ds_read_b128 v[208:211], v141 offset:39936
	global_load_lds_dwordx4 v[218:219], off
	v_lshl_add_u64 v[218:219], s[30:31], 0, v[132:133]
	s_mov_b32 m0, s13
	s_nop 0
	global_load_lds_dwordx4 v[218:219], off
	s_waitcnt vmcnt(8)
	s_waitcnt lgkmcnt(0)
	s_setprio 1
	s_barrier
	v_mfma_f32_16x16x32_bf16 v[128:131], v[142:145], v[174:177], v[128:131]
	v_mfma_f32_16x16x32_bf16 v[124:127], v[150:153], v[174:177], v[124:127]
	v_mfma_f32_16x16x32_bf16 v[112:115], v[142:145], v[182:185], v[112:115]
	v_mfma_f32_16x16x32_bf16 v[108:111], v[150:153], v[182:185], v[108:111]
	v_mfma_f32_16x16x32_bf16 v[96:99], v[142:145], v[190:193], v[96:99]
	v_mfma_f32_16x16x32_bf16 v[92:95], v[150:153], v[190:193], v[92:95]
	v_mfma_f32_16x16x32_bf16 v[80:83], v[142:145], v[204:207], v[80:83]
	v_mfma_f32_16x16x32_bf16 v[76:79], v[150:153], v[204:207], v[76:79]
	v_mfma_f32_16x16x32_bf16 v[128:131], v[146:149], v[178:181], v[128:131]
	v_mfma_f32_16x16x32_bf16 v[124:127], v[154:157], v[178:181], v[124:127]
	v_mfma_f32_16x16x32_bf16 v[112:115], v[146:149], v[186:189], v[112:115]
	v_mfma_f32_16x16x32_bf16 v[108:111], v[154:157], v[186:189], v[108:111]
	v_mfma_f32_16x16x32_bf16 v[96:99], v[146:149], v[194:197], v[96:99]
	v_mfma_f32_16x16x32_bf16 v[92:95], v[154:157], v[194:197], v[92:95]
	v_mfma_f32_16x16x32_bf16 v[80:83], v[146:149], v[208:211], v[80:83]
	v_mfma_f32_16x16x32_bf16 v[76:79], v[154:157], v[208:211], v[76:79]
	s_setprio 0
	s_setprio 1
	v_mfma_f32_16x16x32_bf16 v[120:123], v[158:161], v[174:177], v[120:123]
	v_mfma_f32_16x16x32_bf16 v[116:119], v[166:169], v[174:177], v[116:119]
	v_mfma_f32_16x16x32_bf16 v[104:107], v[158:161], v[182:185], v[104:107]
	v_mfma_f32_16x16x32_bf16 v[100:103], v[166:169], v[182:185], v[100:103]
	v_mfma_f32_16x16x32_bf16 v[88:91], v[158:161], v[190:193], v[88:91]
	v_mfma_f32_16x16x32_bf16 v[84:87], v[166:169], v[190:193], v[84:87]
	v_mfma_f32_16x16x32_bf16 v[72:75], v[158:161], v[204:207], v[72:75]
	v_mfma_f32_16x16x32_bf16 v[68:71], v[166:169], v[204:207], v[68:71]
	v_mfma_f32_16x16x32_bf16 v[120:123], v[162:165], v[178:181], v[120:123]
	v_mfma_f32_16x16x32_bf16 v[116:119], v[170:173], v[178:181], v[116:119]
	v_mfma_f32_16x16x32_bf16 v[104:107], v[162:165], v[186:189], v[104:107]
	v_mfma_f32_16x16x32_bf16 v[100:103], v[170:173], v[186:189], v[100:103]
	v_mfma_f32_16x16x32_bf16 v[88:91], v[162:165], v[194:197], v[88:91]
	v_mfma_f32_16x16x32_bf16 v[84:87], v[170:173], v[194:197], v[84:87]
	v_mfma_f32_16x16x32_bf16 v[72:75], v[162:165], v[208:211], v[72:75]
	v_mfma_f32_16x16x32_bf16 v[68:71], v[170:173], v[208:211], v[68:71]
	s_barrier
	s_setprio 0
	s_add_i32 s29, s29, s9
	v_lshl_add_u64 v[198:199], v[198:199], 0, s[68:69]
	s_mov_b32 m0, s29
	ds_read_b128 v[174:177], v141 offset:49152
	ds_read_b128 v[178:181], v141 offset:50176
	ds_read_b128 v[182:185], v141 offset:51200
	ds_read_b128 v[186:189], v141 offset:52224
	ds_read_b128 v[190:193], v141 offset:53248
	ds_read_b128 v[194:197], v141 offset:54272
	ds_read_b128 v[204:207], v141 offset:55296
	ds_read_b128 v[208:211], v141 offset:56320
	global_load_lds_dwordx4 v[198:199], off
	s_add_i32 m0, s29, 0x2000
	s_add_u32 s26, s26, 0x80080
	v_lshl_add_u64 v[198:199], v[212:213], 0, s[68:69]
	s_addc_u32 s27, s27, 0
	s_add_i32 s29, s33, s9
	global_load_lds_dwordx4 v[198:199], off
	v_lshl_add_u64 v[198:199], s[26:27], 0, v[2:3]
	s_mov_b32 m0, s29
	s_nop 0
	global_load_lds_dwordx4 v[198:199], off
	v_lshl_add_u64 v[198:199], s[26:27], 0, v[134:135]
	s_add_i32 m0, s29, 0x2000
	s_nop 0
	global_load_lds_dwordx4 v[198:199], off
	v_lshl_add_u64 v[198:199], v[214:215], 0, s[68:69]
	s_mov_b32 m0, s14
	s_nop 0
	global_load_lds_dwordx4 v[198:199], off
	v_lshl_add_u64 v[198:199], v[216:217], 0, s[68:69]
	s_mov_b32 m0, s15
	s_nop 0
	global_load_lds_dwordx4 v[198:199], off
	s_waitcnt vmcnt(8)
	s_waitcnt lgkmcnt(0)
	s_setprio 1
	s_barrier
	v_mfma_f32_16x16x32_bf16 v[64:67], v[142:145], v[174:177], v[64:67]
	v_mfma_f32_16x16x32_bf16 v[60:63], v[150:153], v[174:177], v[60:63]
	v_mfma_f32_16x16x32_bf16 v[48:51], v[142:145], v[182:185], v[48:51]
	v_mfma_f32_16x16x32_bf16 v[44:47], v[150:153], v[182:185], v[44:47]
	v_mfma_f32_16x16x32_bf16 v[32:35], v[142:145], v[190:193], v[32:35]
	v_mfma_f32_16x16x32_bf16 v[28:31], v[150:153], v[190:193], v[28:31]
	v_mfma_f32_16x16x32_bf16 v[16:19], v[142:145], v[204:207], v[16:19]
	v_mfma_f32_16x16x32_bf16 v[12:15], v[150:153], v[204:207], v[12:15]
	v_mfma_f32_16x16x32_bf16 v[64:67], v[146:149], v[178:181], v[64:67]
	v_mfma_f32_16x16x32_bf16 v[60:63], v[154:157], v[178:181], v[60:63]
	v_mfma_f32_16x16x32_bf16 v[48:51], v[146:149], v[186:189], v[48:51]
	v_mfma_f32_16x16x32_bf16 v[44:47], v[154:157], v[186:189], v[44:47]
	v_mfma_f32_16x16x32_bf16 v[32:35], v[146:149], v[194:197], v[32:35]
	v_mfma_f32_16x16x32_bf16 v[28:31], v[154:157], v[194:197], v[28:31]
	v_mfma_f32_16x16x32_bf16 v[16:19], v[146:149], v[208:211], v[16:19]
	v_mfma_f32_16x16x32_bf16 v[12:15], v[154:157], v[208:211], v[12:15]
	s_setprio 0
	s_setprio 1
	v_mfma_f32_16x16x32_bf16 v[56:59], v[158:161], v[174:177], v[56:59]
	v_mfma_f32_16x16x32_bf16 v[52:55], v[166:169], v[174:177], v[52:55]
	v_mfma_f32_16x16x32_bf16 v[40:43], v[158:161], v[182:185], v[40:43]
	v_mfma_f32_16x16x32_bf16 v[36:39], v[166:169], v[182:185], v[36:39]
	v_mfma_f32_16x16x32_bf16 v[24:27], v[158:161], v[190:193], v[24:27]
	v_mfma_f32_16x16x32_bf16 v[20:23], v[166:169], v[190:193], v[20:23]
	v_mfma_f32_16x16x32_bf16 v[8:11], v[158:161], v[204:207], v[8:11]
	v_mfma_f32_16x16x32_bf16 v[4:7], v[166:169], v[204:207], v[4:7]
	v_mfma_f32_16x16x32_bf16 v[56:59], v[162:165], v[178:181], v[56:59]
	v_mfma_f32_16x16x32_bf16 v[52:55], v[170:173], v[178:181], v[52:55]
	v_mfma_f32_16x16x32_bf16 v[40:43], v[162:165], v[186:189], v[40:43]
	v_mfma_f32_16x16x32_bf16 v[36:39], v[170:173], v[186:189], v[36:39]
	v_mfma_f32_16x16x32_bf16 v[24:27], v[162:165], v[194:197], v[24:27]
	v_mfma_f32_16x16x32_bf16 v[20:23], v[170:173], v[194:197], v[20:23]
	v_mfma_f32_16x16x32_bf16 v[8:11], v[162:165], v[208:211], v[8:11]
	v_mfma_f32_16x16x32_bf16 v[4:7], v[170:173], v[208:211], v[4:7]
	s_barrier
	s_setprio 0
	s_add_i32 s28, s28, 2
	s_add_u32 s24, s24, 0x100
	s_addc_u32 s25, s25, 0
	s_cmp_lt_u32 s28, 30
	s_cbranch_scc1 .LBB0_854
	s_waitcnt vmcnt(0)
	s_cmpk_gt_u32 s6, 0xff
	s_cbranch_scc1 .LBB0_857
	s_barrier

.LBB0_946:
	s_ashr_i32 s49, s48, 31
	s_andn2_b64 vcc, exec, s[56:57]
	s_lshl_b64 s[6:7], s[48:49], 19
	s_add_u32 s52, s62, s6
	s_addc_u32 s53, s63, s7
	s_and_b64 s[6:7], s[56:57], exec
	s_cselect_b32 s5, s53, s41
	s_cselect_b32 s6, s52, s40
	s_ashr_i32 s51, s50, 31
	s_lshl_b64 s[8:9], s[50:51], 19
	s_add_u32 s54, s64, s8
	s_addc_u32 s55, s65, s9
	s_and_b64 s[8:9], s[56:57], exec
	s_cselect_b32 s7, s55, s39
	s_cselect_b32 s8, s54, s38
	s_add_u32 s9, s38, 0x100
	v_cndmask_b32_e64 v4, 0, 1, s[56:57]
	s_addc_u32 s10, s39, 0
	v_cmp_ne_u32_e64 s[36:37], 1, v4
	s_add_u32 s38, s40, 0x40080
	s_addc_u32 s39, s41, 0
	s_mov_b32 s11, -2
	s_waitcnt lgkmcnt(0)
	s_add_u32 s12, s38, 0xfffc0080
	s_addc_u32 s13, s39, -1
	s_add_i32 s14, 0, 0x10000
	s_cmp_eq_u32 s11, 12
	s_cselect_b32 s57, s5, s13
	s_cselect_b32 s56, s6, s12
	s_cselect_b32 s41, s7, s10
	s_cselect_b32 s40, s8, s9
	s_add_i32 s15, 0, 0x14000
	v_add_u32_e32 v144, s14, v230
	v_add_u32_e32 v160, s15, v230
	ds_read_b128 v[124:127], v144
	ds_read_b128 v[128:131], v144 offset:1024
	ds_read_b128 v[136:139], v144 offset:2048
	ds_read_b128 v[144:147], v144 offset:3072
	ds_read_b128 v[148:151], v160
	ds_read_b128 v[152:155], v160 offset:1024
	ds_read_b128 v[156:159], v160 offset:2048
	ds_read_b128 v[160:163], v160 offset:3072
	v_lshl_add_u64 v[196:197], s[38:39], 0, v[222:223]
	s_add_i32 m0, s71, 0xc000
	ds_read_b128 v[164:167], v243
	ds_read_b128 v[168:171], v243 offset:1024
	ds_read_b128 v[172:175], v243 offset:2048
	ds_read_b128 v[176:179], v243 offset:3072
	ds_read_b128 v[180:183], v243 offset:4096
	ds_read_b128 v[184:187], v243 offset:5120
	ds_read_b128 v[188:191], v243 offset:6144
	ds_read_b128 v[192:195], v243 offset:7168
	global_load_lds_dwordx4 v[196:197], off
	v_lshl_add_u64 v[196:197], s[38:39], 0, v[220:221]
	s_add_i32 m0, s71, 0xe000
	s_nop 0
	global_load_lds_dwordx4 v[196:197], off
	s_waitcnt vmcnt(8)
	s_waitcnt lgkmcnt(0)
	s_setprio 1
	s_barrier
	v_mfma_f32_16x16x32_bf16 v[140:143], v[124:127], v[164:167], 0
	v_mfma_f32_16x16x32_bf16 v[132:135], v[136:139], v[164:167], 0
	v_mfma_f32_16x16x32_bf16 v[112:115], v[124:127], v[172:175], 0
	v_mfma_f32_16x16x32_bf16 v[108:111], v[136:139], v[172:175], 0
	v_mfma_f32_16x16x32_bf16 v[96:99], v[124:127], v[180:183], 0
	v_mfma_f32_16x16x32_bf16 v[92:95], v[136:139], v[180:183], 0
	v_mfma_f32_16x16x32_bf16 v[80:83], v[124:127], v[188:191], 0
	v_mfma_f32_16x16x32_bf16 v[76:79], v[136:139], v[188:191], 0
	v_mfma_f32_16x16x32_bf16 v[140:143], v[128:131], v[168:171], v[140:143]
	v_mfma_f32_16x16x32_bf16 v[132:135], v[144:147], v[168:171], v[132:135]
	v_mfma_f32_16x16x32_bf16 v[112:115], v[128:131], v[176:179], v[112:115]
	v_mfma_f32_16x16x32_bf16 v[108:111], v[144:147], v[176:179], v[108:111]
	v_mfma_f32_16x16x32_bf16 v[96:99], v[128:131], v[184:187], v[96:99]
	v_mfma_f32_16x16x32_bf16 v[92:95], v[144:147], v[184:187], v[92:95]
	v_mfma_f32_16x16x32_bf16 v[80:83], v[128:131], v[192:195], v[80:83]
	v_mfma_f32_16x16x32_bf16 v[76:79], v[144:147], v[192:195], v[76:79]
	s_setprio 0
	s_setprio 1
	v_mfma_f32_16x16x32_bf16 v[120:123], v[148:151], v[164:167], 0
	v_mfma_f32_16x16x32_bf16 v[116:119], v[156:159], v[164:167], 0
	v_mfma_f32_16x16x32_bf16 v[104:107], v[148:151], v[172:175], 0
	v_mfma_f32_16x16x32_bf16 v[100:103], v[156:159], v[172:175], 0
	v_mfma_f32_16x16x32_bf16 v[88:91], v[148:151], v[180:183], 0
	v_mfma_f32_16x16x32_bf16 v[84:87], v[156:159], v[180:183], 0
	v_mfma_f32_16x16x32_bf16 v[72:75], v[148:151], v[188:191], 0
	v_mfma_f32_16x16x32_bf16 v[68:71], v[156:159], v[188:191], 0
	v_mfma_f32_16x16x32_bf16 v[120:123], v[152:155], v[168:171], v[120:123]
	v_mfma_f32_16x16x32_bf16 v[116:119], v[160:163], v[168:171], v[116:119]
	v_mfma_f32_16x16x32_bf16 v[104:107], v[152:155], v[176:179], v[104:107]
	v_mfma_f32_16x16x32_bf16 v[100:103], v[160:163], v[176:179], v[100:103]
	v_mfma_f32_16x16x32_bf16 v[88:91], v[152:155], v[184:187], v[88:91]
	v_mfma_f32_16x16x32_bf16 v[84:87], v[160:163], v[184:187], v[84:87]
	v_mfma_f32_16x16x32_bf16 v[72:75], v[152:155], v[192:195], v[72:75]
	v_mfma_f32_16x16x32_bf16 v[68:71], v[160:163], v[192:195], v[68:71]
	s_barrier
	s_setprio 0
	s_add_i32 s12, s14, s70
	v_lshl_add_u64 v[196:197], s[40:41], 0, v[2:3]
	s_mov_b32 m0, s12
	ds_read_b128 v[164:167], v243 offset:16384
	ds_read_b128 v[168:171], v243 offset:17408
	ds_read_b128 v[172:175], v243 offset:18432
	ds_read_b128 v[176:179], v243 offset:19456
	ds_read_b128 v[180:183], v243 offset:20480
	ds_read_b128 v[184:187], v243 offset:21504
	ds_read_b128 v[188:191], v243 offset:22528
	ds_read_b128 v[192:195], v243 offset:23552
	global_load_lds_dwordx4 v[196:197], off
	s_add_i32 m0, s12, 0x2000
	s_add_u32 s12, s40, 0x40000
	v_lshl_add_u64 v[198:199], s[40:41], 0, v[218:219]
	s_addc_u32 s13, s41, 0
	s_add_i32 s14, s15, s70
	global_load_lds_dwordx4 v[198:199], off
	v_lshl_add_u64 v[200:201], s[12:13], 0, v[2:3]
	s_mov_b32 m0, s14
	v_lshl_add_u64 v[202:203], s[56:57], 0, v[216:217]
	global_load_lds_dwordx4 v[200:201], off
	v_lshl_add_u64 v[200:201], s[12:13], 0, v[218:219]
	s_add_i32 m0, s14, 0x2000
	s_nop 0
	global_load_lds_dwordx4 v[200:201], off
	v_lshl_add_u64 v[200:201], s[56:57], 0, v[0:1]
	s_mov_b32 m0, s71
	s_nop 0
	global_load_lds_dwordx4 v[200:201], off
	s_mov_b32 m0, s80
	s_nop 0
	global_load_lds_dwordx4 v[202:203], off
	s_waitcnt vmcnt(8)
	s_waitcnt lgkmcnt(0)
	s_setprio 1
	s_barrier
	v_mfma_f32_16x16x32_bf16 v[64:67], v[124:127], v[164:167], 0
	v_mfma_f32_16x16x32_bf16 v[60:63], v[136:139], v[164:167], 0
	v_mfma_f32_16x16x32_bf16 v[48:51], v[124:127], v[172:175], 0
	v_mfma_f32_16x16x32_bf16 v[44:47], v[136:139], v[172:175], 0
	v_mfma_f32_16x16x32_bf16 v[32:35], v[124:127], v[180:183], 0
	v_mfma_f32_16x16x32_bf16 v[28:31], v[136:139], v[180:183], 0
	v_mfma_f32_16x16x32_bf16 v[16:19], v[124:127], v[188:191], 0
	v_mfma_f32_16x16x32_bf16 v[12:15], v[136:139], v[188:191], 0
	v_mfma_f32_16x16x32_bf16 v[64:67], v[128:131], v[168:171], v[64:67]
	v_mfma_f32_16x16x32_bf16 v[60:63], v[144:147], v[168:171], v[60:63]
	v_mfma_f32_16x16x32_bf16 v[48:51], v[128:131], v[176:179], v[48:51]
	v_mfma_f32_16x16x32_bf16 v[44:47], v[144:147], v[176:179], v[44:47]
	v_mfma_f32_16x16x32_bf16 v[32:35], v[128:131], v[184:187], v[32:35]
	v_mfma_f32_16x16x32_bf16 v[28:31], v[144:147], v[184:187], v[28:31]
	v_mfma_f32_16x16x32_bf16 v[16:19], v[128:131], v[192:195], v[16:19]
	v_mfma_f32_16x16x32_bf16 v[12:15], v[144:147], v[192:195], v[12:15]
	s_setprio 0
	s_setprio 1
	v_mfma_f32_16x16x32_bf16 v[56:59], v[148:151], v[164:167], 0
	v_mfma_f32_16x16x32_bf16 v[52:55], v[156:159], v[164:167], 0
	v_mfma_f32_16x16x32_bf16 v[40:43], v[148:151], v[172:175], 0
	v_mfma_f32_16x16x32_bf16 v[36:39], v[156:159], v[172:175], 0
	v_mfma_f32_16x16x32_bf16 v[24:27], v[148:151], v[180:183], 0
	v_mfma_f32_16x16x32_bf16 v[20:23], v[156:159], v[180:183], 0
	v_mfma_f32_16x16x32_bf16 v[8:11], v[148:151], v[188:191], 0
	v_mfma_f32_16x16x32_bf16 v[4:7], v[156:159], v[188:191], 0
	v_mfma_f32_16x16x32_bf16 v[56:59], v[152:155], v[168:171], v[56:59]
	v_mfma_f32_16x16x32_bf16 v[52:55], v[160:163], v[168:171], v[52:55]
	v_mfma_f32_16x16x32_bf16 v[40:43], v[152:155], v[176:179], v[40:43]
	v_mfma_f32_16x16x32_bf16 v[36:39], v[160:163], v[176:179], v[36:39]
	v_mfma_f32_16x16x32_bf16 v[24:27], v[152:155], v[184:187], v[24:27]
	v_mfma_f32_16x16x32_bf16 v[20:23], v[160:163], v[184:187], v[20:23]
	v_mfma_f32_16x16x32_bf16 v[8:11], v[152:155], v[192:195], v[8:11]
	v_mfma_f32_16x16x32_bf16 v[4:7], v[160:163], v[192:195], v[4:7]
	s_barrier
	s_setprio 0
	s_add_i32 s14, 0, 0x18000
	s_add_i32 s15, 0, 0x1c000
	v_add_u32_e32 v144, s14, v230
	v_add_u32_e32 v160, s15, v230
	ds_read_b128 v[124:127], v144
	ds_read_b128 v[128:131], v144 offset:1024
	ds_read_b128 v[136:139], v144 offset:2048
	ds_read_b128 v[144:147], v144 offset:3072
	ds_read_b128 v[148:151], v160
	ds_read_b128 v[152:155], v160 offset:1024
	ds_read_b128 v[156:159], v160 offset:2048
	ds_read_b128 v[160:163], v160 offset:3072
	s_add_u32 s12, s56, 0x40000
	s_addc_u32 s13, s57, 0
	s_mov_b32 m0, s81
	v_lshl_add_u64 v[204:205], s[12:13], 0, v[0:1]
	ds_read_b128 v[164:167], v243 offset:32768
	ds_read_b128 v[168:171], v243 offset:33792
	ds_read_b128 v[172:175], v243 offset:34816
	ds_read_b128 v[176:179], v243 offset:35840
	ds_read_b128 v[180:183], v243 offset:36864
	ds_read_b128 v[184:187], v243 offset:37888
	ds_read_b128 v[188:191], v243 offset:38912
	ds_read_b128 v[192:195], v243 offset:39936
	global_load_lds_dwordx4 v[204:205], off
	v_lshl_add_u64 v[204:205], s[12:13], 0, v[216:217]
	s_mov_b32 m0, s82
	s_nop 0
	global_load_lds_dwordx4 v[204:205], off
	s_waitcnt vmcnt(8)
	s_waitcnt lgkmcnt(0)
	s_setprio 1
	s_barrier
	v_mfma_f32_16x16x32_bf16 v[140:143], v[124:127], v[164:167], v[140:143]
	v_mfma_f32_16x16x32_bf16 v[132:135], v[136:139], v[164:167], v[132:135]
	v_mfma_f32_16x16x32_bf16 v[112:115], v[124:127], v[172:175], v[112:115]
	v_mfma_f32_16x16x32_bf16 v[108:111], v[136:139], v[172:175], v[108:111]
	v_mfma_f32_16x16x32_bf16 v[96:99], v[124:127], v[180:183], v[96:99]
	v_mfma_f32_16x16x32_bf16 v[92:95], v[136:139], v[180:183], v[92:95]
	v_mfma_f32_16x16x32_bf16 v[80:83], v[124:127], v[188:191], v[80:83]
	v_mfma_f32_16x16x32_bf16 v[76:79], v[136:139], v[188:191], v[76:79]
	v_mfma_f32_16x16x32_bf16 v[140:143], v[128:131], v[168:171], v[140:143]
	v_mfma_f32_16x16x32_bf16 v[132:135], v[144:147], v[168:171], v[132:135]
	v_mfma_f32_16x16x32_bf16 v[112:115], v[128:131], v[176:179], v[112:115]
	v_mfma_f32_16x16x32_bf16 v[108:111], v[144:147], v[176:179], v[108:111]
	v_mfma_f32_16x16x32_bf16 v[96:99], v[128:131], v[184:187], v[96:99]
	v_mfma_f32_16x16x32_bf16 v[92:95], v[144:147], v[184:187], v[92:95]
	v_mfma_f32_16x16x32_bf16 v[80:83], v[128:131], v[192:195], v[80:83]
	v_mfma_f32_16x16x32_bf16 v[76:79], v[144:147], v[192:195], v[76:79]
	s_setprio 0
	s_setprio 1
	v_mfma_f32_16x16x32_bf16 v[120:123], v[148:151], v[164:167], v[120:123]
	v_mfma_f32_16x16x32_bf16 v[116:119], v[156:159], v[164:167], v[116:119]
	v_mfma_f32_16x16x32_bf16 v[104:107], v[148:151], v[172:175], v[104:107]
	v_mfma_f32_16x16x32_bf16 v[100:103], v[156:159], v[172:175], v[100:103]
	v_mfma_f32_16x16x32_bf16 v[88:91], v[148:151], v[180:183], v[88:91]
	v_mfma_f32_16x16x32_bf16 v[84:87], v[156:159], v[180:183], v[84:87]
	v_mfma_f32_16x16x32_bf16 v[72:75], v[148:151], v[188:191], v[72:75]
	v_mfma_f32_16x16x32_bf16 v[68:71], v[156:159], v[188:191], v[68:71]
	v_mfma_f32_16x16x32_bf16 v[120:123], v[152:155], v[168:171], v[120:123]
	v_mfma_f32_16x16x32_bf16 v[116:119], v[160:163], v[168:171], v[116:119]
	v_mfma_f32_16x16x32_bf16 v[104:107], v[152:155], v[176:179], v[104:107]
	v_mfma_f32_16x16x32_bf16 v[100:103], v[160:163], v[176:179], v[100:103]
	v_mfma_f32_16x16x32_bf16 v[88:91], v[152:155], v[184:187], v[88:91]
	v_mfma_f32_16x16x32_bf16 v[84:87], v[160:163], v[184:187], v[84:87]
	v_mfma_f32_16x16x32_bf16 v[72:75], v[152:155], v[192:195], v[72:75]
	v_mfma_f32_16x16x32_bf16 v[68:71], v[160:163], v[192:195], v[68:71]
	s_barrier
	s_setprio 0
	s_add_i32 s12, s14, s70
	v_lshl_add_u64 v[196:197], v[196:197], 0, s[68:69]
	s_mov_b32 m0, s12
	ds_read_b128 v[164:167], v243 offset:49152
	ds_read_b128 v[168:171], v243 offset:50176
	ds_read_b128 v[172:175], v243 offset:51200
	ds_read_b128 v[176:179], v243 offset:52224
	ds_read_b128 v[180:183], v243 offset:53248
	ds_read_b128 v[184:187], v243 offset:54272
	ds_read_b128 v[188:191], v243 offset:55296
	ds_read_b128 v[192:195], v243 offset:56320
	global_load_lds_dwordx4 v[196:197], off
	s_add_i32 m0, s12, 0x2000
	s_add_u32 s12, s40, 0x40080
	v_lshl_add_u64 v[196:197], v[198:199], 0, s[68:69]
	s_addc_u32 s13, s41, 0
	s_add_i32 s14, s15, s70
	global_load_lds_dwordx4 v[196:197], off
	v_lshl_add_u64 v[196:197], s[12:13], 0, v[2:3]
	s_mov_b32 m0, s14
	s_nop 0
	global_load_lds_dwordx4 v[196:197], off
	v_lshl_add_u64 v[196:197], s[12:13], 0, v[218:219]
	s_add_i32 m0, s14, 0x2000
	s_nop 0
	global_load_lds_dwordx4 v[196:197], off
	v_lshl_add_u64 v[196:197], v[200:201], 0, s[68:69]
	s_mov_b32 m0, s85
	s_nop 0
	global_load_lds_dwordx4 v[196:197], off
	v_lshl_add_u64 v[196:197], v[202:203], 0, s[68:69]
	s_mov_b32 m0, s87
	s_nop 0
	global_load_lds_dwordx4 v[196:197], off
	s_waitcnt vmcnt(8)
	s_waitcnt lgkmcnt(0)
	s_setprio 1
	s_barrier
	v_mfma_f32_16x16x32_bf16 v[64:67], v[124:127], v[164:167], v[64:67]
	v_mfma_f32_16x16x32_bf16 v[60:63], v[136:139], v[164:167], v[60:63]
	v_mfma_f32_16x16x32_bf16 v[48:51], v[124:127], v[172:175], v[48:51]
	v_mfma_f32_16x16x32_bf16 v[44:47], v[136:139], v[172:175], v[44:47]
	v_mfma_f32_16x16x32_bf16 v[32:35], v[124:127], v[180:183], v[32:35]
	v_mfma_f32_16x16x32_bf16 v[28:31], v[136:139], v[180:183], v[28:31]
	v_mfma_f32_16x16x32_bf16 v[16:19], v[124:127], v[188:191], v[16:19]
	v_mfma_f32_16x16x32_bf16 v[12:15], v[136:139], v[188:191], v[12:15]
	v_mfma_f32_16x16x32_bf16 v[64:67], v[128:131], v[168:171], v[64:67]
	v_mfma_f32_16x16x32_bf16 v[60:63], v[144:147], v[168:171], v[60:63]
	v_mfma_f32_16x16x32_bf16 v[48:51], v[128:131], v[176:179], v[48:51]
	v_mfma_f32_16x16x32_bf16 v[44:47], v[144:147], v[176:179], v[44:47]
	v_mfma_f32_16x16x32_bf16 v[32:35], v[128:131], v[184:187], v[32:35]
	v_mfma_f32_16x16x32_bf16 v[28:31], v[144:147], v[184:187], v[28:31]
	v_mfma_f32_16x16x32_bf16 v[16:19], v[128:131], v[192:195], v[16:19]
	v_mfma_f32_16x16x32_bf16 v[12:15], v[144:147], v[192:195], v[12:15]
	s_setprio 0
	s_setprio 1
	v_mfma_f32_16x16x32_bf16 v[56:59], v[148:151], v[164:167], v[56:59]
	v_mfma_f32_16x16x32_bf16 v[52:55], v[156:159], v[164:167], v[52:55]
	v_mfma_f32_16x16x32_bf16 v[40:43], v[148:151], v[172:175], v[40:43]
	v_mfma_f32_16x16x32_bf16 v[36:39], v[156:159], v[172:175], v[36:39]
	v_mfma_f32_16x16x32_bf16 v[24:27], v[148:151], v[180:183], v[24:27]
	v_mfma_f32_16x16x32_bf16 v[20:23], v[156:159], v[180:183], v[20:23]
	v_mfma_f32_16x16x32_bf16 v[8:11], v[148:151], v[188:191], v[8:11]
	v_mfma_f32_16x16x32_bf16 v[4:7], v[156:159], v[188:191], v[4:7]
	v_mfma_f32_16x16x32_bf16 v[56:59], v[152:155], v[168:171], v[56:59]
	v_mfma_f32_16x16x32_bf16 v[52:55], v[160:163], v[168:171], v[52:55]
	v_mfma_f32_16x16x32_bf16 v[40:43], v[152:155], v[176:179], v[40:43]
	v_mfma_f32_16x16x32_bf16 v[36:39], v[160:163], v[176:179], v[36:39]
	v_mfma_f32_16x16x32_bf16 v[24:27], v[152:155], v[184:187], v[24:27]
	v_mfma_f32_16x16x32_bf16 v[20:23], v[160:163], v[184:187], v[20:23]
	v_mfma_f32_16x16x32_bf16 v[8:11], v[152:155], v[192:195], v[8:11]
	v_mfma_f32_16x16x32_bf16 v[4:7], v[160:163], v[192:195], v[4:7]
	s_barrier
	s_setprio 0
	s_add_i32 s11, s11, 2
	s_add_u32 s9, s9, 0x100
	s_addc_u32 s10, s10, 0
	s_add_u32 s38, s38, 0x100
	s_addc_u32 s39, s39, 0
	s_cmp_gt_u32 s11, 13
.LBB0_947:
	s_add_u32 s12, s38, 0xfffc0080
	s_addc_u32 s13, s39, -1
	s_add_i32 s14, 0, 0x10000
	s_cmp_eq_u32 s11, 12
	s_cselect_b32 s57, s5, s13
	s_cselect_b32 s56, s6, s12
	s_cselect_b32 s41, s7, s10
	s_cselect_b32 s40, s8, s9
	s_add_i32 s15, 0, 0x14000
	v_add_u32_e32 v144, s14, v230
	v_add_u32_e32 v160, s15, v230
	ds_read_b128 v[124:127], v144
	ds_read_b128 v[128:131], v144 offset:1024
	ds_read_b128 v[136:139], v144 offset:2048
	ds_read_b128 v[144:147], v144 offset:3072
	ds_read_b128 v[148:151], v160
	ds_read_b128 v[152:155], v160 offset:1024
	ds_read_b128 v[156:159], v160 offset:2048
	ds_read_b128 v[160:163], v160 offset:3072
	v_lshl_add_u64 v[196:197], s[38:39], 0, v[222:223]
	s_add_i32 m0, s71, 0xc000
	ds_read_b128 v[164:167], v243
	ds_read_b128 v[168:171], v243 offset:1024
	ds_read_b128 v[172:175], v243 offset:2048
	ds_read_b128 v[176:179], v243 offset:3072
	ds_read_b128 v[180:183], v243 offset:4096
	ds_read_b128 v[184:187], v243 offset:5120
	ds_read_b128 v[188:191], v243 offset:6144
	ds_read_b128 v[192:195], v243 offset:7168
	global_load_lds_dwordx4 v[196:197], off
	v_lshl_add_u64 v[196:197], s[38:39], 0, v[220:221]
	s_add_i32 m0, s71, 0xe000
	s_nop 0
	global_load_lds_dwordx4 v[196:197], off
	s_waitcnt vmcnt(8)
	s_waitcnt lgkmcnt(0)
	s_setprio 1
	s_barrier
	v_mfma_f32_16x16x32_bf16 v[140:143], v[124:127], v[164:167], v[140:143]
	v_mfma_f32_16x16x32_bf16 v[132:135], v[136:139], v[164:167], v[132:135]
	v_mfma_f32_16x16x32_bf16 v[112:115], v[124:127], v[172:175], v[112:115]
	v_mfma_f32_16x16x32_bf16 v[108:111], v[136:139], v[172:175], v[108:111]
	v_mfma_f32_16x16x32_bf16 v[96:99], v[124:127], v[180:183], v[96:99]
	v_mfma_f32_16x16x32_bf16 v[92:95], v[136:139], v[180:183], v[92:95]
	v_mfma_f32_16x16x32_bf16 v[80:83], v[124:127], v[188:191], v[80:83]
	v_mfma_f32_16x16x32_bf16 v[76:79], v[136:139], v[188:191], v[76:79]
	v_mfma_f32_16x16x32_bf16 v[140:143], v[128:131], v[168:171], v[140:143]
	v_mfma_f32_16x16x32_bf16 v[132:135], v[144:147], v[168:171], v[132:135]
	v_mfma_f32_16x16x32_bf16 v[112:115], v[128:131], v[176:179], v[112:115]
	v_mfma_f32_16x16x32_bf16 v[108:111], v[144:147], v[176:179], v[108:111]
	v_mfma_f32_16x16x32_bf16 v[96:99], v[128:131], v[184:187], v[96:99]
	v_mfma_f32_16x16x32_bf16 v[92:95], v[144:147], v[184:187], v[92:95]
	v_mfma_f32_16x16x32_bf16 v[80:83], v[128:131], v[192:195], v[80:83]
	v_mfma_f32_16x16x32_bf16 v[76:79], v[144:147], v[192:195], v[76:79]
	s_setprio 0
	s_setprio 1
	v_mfma_f32_16x16x32_bf16 v[120:123], v[148:151], v[164:167], v[120:123]
	v_mfma_f32_16x16x32_bf16 v[116:119], v[156:159], v[164:167], v[116:119]
	v_mfma_f32_16x16x32_bf16 v[104:107], v[148:151], v[172:175], v[104:107]
	v_mfma_f32_16x16x32_bf16 v[100:103], v[156:159], v[172:175], v[100:103]
	v_mfma_f32_16x16x32_bf16 v[88:91], v[148:151], v[180:183], v[88:91]
	v_mfma_f32_16x16x32_bf16 v[84:87], v[156:159], v[180:183], v[84:87]
	v_mfma_f32_16x16x32_bf16 v[72:75], v[148:151], v[188:191], v[72:75]
	v_mfma_f32_16x16x32_bf16 v[68:71], v[156:159], v[188:191], v[68:71]
	v_mfma_f32_16x16x32_bf16 v[120:123], v[152:155], v[168:171], v[120:123]
	v_mfma_f32_16x16x32_bf16 v[116:119], v[160:163], v[168:171], v[116:119]
	v_mfma_f32_16x16x32_bf16 v[104:107], v[152:155], v[176:179], v[104:107]
	v_mfma_f32_16x16x32_bf16 v[100:103], v[160:163], v[176:179], v[100:103]
	v_mfma_f32_16x16x32_bf16 v[88:91], v[152:155], v[184:187], v[88:91]
	v_mfma_f32_16x16x32_bf16 v[84:87], v[160:163], v[184:187], v[84:87]
	v_mfma_f32_16x16x32_bf16 v[72:75], v[152:155], v[192:195], v[72:75]
	v_mfma_f32_16x16x32_bf16 v[68:71], v[160:163], v[192:195], v[68:71]
	s_barrier
	s_setprio 0
	s_add_i32 s12, s14, s70
	v_lshl_add_u64 v[196:197], s[40:41], 0, v[2:3]
	s_mov_b32 m0, s12
	ds_read_b128 v[164:167], v243 offset:16384
	ds_read_b128 v[168:171], v243 offset:17408
	ds_read_b128 v[172:175], v243 offset:18432
	ds_read_b128 v[176:179], v243 offset:19456
	ds_read_b128 v[180:183], v243 offset:20480
	ds_read_b128 v[184:187], v243 offset:21504
	ds_read_b128 v[188:191], v243 offset:22528
	ds_read_b128 v[192:195], v243 offset:23552
	global_load_lds_dwordx4 v[196:197], off
	s_add_i32 m0, s12, 0x2000
	s_add_u32 s12, s40, 0x40000
	v_lshl_add_u64 v[198:199], s[40:41], 0, v[218:219]
	s_addc_u32 s13, s41, 0
	s_add_i32 s14, s15, s70
	global_load_lds_dwordx4 v[198:199], off
	v_lshl_add_u64 v[200:201], s[12:13], 0, v[2:3]
	s_mov_b32 m0, s14
	v_lshl_add_u64 v[202:203], s[56:57], 0, v[216:217]
	global_load_lds_dwordx4 v[200:201], off
	v_lshl_add_u64 v[200:201], s[12:13], 0, v[218:219]
	s_add_i32 m0, s14, 0x2000
	s_nop 0
	global_load_lds_dwordx4 v[200:201], off
	v_lshl_add_u64 v[200:201], s[56:57], 0, v[0:1]
	s_mov_b32 m0, s71
	s_nop 0
	global_load_lds_dwordx4 v[200:201], off
	s_mov_b32 m0, s80
	s_nop 0
	global_load_lds_dwordx4 v[202:203], off
	s_waitcnt vmcnt(8)
	s_waitcnt lgkmcnt(0)
	s_setprio 1
	s_barrier
	v_mfma_f32_16x16x32_bf16 v[64:67], v[124:127], v[164:167], v[64:67]
	v_mfma_f32_16x16x32_bf16 v[60:63], v[136:139], v[164:167], v[60:63]
	v_mfma_f32_16x16x32_bf16 v[48:51], v[124:127], v[172:175], v[48:51]
	v_mfma_f32_16x16x32_bf16 v[44:47], v[136:139], v[172:175], v[44:47]
	v_mfma_f32_16x16x32_bf16 v[32:35], v[124:127], v[180:183], v[32:35]
	v_mfma_f32_16x16x32_bf16 v[28:31], v[136:139], v[180:183], v[28:31]
	v_mfma_f32_16x16x32_bf16 v[16:19], v[124:127], v[188:191], v[16:19]
	v_mfma_f32_16x16x32_bf16 v[12:15], v[136:139], v[188:191], v[12:15]
	v_mfma_f32_16x16x32_bf16 v[64:67], v[128:131], v[168:171], v[64:67]
	v_mfma_f32_16x16x32_bf16 v[60:63], v[144:147], v[168:171], v[60:63]
	v_mfma_f32_16x16x32_bf16 v[48:51], v[128:131], v[176:179], v[48:51]
	v_mfma_f32_16x16x32_bf16 v[44:47], v[144:147], v[176:179], v[44:47]
	v_mfma_f32_16x16x32_bf16 v[32:35], v[128:131], v[184:187], v[32:35]
	v_mfma_f32_16x16x32_bf16 v[28:31], v[144:147], v[184:187], v[28:31]
	v_mfma_f32_16x16x32_bf16 v[16:19], v[128:131], v[192:195], v[16:19]
	v_mfma_f32_16x16x32_bf16 v[12:15], v[144:147], v[192:195], v[12:15]
	s_setprio 0
	s_setprio 1
	v_mfma_f32_16x16x32_bf16 v[56:59], v[148:151], v[164:167], v[56:59]
	v_mfma_f32_16x16x32_bf16 v[52:55], v[156:159], v[164:167], v[52:55]
	v_mfma_f32_16x16x32_bf16 v[40:43], v[148:151], v[172:175], v[40:43]
	v_mfma_f32_16x16x32_bf16 v[36:39], v[156:159], v[172:175], v[36:39]
	v_mfma_f32_16x16x32_bf16 v[24:27], v[148:151], v[180:183], v[24:27]
	v_mfma_f32_16x16x32_bf16 v[20:23], v[156:159], v[180:183], v[20:23]
	v_mfma_f32_16x16x32_bf16 v[8:11], v[148:151], v[188:191], v[8:11]
	v_mfma_f32_16x16x32_bf16 v[4:7], v[156:159], v[188:191], v[4:7]
	v_mfma_f32_16x16x32_bf16 v[56:59], v[152:155], v[168:171], v[56:59]
	v_mfma_f32_16x16x32_bf16 v[52:55], v[160:163], v[168:171], v[52:55]
	v_mfma_f32_16x16x32_bf16 v[40:43], v[152:155], v[176:179], v[40:43]
	v_mfma_f32_16x16x32_bf16 v[36:39], v[160:163], v[176:179], v[36:39]
	v_mfma_f32_16x16x32_bf16 v[24:27], v[152:155], v[184:187], v[24:27]
	v_mfma_f32_16x16x32_bf16 v[20:23], v[160:163], v[184:187], v[20:23]
	v_mfma_f32_16x16x32_bf16 v[8:11], v[152:155], v[192:195], v[8:11]
	v_mfma_f32_16x16x32_bf16 v[4:7], v[160:163], v[192:195], v[4:7]
	s_barrier
	s_setprio 0
	s_add_i32 s14, 0, 0x18000
	s_add_i32 s15, 0, 0x1c000
	v_add_u32_e32 v144, s14, v230
	v_add_u32_e32 v160, s15, v230
	ds_read_b128 v[124:127], v144
	ds_read_b128 v[128:131], v144 offset:1024
	ds_read_b128 v[136:139], v144 offset:2048
	ds_read_b128 v[144:147], v144 offset:3072
	ds_read_b128 v[148:151], v160
	ds_read_b128 v[152:155], v160 offset:1024
	ds_read_b128 v[156:159], v160 offset:2048
	ds_read_b128 v[160:163], v160 offset:3072
	s_add_u32 s12, s56, 0x40000
	s_addc_u32 s13, s57, 0
	s_mov_b32 m0, s81
	v_lshl_add_u64 v[204:205], s[12:13], 0, v[0:1]
	ds_read_b128 v[164:167], v243 offset:32768
	ds_read_b128 v[168:171], v243 offset:33792
	ds_read_b128 v[172:175], v243 offset:34816
	ds_read_b128 v[176:179], v243 offset:35840
	ds_read_b128 v[180:183], v243 offset:36864
	ds_read_b128 v[184:187], v243 offset:37888
	ds_read_b128 v[188:191], v243 offset:38912
	ds_read_b128 v[192:195], v243 offset:39936
	global_load_lds_dwordx4 v[204:205], off
	v_lshl_add_u64 v[204:205], s[12:13], 0, v[216:217]
	s_mov_b32 m0, s82
	s_nop 0
	global_load_lds_dwordx4 v[204:205], off
	s_waitcnt vmcnt(8)
	s_waitcnt lgkmcnt(0)
	s_setprio 1
	s_barrier
	v_mfma_f32_16x16x32_bf16 v[140:143], v[124:127], v[164:167], v[140:143]
	v_mfma_f32_16x16x32_bf16 v[132:135], v[136:139], v[164:167], v[132:135]
	v_mfma_f32_16x16x32_bf16 v[112:115], v[124:127], v[172:175], v[112:115]
	v_mfma_f32_16x16x32_bf16 v[108:111], v[136:139], v[172:175], v[108:111]
	v_mfma_f32_16x16x32_bf16 v[96:99], v[124:127], v[180:183], v[96:99]
	v_mfma_f32_16x16x32_bf16 v[92:95], v[136:139], v[180:183], v[92:95]
	v_mfma_f32_16x16x32_bf16 v[80:83], v[124:127], v[188:191], v[80:83]
	v_mfma_f32_16x16x32_bf16 v[76:79], v[136:139], v[188:191], v[76:79]
	v_mfma_f32_16x16x32_bf16 v[140:143], v[128:131], v[168:171], v[140:143]
	v_mfma_f32_16x16x32_bf16 v[132:135], v[144:147], v[168:171], v[132:135]
	v_mfma_f32_16x16x32_bf16 v[112:115], v[128:131], v[176:179], v[112:115]
	v_mfma_f32_16x16x32_bf16 v[108:111], v[144:147], v[176:179], v[108:111]
	v_mfma_f32_16x16x32_bf16 v[96:99], v[128:131], v[184:187], v[96:99]
	v_mfma_f32_16x16x32_bf16 v[92:95], v[144:147], v[184:187], v[92:95]
	v_mfma_f32_16x16x32_bf16 v[80:83], v[128:131], v[192:195], v[80:83]
	v_mfma_f32_16x16x32_bf16 v[76:79], v[144:147], v[192:195], v[76:79]
	s_setprio 0
	s_setprio 1
	v_mfma_f32_16x16x32_bf16 v[120:123], v[148:151], v[164:167], v[120:123]
	v_mfma_f32_16x16x32_bf16 v[116:119], v[156:159], v[164:167], v[116:119]
	v_mfma_f32_16x16x32_bf16 v[104:107], v[148:151], v[172:175], v[104:107]
	v_mfma_f32_16x16x32_bf16 v[100:103], v[156:159], v[172:175], v[100:103]
	v_mfma_f32_16x16x32_bf16 v[88:91], v[148:151], v[180:183], v[88:91]
	v_mfma_f32_16x16x32_bf16 v[84:87], v[156:159], v[180:183], v[84:87]
	v_mfma_f32_16x16x32_bf16 v[72:75], v[148:151], v[188:191], v[72:75]
	v_mfma_f32_16x16x32_bf16 v[68:71], v[156:159], v[188:191], v[68:71]
	v_mfma_f32_16x16x32_bf16 v[120:123], v[152:155], v[168:171], v[120:123]
	v_mfma_f32_16x16x32_bf16 v[116:119], v[160:163], v[168:171], v[116:119]
	v_mfma_f32_16x16x32_bf16 v[104:107], v[152:155], v[176:179], v[104:107]
	v_mfma_f32_16x16x32_bf16 v[100:103], v[160:163], v[176:179], v[100:103]
	v_mfma_f32_16x16x32_bf16 v[88:91], v[152:155], v[184:187], v[88:91]
	v_mfma_f32_16x16x32_bf16 v[84:87], v[160:163], v[184:187], v[84:87]
	v_mfma_f32_16x16x32_bf16 v[72:75], v[152:155], v[192:195], v[72:75]
	v_mfma_f32_16x16x32_bf16 v[68:71], v[160:163], v[192:195], v[68:71]
	s_barrier
	s_setprio 0
	s_add_i32 s12, s14, s70
	v_lshl_add_u64 v[196:197], v[196:197], 0, s[68:69]
	s_mov_b32 m0, s12
	ds_read_b128 v[164:167], v243 offset:49152
	ds_read_b128 v[168:171], v243 offset:50176
	ds_read_b128 v[172:175], v243 offset:51200
	ds_read_b128 v[176:179], v243 offset:52224
	ds_read_b128 v[180:183], v243 offset:53248
	ds_read_b128 v[184:187], v243 offset:54272
	ds_read_b128 v[188:191], v243 offset:55296
	ds_read_b128 v[192:195], v243 offset:56320
	global_load_lds_dwordx4 v[196:197], off
	s_add_i32 m0, s12, 0x2000
	s_add_u32 s12, s40, 0x40080
	v_lshl_add_u64 v[196:197], v[198:199], 0, s[68:69]
	s_addc_u32 s13, s41, 0
	s_add_i32 s14, s15, s70
	global_load_lds_dwordx4 v[196:197], off
	v_lshl_add_u64 v[196:197], s[12:13], 0, v[2:3]
	s_mov_b32 m0, s14
	s_nop 0
	global_load_lds_dwordx4 v[196:197], off
	v_lshl_add_u64 v[196:197], s[12:13], 0, v[218:219]
	s_add_i32 m0, s14, 0x2000
	s_nop 0
	global_load_lds_dwordx4 v[196:197], off
	v_lshl_add_u64 v[196:197], v[200:201], 0, s[68:69]
	s_mov_b32 m0, s85
	s_nop 0
	global_load_lds_dwordx4 v[196:197], off
	v_lshl_add_u64 v[196:197], v[202:203], 0, s[68:69]
	s_mov_b32 m0, s87
	s_nop 0
	global_load_lds_dwordx4 v[196:197], off
	s_waitcnt vmcnt(8)
	s_waitcnt lgkmcnt(0)
	s_setprio 1
	s_barrier
	v_mfma_f32_16x16x32_bf16 v[64:67], v[124:127], v[164:167], v[64:67]
	v_mfma_f32_16x16x32_bf16 v[60:63], v[136:139], v[164:167], v[60:63]
	v_mfma_f32_16x16x32_bf16 v[48:51], v[124:127], v[172:175], v[48:51]
	v_mfma_f32_16x16x32_bf16 v[44:47], v[136:139], v[172:175], v[44:47]
	v_mfma_f32_16x16x32_bf16 v[32:35], v[124:127], v[180:183], v[32:35]
	v_mfma_f32_16x16x32_bf16 v[28:31], v[136:139], v[180:183], v[28:31]
	v_mfma_f32_16x16x32_bf16 v[16:19], v[124:127], v[188:191], v[16:19]
	v_mfma_f32_16x16x32_bf16 v[12:15], v[136:139], v[188:191], v[12:15]
	v_mfma_f32_16x16x32_bf16 v[64:67], v[128:131], v[168:171], v[64:67]
	v_mfma_f32_16x16x32_bf16 v[60:63], v[144:147], v[168:171], v[60:63]
	v_mfma_f32_16x16x32_bf16 v[48:51], v[128:131], v[176:179], v[48:51]
	v_mfma_f32_16x16x32_bf16 v[44:47], v[144:147], v[176:179], v[44:47]
	v_mfma_f32_16x16x32_bf16 v[32:35], v[128:131], v[184:187], v[32:35]
	v_mfma_f32_16x16x32_bf16 v[28:31], v[144:147], v[184:187], v[28:31]
	v_mfma_f32_16x16x32_bf16 v[16:19], v[128:131], v[192:195], v[16:19]
	v_mfma_f32_16x16x32_bf16 v[12:15], v[144:147], v[192:195], v[12:15]
	s_setprio 0
	s_setprio 1
	v_mfma_f32_16x16x32_bf16 v[56:59], v[148:151], v[164:167], v[56:59]
	v_mfma_f32_16x16x32_bf16 v[52:55], v[156:159], v[164:167], v[52:55]
	v_mfma_f32_16x16x32_bf16 v[40:43], v[148:151], v[172:175], v[40:43]
	v_mfma_f32_16x16x32_bf16 v[36:39], v[156:159], v[172:175], v[36:39]
	v_mfma_f32_16x16x32_bf16 v[24:27], v[148:151], v[180:183], v[24:27]
	v_mfma_f32_16x16x32_bf16 v[20:23], v[156:159], v[180:183], v[20:23]
	v_mfma_f32_16x16x32_bf16 v[8:11], v[148:151], v[188:191], v[8:11]
	v_mfma_f32_16x16x32_bf16 v[4:7], v[156:159], v[188:191], v[4:7]
	v_mfma_f32_16x16x32_bf16 v[56:59], v[152:155], v[168:171], v[56:59]
	v_mfma_f32_16x16x32_bf16 v[52:55], v[160:163], v[168:171], v[52:55]
	v_mfma_f32_16x16x32_bf16 v[40:43], v[152:155], v[176:179], v[40:43]
	v_mfma_f32_16x16x32_bf16 v[36:39], v[160:163], v[176:179], v[36:39]
	v_mfma_f32_16x16x32_bf16 v[24:27], v[152:155], v[184:187], v[24:27]
	v_mfma_f32_16x16x32_bf16 v[20:23], v[160:163], v[184:187], v[20:23]
	v_mfma_f32_16x16x32_bf16 v[8:11], v[152:155], v[192:195], v[8:11]
	v_mfma_f32_16x16x32_bf16 v[4:7], v[160:163], v[192:195], v[4:7]
	s_barrier
	s_setprio 0
	s_add_i32 s11, s11, 2
	s_add_u32 s9, s9, 0x100
	s_addc_u32 s10, s10, 0
	s_add_u32 s38, s38, 0x100
	s_addc_u32 s39, s39, 0
	s_cmp_gt_u32 s11, 13
	s_cbranch_scc0 .LBB0_947
	s_and_b64 vcc, exec, s[46:47]
	s_cbranch_vccz .LBB0_950
	s_barrier

.Lgu_skip1_p:
	s_waitcnt lgkmcnt(0)
	s_setprio 1
	s_barrier
	v_mfma_f32_16x16x32_bf16 v[124:127], v[142:145], v[184:187], 0
	v_mfma_f32_16x16x32_bf16 v[120:123], v[150:153], v[184:187], 0
	v_mfma_f32_16x16x32_bf16 v[112:115], v[142:145], v[192:195], 0
	v_mfma_f32_16x16x32_bf16 v[104:107], v[150:153], v[192:195], 0
	v_mfma_f32_16x16x32_bf16 v[96:99], v[142:145], v[200:203], 0
	v_mfma_f32_16x16x32_bf16 v[88:91], v[150:153], v[200:203], 0
	v_mfma_f32_16x16x32_bf16 v[80:83], v[142:145], v[208:211], 0
	v_mfma_f32_16x16x32_bf16 v[72:75], v[150:153], v[208:211], 0
	v_mfma_f32_16x16x32_bf16 v[124:127], v[146:149], v[188:191], v[124:127]
	v_mfma_f32_16x16x32_bf16 v[120:123], v[154:157], v[188:191], v[120:123]
	v_mfma_f32_16x16x32_bf16 v[112:115], v[146:149], v[196:199], v[112:115]
	v_mfma_f32_16x16x32_bf16 v[104:107], v[154:157], v[196:199], v[104:107]
	v_mfma_f32_16x16x32_bf16 v[96:99], v[146:149], v[204:207], v[96:99]
	v_mfma_f32_16x16x32_bf16 v[88:91], v[154:157], v[204:207], v[88:91]
	v_mfma_f32_16x16x32_bf16 v[80:83], v[146:149], v[212:215], v[80:83]
	v_mfma_f32_16x16x32_bf16 v[72:75], v[154:157], v[212:215], v[72:75]
	v_mfma_f32_16x16x32_bf16 v[128:131], v[168:171], v[184:187], 0
	v_mfma_f32_16x16x32_bf16 v[116:119], v[176:179], v[184:187], 0
	v_mfma_f32_16x16x32_bf16 v[108:111], v[168:171], v[192:195], 0
	v_mfma_f32_16x16x32_bf16 v[100:103], v[176:179], v[192:195], 0
	v_mfma_f32_16x16x32_bf16 v[92:95], v[168:171], v[200:203], 0
	v_mfma_f32_16x16x32_bf16 v[84:87], v[176:179], v[200:203], 0
	v_mfma_f32_16x16x32_bf16 v[76:79], v[168:171], v[208:211], 0
	v_mfma_f32_16x16x32_bf16 v[68:71], v[176:179], v[208:211], 0
	v_mfma_f32_16x16x32_bf16 v[128:131], v[172:175], v[188:191], v[128:131]
	v_mfma_f32_16x16x32_bf16 v[116:119], v[180:183], v[188:191], v[116:119]
	v_mfma_f32_16x16x32_bf16 v[108:111], v[172:175], v[196:199], v[108:111]
	v_mfma_f32_16x16x32_bf16 v[100:103], v[180:183], v[196:199], v[100:103]
	v_mfma_f32_16x16x32_bf16 v[92:95], v[172:175], v[204:207], v[92:95]
	v_mfma_f32_16x16x32_bf16 v[84:87], v[180:183], v[204:207], v[84:87]
	v_mfma_f32_16x16x32_bf16 v[76:79], v[172:175], v[212:215], v[76:79]
	v_mfma_f32_16x16x32_bf16 v[68:71], v[180:183], v[212:215], v[68:71]
	s_barrier
	s_setprio 0
	s_add_i32 s12, s14, s56
	s_mov_b32 m0, s12
	ds_read_b128 v[184:187], v167 offset:16384
	ds_read_b128 v[188:191], v167 offset:17408
	ds_read_b128 v[192:195], v167 offset:18432
	ds_read_b128 v[196:199], v167 offset:19456
	ds_read_b128 v[200:203], v167 offset:20480
	ds_read_b128 v[204:207], v167 offset:21504
	ds_read_b128 v[208:211], v167 offset:22528
	ds_read_b128 v[212:215], v167 offset:23552
	global_load_lds_dwordx4 v2, s[46:47]
	s_add_i32 m0, s12, 0x2000
	s_add_u32 s12, s46, 0x80000
	s_addc_u32 s13, s47, 0
	s_add_i32 s14, s15, s56
	global_load_lds_dwordx4 v0, s[46:47]
	s_mov_b32 m0, s14
	s_nop 0
	global_load_lds_dwordx4 v2, s[12:13]
	s_add_i32 m0, s14, 0x2000
	s_nop 0
	global_load_lds_dwordx4 v0, s[12:13]
	s_mov_b32 m0, s60
	s_nop 0
	global_load_lds_dwordx4 v134, s[48:49]
	s_mov_b32 m0, s61
	s_nop 0
	global_load_lds_dwordx4 v132, s[48:49]
	s_cmp_lg_u32 s32, 0
	s_cbranch_scc1 .Lgu_skip2_p
	s_waitcnt vmcnt(8)
.Lgu_skip2_p:
	s_mov_b32 s32, 0
	s_waitcnt lgkmcnt(0)
	s_setprio 1
	s_barrier
	v_mfma_f32_16x16x32_bf16 v[64:67], v[142:145], v[184:187], 0
	v_mfma_f32_16x16x32_bf16 v[56:59], v[150:153], v[184:187], 0
	v_mfma_f32_16x16x32_bf16 v[48:51], v[142:145], v[192:195], 0
	v_mfma_f32_16x16x32_bf16 v[40:43], v[150:153], v[192:195], 0
	v_mfma_f32_16x16x32_bf16 v[32:35], v[142:145], v[200:203], 0
	v_mfma_f32_16x16x32_bf16 v[24:27], v[150:153], v[200:203], 0
	v_mfma_f32_16x16x32_bf16 v[16:19], v[142:145], v[208:211], 0
	v_mfma_f32_16x16x32_bf16 v[8:11], v[150:153], v[208:211], 0
	v_mfma_f32_16x16x32_bf16 v[64:67], v[146:149], v[188:191], v[64:67]
	v_mfma_f32_16x16x32_bf16 v[56:59], v[154:157], v[188:191], v[56:59]
	v_mfma_f32_16x16x32_bf16 v[48:51], v[146:149], v[196:199], v[48:51]
	v_mfma_f32_16x16x32_bf16 v[40:43], v[154:157], v[196:199], v[40:43]
	v_mfma_f32_16x16x32_bf16 v[32:35], v[146:149], v[204:207], v[32:35]
	v_mfma_f32_16x16x32_bf16 v[24:27], v[154:157], v[204:207], v[24:27]
	v_mfma_f32_16x16x32_bf16 v[16:19], v[146:149], v[212:215], v[16:19]
	v_mfma_f32_16x16x32_bf16 v[8:11], v[154:157], v[212:215], v[8:11]
	v_mfma_f32_16x16x32_bf16 v[60:63], v[168:171], v[184:187], 0
	v_mfma_f32_16x16x32_bf16 v[52:55], v[176:179], v[184:187], 0
	v_mfma_f32_16x16x32_bf16 v[44:47], v[168:171], v[192:195], 0
	v_mfma_f32_16x16x32_bf16 v[36:39], v[176:179], v[192:195], 0
	v_mfma_f32_16x16x32_bf16 v[28:31], v[168:171], v[200:203], 0
	v_mfma_f32_16x16x32_bf16 v[20:23], v[176:179], v[200:203], 0
	v_mfma_f32_16x16x32_bf16 v[12:15], v[168:171], v[208:211], 0
	v_mfma_f32_16x16x32_bf16 v[4:7], v[176:179], v[208:211], 0
	v_mfma_f32_16x16x32_bf16 v[60:63], v[172:175], v[188:191], v[60:63]
	v_mfma_f32_16x16x32_bf16 v[52:55], v[180:183], v[188:191], v[52:55]
	v_mfma_f32_16x16x32_bf16 v[44:47], v[172:175], v[196:199], v[44:47]
	v_mfma_f32_16x16x32_bf16 v[36:39], v[180:183], v[196:199], v[36:39]
	v_mfma_f32_16x16x32_bf16 v[28:31], v[172:175], v[204:207], v[28:31]
	v_mfma_f32_16x16x32_bf16 v[20:23], v[180:183], v[204:207], v[20:23]
	v_mfma_f32_16x16x32_bf16 v[12:15], v[172:175], v[212:215], v[12:15]
	v_mfma_f32_16x16x32_bf16 v[4:7], v[180:183], v[212:215], v[4:7]
	s_barrier
	s_setprio 0
	s_add_i32 s14, 0, 0x18000
	s_add_i32 s15, 0, 0x1c000
	v_add_u32_e32 v154, s14, v163
	v_add_u32_e32 v160, s15, v163
	ds_read_b128 v[142:145], v154
	ds_read_b128 v[146:149], v154 offset:1024
	ds_read_b128 v[150:153], v154 offset:2048
	ds_read_b128 v[154:157], v154 offset:3072
	ds_read_b128 v[168:171], v160
	ds_read_b128 v[172:175], v160 offset:1024
	ds_read_b128 v[176:179], v160 offset:2048
	ds_read_b128 v[180:183], v160 offset:3072
	s_add_u32 s12, s48, 0x80000
	s_addc_u32 s13, s49, 0
	s_mov_b32 m0, s62
	ds_read_b128 v[184:187], v167 offset:32768
	ds_read_b128 v[188:191], v167 offset:33792
	ds_read_b128 v[192:195], v167 offset:34816
	ds_read_b128 v[196:199], v167 offset:35840
	ds_read_b128 v[200:203], v167 offset:36864
	ds_read_b128 v[204:207], v167 offset:37888
	ds_read_b128 v[208:211], v167 offset:38912
	ds_read_b128 v[212:215], v167 offset:39936
	global_load_lds_dwordx4 v134, s[12:13]
	s_mov_b32 m0, s63
	s_nop 0
	global_load_lds_dwordx4 v132, s[12:13]
	s_waitcnt vmcnt(8)
	s_waitcnt lgkmcnt(0)
	s_setprio 1
	s_barrier
	v_mfma_f32_16x16x32_bf16 v[124:127], v[142:145], v[184:187], v[124:127]
	v_mfma_f32_16x16x32_bf16 v[120:123], v[150:153], v[184:187], v[120:123]
	v_mfma_f32_16x16x32_bf16 v[112:115], v[142:145], v[192:195], v[112:115]
	v_mfma_f32_16x16x32_bf16 v[104:107], v[150:153], v[192:195], v[104:107]
	v_mfma_f32_16x16x32_bf16 v[96:99], v[142:145], v[200:203], v[96:99]
	v_mfma_f32_16x16x32_bf16 v[88:91], v[150:153], v[200:203], v[88:91]
	v_mfma_f32_16x16x32_bf16 v[80:83], v[142:145], v[208:211], v[80:83]
	v_mfma_f32_16x16x32_bf16 v[72:75], v[150:153], v[208:211], v[72:75]
	v_mfma_f32_16x16x32_bf16 v[124:127], v[146:149], v[188:191], v[124:127]
	v_mfma_f32_16x16x32_bf16 v[120:123], v[154:157], v[188:191], v[120:123]
	v_mfma_f32_16x16x32_bf16 v[112:115], v[146:149], v[196:199], v[112:115]
	v_mfma_f32_16x16x32_bf16 v[104:107], v[154:157], v[196:199], v[104:107]
	v_mfma_f32_16x16x32_bf16 v[96:99], v[146:149], v[204:207], v[96:99]
	v_mfma_f32_16x16x32_bf16 v[88:91], v[154:157], v[204:207], v[88:91]
	v_mfma_f32_16x16x32_bf16 v[80:83], v[146:149], v[212:215], v[80:83]
	v_mfma_f32_16x16x32_bf16 v[72:75], v[154:157], v[212:215], v[72:75]
	v_mfma_f32_16x16x32_bf16 v[128:131], v[168:171], v[184:187], v[128:131]
	v_mfma_f32_16x16x32_bf16 v[116:119], v[176:179], v[184:187], v[116:119]
	v_mfma_f32_16x16x32_bf16 v[108:111], v[168:171], v[192:195], v[108:111]
	v_mfma_f32_16x16x32_bf16 v[100:103], v[176:179], v[192:195], v[100:103]
	v_mfma_f32_16x16x32_bf16 v[92:95], v[168:171], v[200:203], v[92:95]
	v_mfma_f32_16x16x32_bf16 v[84:87], v[176:179], v[200:203], v[84:87]
	v_mfma_f32_16x16x32_bf16 v[76:79], v[168:171], v[208:211], v[76:79]
	v_mfma_f32_16x16x32_bf16 v[68:71], v[176:179], v[208:211], v[68:71]
	v_mfma_f32_16x16x32_bf16 v[128:131], v[172:175], v[188:191], v[128:131]
	v_mfma_f32_16x16x32_bf16 v[116:119], v[180:183], v[188:191], v[116:119]
	v_mfma_f32_16x16x32_bf16 v[108:111], v[172:175], v[196:199], v[108:111]
	v_mfma_f32_16x16x32_bf16 v[100:103], v[180:183], v[196:199], v[100:103]
	v_mfma_f32_16x16x32_bf16 v[92:95], v[172:175], v[204:207], v[92:95]
	v_mfma_f32_16x16x32_bf16 v[84:87], v[180:183], v[204:207], v[84:87]
	v_mfma_f32_16x16x32_bf16 v[76:79], v[172:175], v[212:215], v[76:79]
	v_mfma_f32_16x16x32_bf16 v[68:71], v[180:183], v[212:215], v[68:71]
	s_barrier
	s_setprio 0
	s_add_i32 s12, s14, s56
	s_mov_b32 m0, s12
	ds_read_b128 v[184:187], v167 offset:49152
	ds_read_b128 v[188:191], v167 offset:50176
	ds_read_b128 v[192:195], v167 offset:51200
	ds_read_b128 v[196:199], v167 offset:52224
	ds_read_b128 v[200:203], v167 offset:53248
	ds_read_b128 v[204:207], v167 offset:54272
	ds_read_b128 v[208:211], v167 offset:55296
	ds_read_b128 v[212:215], v167 offset:56320
	s_add_u32 s100, s46, 0x80
	s_addc_u32 s101, s47, 0
	global_load_lds_dwordx4 v2, s[100:101]
	s_add_i32 m0, s12, 0x2000
	s_add_u32 s12, s46, 0x80080
	s_addc_u32 s13, s47, 0
	s_add_i32 s14, s15, s56
	s_add_u32 s100, s46, 0x80
	s_addc_u32 s101, s47, 0
	global_load_lds_dwordx4 v0, s[100:101]
	s_mov_b32 m0, s14
	s_nop 0
	global_load_lds_dwordx4 v2, s[12:13]
	s_add_i32 m0, s14, 0x2000
	s_nop 0
	global_load_lds_dwordx4 v0, s[12:13]
	s_mov_b32 m0, s64
	s_nop 0
	s_add_u32 s100, s48, 0x80
	s_addc_u32 s101, s49, 0
	global_load_lds_dwordx4 v134, s[100:101]
	s_mov_b32 m0, s65
	s_nop 0
	s_add_u32 s100, s48, 0x80
	s_addc_u32 s101, s49, 0
	global_load_lds_dwordx4 v132, s[100:101]
	s_waitcnt vmcnt(8)
	s_waitcnt lgkmcnt(0)
	s_setprio 1
	s_barrier
	v_mfma_f32_16x16x32_bf16 v[64:67], v[142:145], v[184:187], v[64:67]
	v_mfma_f32_16x16x32_bf16 v[56:59], v[150:153], v[184:187], v[56:59]
	v_mfma_f32_16x16x32_bf16 v[48:51], v[142:145], v[192:195], v[48:51]
	v_mfma_f32_16x16x32_bf16 v[40:43], v[150:153], v[192:195], v[40:43]
	v_mfma_f32_16x16x32_bf16 v[32:35], v[142:145], v[200:203], v[32:35]
	v_mfma_f32_16x16x32_bf16 v[24:27], v[150:153], v[200:203], v[24:27]
	v_mfma_f32_16x16x32_bf16 v[16:19], v[142:145], v[208:211], v[16:19]
	v_mfma_f32_16x16x32_bf16 v[8:11], v[150:153], v[208:211], v[8:11]
	v_mfma_f32_16x16x32_bf16 v[64:67], v[146:149], v[188:191], v[64:67]
	v_mfma_f32_16x16x32_bf16 v[56:59], v[154:157], v[188:191], v[56:59]
	v_mfma_f32_16x16x32_bf16 v[48:51], v[146:149], v[196:199], v[48:51]
	v_mfma_f32_16x16x32_bf16 v[40:43], v[154:157], v[196:199], v[40:43]
	v_mfma_f32_16x16x32_bf16 v[32:35], v[146:149], v[204:207], v[32:35]
	v_mfma_f32_16x16x32_bf16 v[24:27], v[154:157], v[204:207], v[24:27]
	v_mfma_f32_16x16x32_bf16 v[16:19], v[146:149], v[212:215], v[16:19]
	v_mfma_f32_16x16x32_bf16 v[8:11], v[154:157], v[212:215], v[8:11]
	v_mfma_f32_16x16x32_bf16 v[60:63], v[168:171], v[184:187], v[60:63]
	v_mfma_f32_16x16x32_bf16 v[52:55], v[176:179], v[184:187], v[52:55]
	v_mfma_f32_16x16x32_bf16 v[44:47], v[168:171], v[192:195], v[44:47]
	v_mfma_f32_16x16x32_bf16 v[36:39], v[176:179], v[192:195], v[36:39]
	v_mfma_f32_16x16x32_bf16 v[28:31], v[168:171], v[200:203], v[28:31]
	v_mfma_f32_16x16x32_bf16 v[20:23], v[176:179], v[200:203], v[20:23]
	v_mfma_f32_16x16x32_bf16 v[12:15], v[168:171], v[208:211], v[12:15]
	v_mfma_f32_16x16x32_bf16 v[4:7], v[176:179], v[208:211], v[4:7]
	v_mfma_f32_16x16x32_bf16 v[60:63], v[172:175], v[188:191], v[60:63]
	v_mfma_f32_16x16x32_bf16 v[52:55], v[180:183], v[188:191], v[52:55]
	v_mfma_f32_16x16x32_bf16 v[44:47], v[172:175], v[196:199], v[44:47]
	v_mfma_f32_16x16x32_bf16 v[36:39], v[180:183], v[196:199], v[36:39]
	v_mfma_f32_16x16x32_bf16 v[28:31], v[172:175], v[204:207], v[28:31]
	v_mfma_f32_16x16x32_bf16 v[20:23], v[180:183], v[204:207], v[20:23]
	v_mfma_f32_16x16x32_bf16 v[12:15], v[172:175], v[212:215], v[12:15]
	v_mfma_f32_16x16x32_bf16 v[4:7], v[180:183], v[212:215], v[4:7]
	s_barrier
	s_setprio 0
	s_add_i32 s11, s11, 2
	s_add_u32 s9, s9, 0x100
	s_addc_u32 s10, s10, 0
	s_add_u32 s44, s44, 0x100
	s_addc_u32 s45, s45, 0
	s_cmp_gt_u32 s11, 29
.LBB0_1066:
	s_add_u32 s12, s44, 0xfff80080
	s_addc_u32 s13, s45, -1
	s_add_i32 s14, 0, 0x10000
	s_cmp_eq_u32 s11, 28
	s_cselect_b32 s49, s5, s13
	s_cselect_b32 s48, s6, s12
	s_cselect_b32 s47, s7, s10
	s_cselect_b32 s46, s8, s9
	s_add_i32 s15, 0, 0x14000
	v_add_u32_e32 v154, s14, v163
	v_add_u32_e32 v158, s15, v163
	ds_read_b128 v[142:145], v154
	ds_read_b128 v[146:149], v154 offset:1024
	ds_read_b128 v[150:153], v154 offset:2048
	ds_read_b128 v[154:157], v154 offset:3072
	ds_read_b128 v[168:171], v158
	ds_read_b128 v[172:175], v158 offset:1024
	ds_read_b128 v[176:179], v158 offset:2048
	ds_read_b128 v[180:183], v158 offset:3072
	s_add_i32 m0, s60, 0xc000
	ds_read_b128 v[184:187], v167
	ds_read_b128 v[188:191], v167 offset:1024
	ds_read_b128 v[192:195], v167 offset:2048
	ds_read_b128 v[196:199], v167 offset:3072
	ds_read_b128 v[200:203], v167 offset:4096
	ds_read_b128 v[204:207], v167 offset:5120
	ds_read_b128 v[208:211], v167 offset:6144
	ds_read_b128 v[212:215], v167 offset:7168
	global_load_lds_dwordx4 v140, s[44:45]
	s_add_i32 m0, s60, 0xe000
	s_nop 0
	global_load_lds_dwordx4 v138, s[44:45]
	s_waitcnt vmcnt(8)
	s_waitcnt lgkmcnt(0)
	s_setprio 1
	s_barrier
	v_mfma_f32_16x16x32_bf16 v[124:127], v[142:145], v[184:187], v[124:127]
	v_mfma_f32_16x16x32_bf16 v[120:123], v[150:153], v[184:187], v[120:123]
	v_mfma_f32_16x16x32_bf16 v[112:115], v[142:145], v[192:195], v[112:115]
	v_mfma_f32_16x16x32_bf16 v[104:107], v[150:153], v[192:195], v[104:107]
	v_mfma_f32_16x16x32_bf16 v[96:99], v[142:145], v[200:203], v[96:99]
	v_mfma_f32_16x16x32_bf16 v[88:91], v[150:153], v[200:203], v[88:91]
	v_mfma_f32_16x16x32_bf16 v[80:83], v[142:145], v[208:211], v[80:83]
	v_mfma_f32_16x16x32_bf16 v[72:75], v[150:153], v[208:211], v[72:75]
	v_mfma_f32_16x16x32_bf16 v[124:127], v[146:149], v[188:191], v[124:127]
	v_mfma_f32_16x16x32_bf16 v[120:123], v[154:157], v[188:191], v[120:123]
	v_mfma_f32_16x16x32_bf16 v[112:115], v[146:149], v[196:199], v[112:115]
	v_mfma_f32_16x16x32_bf16 v[104:107], v[154:157], v[196:199], v[104:107]
	v_mfma_f32_16x16x32_bf16 v[96:99], v[146:149], v[204:207], v[96:99]
	v_mfma_f32_16x16x32_bf16 v[88:91], v[154:157], v[204:207], v[88:91]
	v_mfma_f32_16x16x32_bf16 v[80:83], v[146:149], v[212:215], v[80:83]
	v_mfma_f32_16x16x32_bf16 v[72:75], v[154:157], v[212:215], v[72:75]
	v_mfma_f32_16x16x32_bf16 v[128:131], v[168:171], v[184:187], v[128:131]
	v_mfma_f32_16x16x32_bf16 v[116:119], v[176:179], v[184:187], v[116:119]
	v_mfma_f32_16x16x32_bf16 v[108:111], v[168:171], v[192:195], v[108:111]
	v_mfma_f32_16x16x32_bf16 v[100:103], v[176:179], v[192:195], v[100:103]
	v_mfma_f32_16x16x32_bf16 v[92:95], v[168:171], v[200:203], v[92:95]
	v_mfma_f32_16x16x32_bf16 v[84:87], v[176:179], v[200:203], v[84:87]
	v_mfma_f32_16x16x32_bf16 v[76:79], v[168:171], v[208:211], v[76:79]
	v_mfma_f32_16x16x32_bf16 v[68:71], v[176:179], v[208:211], v[68:71]
	v_mfma_f32_16x16x32_bf16 v[128:131], v[172:175], v[188:191], v[128:131]
	v_mfma_f32_16x16x32_bf16 v[116:119], v[180:183], v[188:191], v[116:119]
	v_mfma_f32_16x16x32_bf16 v[108:111], v[172:175], v[196:199], v[108:111]
	v_mfma_f32_16x16x32_bf16 v[100:103], v[180:183], v[196:199], v[100:103]
	v_mfma_f32_16x16x32_bf16 v[92:95], v[172:175], v[204:207], v[92:95]
	v_mfma_f32_16x16x32_bf16 v[84:87], v[180:183], v[204:207], v[84:87]
	v_mfma_f32_16x16x32_bf16 v[76:79], v[172:175], v[212:215], v[76:79]
	v_mfma_f32_16x16x32_bf16 v[68:71], v[180:183], v[212:215], v[68:71]
	s_barrier
	s_setprio 0
	s_add_i32 s12, s14, s56
	s_mov_b32 m0, s12
	ds_read_b128 v[184:187], v167 offset:16384
	ds_read_b128 v[188:191], v167 offset:17408
	ds_read_b128 v[192:195], v167 offset:18432
	ds_read_b128 v[196:199], v167 offset:19456
	ds_read_b128 v[200:203], v167 offset:20480
	ds_read_b128 v[204:207], v167 offset:21504
	ds_read_b128 v[208:211], v167 offset:22528
	ds_read_b128 v[212:215], v167 offset:23552
	global_load_lds_dwordx4 v2, s[46:47]
	s_add_i32 m0, s12, 0x2000
	s_add_u32 s12, s46, 0x80000
	s_addc_u32 s13, s47, 0
	s_add_i32 s14, s15, s56
	global_load_lds_dwordx4 v0, s[46:47]
	s_mov_b32 m0, s14
	s_nop 0
	global_load_lds_dwordx4 v2, s[12:13]
	s_add_i32 m0, s14, 0x2000
	s_nop 0
	global_load_lds_dwordx4 v0, s[12:13]
	s_mov_b32 m0, s60
	s_nop 0
	global_load_lds_dwordx4 v134, s[48:49]
	s_mov_b32 m0, s61
	s_nop 0
	global_load_lds_dwordx4 v132, s[48:49]
	s_waitcnt vmcnt(8)
	s_waitcnt lgkmcnt(0)
	s_setprio 1
	s_barrier
	v_mfma_f32_16x16x32_bf16 v[64:67], v[142:145], v[184:187], v[64:67]
	v_mfma_f32_16x16x32_bf16 v[56:59], v[150:153], v[184:187], v[56:59]
	v_mfma_f32_16x16x32_bf16 v[48:51], v[142:145], v[192:195], v[48:51]
	v_mfma_f32_16x16x32_bf16 v[40:43], v[150:153], v[192:195], v[40:43]
	v_mfma_f32_16x16x32_bf16 v[32:35], v[142:145], v[200:203], v[32:35]
	v_mfma_f32_16x16x32_bf16 v[24:27], v[150:153], v[200:203], v[24:27]
	v_mfma_f32_16x16x32_bf16 v[16:19], v[142:145], v[208:211], v[16:19]
	v_mfma_f32_16x16x32_bf16 v[8:11], v[150:153], v[208:211], v[8:11]
	v_mfma_f32_16x16x32_bf16 v[64:67], v[146:149], v[188:191], v[64:67]
	v_mfma_f32_16x16x32_bf16 v[56:59], v[154:157], v[188:191], v[56:59]
	v_mfma_f32_16x16x32_bf16 v[48:51], v[146:149], v[196:199], v[48:51]
	v_mfma_f32_16x16x32_bf16 v[40:43], v[154:157], v[196:199], v[40:43]
	v_mfma_f32_16x16x32_bf16 v[32:35], v[146:149], v[204:207], v[32:35]
	v_mfma_f32_16x16x32_bf16 v[24:27], v[154:157], v[204:207], v[24:27]
	v_mfma_f32_16x16x32_bf16 v[16:19], v[146:149], v[212:215], v[16:19]
	v_mfma_f32_16x16x32_bf16 v[8:11], v[154:157], v[212:215], v[8:11]
	v_mfma_f32_16x16x32_bf16 v[60:63], v[168:171], v[184:187], v[60:63]
	v_mfma_f32_16x16x32_bf16 v[52:55], v[176:179], v[184:187], v[52:55]
	v_mfma_f32_16x16x32_bf16 v[44:47], v[168:171], v[192:195], v[44:47]
	v_mfma_f32_16x16x32_bf16 v[36:39], v[176:179], v[192:195], v[36:39]
	v_mfma_f32_16x16x32_bf16 v[28:31], v[168:171], v[200:203], v[28:31]
	v_mfma_f32_16x16x32_bf16 v[20:23], v[176:179], v[200:203], v[20:23]
	v_mfma_f32_16x16x32_bf16 v[12:15], v[168:171], v[208:211], v[12:15]
	v_mfma_f32_16x16x32_bf16 v[4:7], v[176:179], v[208:211], v[4:7]
	v_mfma_f32_16x16x32_bf16 v[60:63], v[172:175], v[188:191], v[60:63]
	v_mfma_f32_16x16x32_bf16 v[52:55], v[180:183], v[188:191], v[52:55]
	v_mfma_f32_16x16x32_bf16 v[44:47], v[172:175], v[196:199], v[44:47]
	v_mfma_f32_16x16x32_bf16 v[36:39], v[180:183], v[196:199], v[36:39]
	v_mfma_f32_16x16x32_bf16 v[28:31], v[172:175], v[204:207], v[28:31]
	v_mfma_f32_16x16x32_bf16 v[20:23], v[180:183], v[204:207], v[20:23]
	v_mfma_f32_16x16x32_bf16 v[12:15], v[172:175], v[212:215], v[12:15]
	v_mfma_f32_16x16x32_bf16 v[4:7], v[180:183], v[212:215], v[4:7]
	s_barrier
	s_setprio 0
	s_add_i32 s14, 0, 0x18000
	s_add_i32 s15, 0, 0x1c000
	v_add_u32_e32 v154, s14, v163
	v_add_u32_e32 v160, s15, v163
	ds_read_b128 v[142:145], v154
	ds_read_b128 v[146:149], v154 offset:1024
	ds_read_b128 v[150:153], v154 offset:2048
	ds_read_b128 v[154:157], v154 offset:3072
	ds_read_b128 v[168:171], v160
	ds_read_b128 v[172:175], v160 offset:1024
	ds_read_b128 v[176:179], v160 offset:2048
	ds_read_b128 v[180:183], v160 offset:3072
	s_add_u32 s12, s48, 0x80000
	s_addc_u32 s13, s49, 0
	s_mov_b32 m0, s62
	ds_read_b128 v[184:187], v167 offset:32768
	ds_read_b128 v[188:191], v167 offset:33792
	ds_read_b128 v[192:195], v167 offset:34816
	ds_read_b128 v[196:199], v167 offset:35840
	ds_read_b128 v[200:203], v167 offset:36864
	ds_read_b128 v[204:207], v167 offset:37888
	ds_read_b128 v[208:211], v167 offset:38912
	ds_read_b128 v[212:215], v167 offset:39936
	global_load_lds_dwordx4 v134, s[12:13]
	s_mov_b32 m0, s63
	s_nop 0
	global_load_lds_dwordx4 v132, s[12:13]
	s_waitcnt vmcnt(8)
	s_waitcnt lgkmcnt(0)
	s_setprio 1
	s_barrier
	v_mfma_f32_16x16x32_bf16 v[124:127], v[142:145], v[184:187], v[124:127]
	v_mfma_f32_16x16x32_bf16 v[120:123], v[150:153], v[184:187], v[120:123]
	v_mfma_f32_16x16x32_bf16 v[112:115], v[142:145], v[192:195], v[112:115]
	v_mfma_f32_16x16x32_bf16 v[104:107], v[150:153], v[192:195], v[104:107]
	v_mfma_f32_16x16x32_bf16 v[96:99], v[142:145], v[200:203], v[96:99]
	v_mfma_f32_16x16x32_bf16 v[88:91], v[150:153], v[200:203], v[88:91]
	v_mfma_f32_16x16x32_bf16 v[80:83], v[142:145], v[208:211], v[80:83]
	v_mfma_f32_16x16x32_bf16 v[72:75], v[150:153], v[208:211], v[72:75]
	v_mfma_f32_16x16x32_bf16 v[124:127], v[146:149], v[188:191], v[124:127]
	v_mfma_f32_16x16x32_bf16 v[120:123], v[154:157], v[188:191], v[120:123]
	v_mfma_f32_16x16x32_bf16 v[112:115], v[146:149], v[196:199], v[112:115]
	v_mfma_f32_16x16x32_bf16 v[104:107], v[154:157], v[196:199], v[104:107]
	v_mfma_f32_16x16x32_bf16 v[96:99], v[146:149], v[204:207], v[96:99]
	v_mfma_f32_16x16x32_bf16 v[88:91], v[154:157], v[204:207], v[88:91]
	v_mfma_f32_16x16x32_bf16 v[80:83], v[146:149], v[212:215], v[80:83]
	v_mfma_f32_16x16x32_bf16 v[72:75], v[154:157], v[212:215], v[72:75]
	v_mfma_f32_16x16x32_bf16 v[128:131], v[168:171], v[184:187], v[128:131]
	v_mfma_f32_16x16x32_bf16 v[116:119], v[176:179], v[184:187], v[116:119]
	v_mfma_f32_16x16x32_bf16 v[108:111], v[168:171], v[192:195], v[108:111]
	v_mfma_f32_16x16x32_bf16 v[100:103], v[176:179], v[192:195], v[100:103]
	v_mfma_f32_16x16x32_bf16 v[92:95], v[168:171], v[200:203], v[92:95]
	v_mfma_f32_16x16x32_bf16 v[84:87], v[176:179], v[200:203], v[84:87]
	v_mfma_f32_16x16x32_bf16 v[76:79], v[168:171], v[208:211], v[76:79]
	v_mfma_f32_16x16x32_bf16 v[68:71], v[176:179], v[208:211], v[68:71]
	v_mfma_f32_16x16x32_bf16 v[128:131], v[172:175], v[188:191], v[128:131]
	v_mfma_f32_16x16x32_bf16 v[116:119], v[180:183], v[188:191], v[116:119]
	v_mfma_f32_16x16x32_bf16 v[108:111], v[172:175], v[196:199], v[108:111]
	v_mfma_f32_16x16x32_bf16 v[100:103], v[180:183], v[196:199], v[100:103]
	v_mfma_f32_16x16x32_bf16 v[92:95], v[172:175], v[204:207], v[92:95]
	v_mfma_f32_16x16x32_bf16 v[84:87], v[180:183], v[204:207], v[84:87]
	v_mfma_f32_16x16x32_bf16 v[76:79], v[172:175], v[212:215], v[76:79]
	v_mfma_f32_16x16x32_bf16 v[68:71], v[180:183], v[212:215], v[68:71]
	s_barrier
	s_setprio 0
	s_add_i32 s12, s14, s56
	s_mov_b32 m0, s12
	ds_read_b128 v[184:187], v167 offset:49152
	ds_read_b128 v[188:191], v167 offset:50176
	ds_read_b128 v[192:195], v167 offset:51200
	ds_read_b128 v[196:199], v167 offset:52224
	ds_read_b128 v[200:203], v167 offset:53248
	ds_read_b128 v[204:207], v167 offset:54272
	ds_read_b128 v[208:211], v167 offset:55296
	ds_read_b128 v[212:215], v167 offset:56320
	s_add_u32 s100, s46, 0x80
	s_addc_u32 s101, s47, 0
	global_load_lds_dwordx4 v2, s[100:101]
	s_add_i32 m0, s12, 0x2000
	s_add_u32 s12, s46, 0x80080
	s_addc_u32 s13, s47, 0
	s_add_i32 s14, s15, s56
	s_add_u32 s100, s46, 0x80
	s_addc_u32 s101, s47, 0
	global_load_lds_dwordx4 v0, s[100:101]
	s_mov_b32 m0, s14
	s_nop 0
	global_load_lds_dwordx4 v2, s[12:13]
	s_add_i32 m0, s14, 0x2000
	s_nop 0
	global_load_lds_dwordx4 v0, s[12:13]
	s_mov_b32 m0, s64
	s_nop 0
	s_add_u32 s100, s48, 0x80
	s_addc_u32 s101, s49, 0
	global_load_lds_dwordx4 v134, s[100:101]
	s_mov_b32 m0, s65
	s_nop 0
	s_add_u32 s100, s48, 0x80
	s_addc_u32 s101, s49, 0
	global_load_lds_dwordx4 v132, s[100:101]
	s_waitcnt vmcnt(8)
	s_waitcnt lgkmcnt(0)
	s_setprio 1
	s_barrier
	v_mfma_f32_16x16x32_bf16 v[64:67], v[142:145], v[184:187], v[64:67]
	v_mfma_f32_16x16x32_bf16 v[56:59], v[150:153], v[184:187], v[56:59]
	v_mfma_f32_16x16x32_bf16 v[48:51], v[142:145], v[192:195], v[48:51]
	v_mfma_f32_16x16x32_bf16 v[40:43], v[150:153], v[192:195], v[40:43]
	v_mfma_f32_16x16x32_bf16 v[32:35], v[142:145], v[200:203], v[32:35]
	v_mfma_f32_16x16x32_bf16 v[24:27], v[150:153], v[200:203], v[24:27]
	v_mfma_f32_16x16x32_bf16 v[16:19], v[142:145], v[208:211], v[16:19]
	v_mfma_f32_16x16x32_bf16 v[8:11], v[150:153], v[208:211], v[8:11]
	v_mfma_f32_16x16x32_bf16 v[64:67], v[146:149], v[188:191], v[64:67]
	v_mfma_f32_16x16x32_bf16 v[56:59], v[154:157], v[188:191], v[56:59]
	v_mfma_f32_16x16x32_bf16 v[48:51], v[146:149], v[196:199], v[48:51]
	v_mfma_f32_16x16x32_bf16 v[40:43], v[154:157], v[196:199], v[40:43]
	v_mfma_f32_16x16x32_bf16 v[32:35], v[146:149], v[204:207], v[32:35]
	v_mfma_f32_16x16x32_bf16 v[24:27], v[154:157], v[204:207], v[24:27]
	v_mfma_f32_16x16x32_bf16 v[16:19], v[146:149], v[212:215], v[16:19]
	v_mfma_f32_16x16x32_bf16 v[8:11], v[154:157], v[212:215], v[8:11]
	v_mfma_f32_16x16x32_bf16 v[60:63], v[168:171], v[184:187], v[60:63]
	v_mfma_f32_16x16x32_bf16 v[52:55], v[176:179], v[184:187], v[52:55]
	v_mfma_f32_16x16x32_bf16 v[44:47], v[168:171], v[192:195], v[44:47]
	v_mfma_f32_16x16x32_bf16 v[36:39], v[176:179], v[192:195], v[36:39]
	v_mfma_f32_16x16x32_bf16 v[28:31], v[168:171], v[200:203], v[28:31]
	v_mfma_f32_16x16x32_bf16 v[20:23], v[176:179], v[200:203], v[20:23]
	v_mfma_f32_16x16x32_bf16 v[12:15], v[168:171], v[208:211], v[12:15]
	v_mfma_f32_16x16x32_bf16 v[4:7], v[176:179], v[208:211], v[4:7]
	v_mfma_f32_16x16x32_bf16 v[60:63], v[172:175], v[188:191], v[60:63]
	v_mfma_f32_16x16x32_bf16 v[52:55], v[180:183], v[188:191], v[52:55]
	v_mfma_f32_16x16x32_bf16 v[44:47], v[172:175], v[196:199], v[44:47]
	v_mfma_f32_16x16x32_bf16 v[36:39], v[180:183], v[196:199], v[36:39]
	v_mfma_f32_16x16x32_bf16 v[28:31], v[172:175], v[204:207], v[28:31]
	v_mfma_f32_16x16x32_bf16 v[20:23], v[180:183], v[204:207], v[20:23]
	v_mfma_f32_16x16x32_bf16 v[12:15], v[172:175], v[212:215], v[12:15]
	v_mfma_f32_16x16x32_bf16 v[4:7], v[180:183], v[212:215], v[4:7]
	s_barrier
	s_setprio 0
	s_add_i32 s11, s11, 2
	s_add_u32 s9, s9, 0x100
	s_addc_u32 s10, s10, 0
	s_add_u32 s44, s44, 0x100
	s_addc_u32 s45, s45, 0
	s_cmp_gt_u32 s11, 29
	s_cbranch_scc0 .LBB0_1066
	s_and_b64 vcc, exec, s[22:23]
	s_cbranch_vccz .LBB0_1069
	s_nop 0

.LBB0_1133:
	s_add_u32 s5, s40, 0x100
	s_addc_u32 s6, s41, 0
	s_mov_b32 s7, -2
	s_waitcnt lgkmcnt(0)
	s_add_u32 s40, s38, 0x100
	s_addc_u32 s41, s39, 0
	s_add_i32 s8, 0, 0x10000
	s_cmpk_eq_i32 s7, 0x54
	s_cselect_b32 s45, s61, s41
	s_cselect_b32 s44, s60, s40
	s_cselect_b32 s43, s63, s6
	s_cselect_b32 s42, s62, s5
	s_add_i32 s10, 0, 0x14000
	v_add_u32_e32 v112, s8, v242
	v_add_u32_e32 v148, s10, v242
	ds_read_b128 v[92:95], v112
	ds_read_b128 v[100:103], v112 offset:1024
	ds_read_b128 v[108:111], v112 offset:2048
	ds_read_b128 v[112:115], v112 offset:3072
	ds_read_b128 v[116:119], v148
	ds_read_b128 v[128:131], v148 offset:1024
	ds_read_b128 v[140:143], v148 offset:2048
	ds_read_b128 v[148:151], v148 offset:3072
	v_lshl_add_u64 v[196:197], s[38:39], 0, v[222:223]
	s_add_i32 m0, s83, 0xc000
	ds_read_b128 v[160:163], v245
	ds_read_b128 v[168:171], v245 offset:1024
	ds_read_b128 v[172:175], v245 offset:2048
	ds_read_b128 v[176:179], v245 offset:3072
	ds_read_b128 v[180:183], v245 offset:4096
	ds_read_b128 v[184:187], v245 offset:5120
	ds_read_b128 v[188:191], v245 offset:6144
	ds_read_b128 v[192:195], v245 offset:7168
	global_load_lds_dwordx4 v[196:197], off
	v_lshl_add_u64 v[196:197], s[38:39], 0, v[220:221]
	s_add_i32 m0, s83, 0xe000
	s_nop 0
	global_load_lds_dwordx4 v[196:197], off
	s_waitcnt vmcnt(8)
	s_waitcnt lgkmcnt(0)
	s_setprio 1
	s_barrier
	v_mfma_f32_16x16x32_bf16 v[164:167], v[92:95], v[160:163], 0
	v_mfma_f32_16x16x32_bf16 v[156:159], v[108:111], v[160:163], 0
	v_mfma_f32_16x16x32_bf16 v[136:139], v[92:95], v[172:175], 0
	v_mfma_f32_16x16x32_bf16 v[132:135], v[108:111], v[172:175], 0
	v_mfma_f32_16x16x32_bf16 v[104:107], v[92:95], v[180:183], 0
	v_mfma_f32_16x16x32_bf16 v[96:99], v[108:111], v[180:183], 0
	v_mfma_f32_16x16x32_bf16 v[80:83], v[92:95], v[188:191], 0
	v_mfma_f32_16x16x32_bf16 v[76:79], v[108:111], v[188:191], 0
	v_mfma_f32_16x16x32_bf16 v[164:167], v[100:103], v[168:171], v[164:167]
	v_mfma_f32_16x16x32_bf16 v[156:159], v[112:115], v[168:171], v[156:159]
	v_mfma_f32_16x16x32_bf16 v[136:139], v[100:103], v[176:179], v[136:139]
	v_mfma_f32_16x16x32_bf16 v[132:135], v[112:115], v[176:179], v[132:135]
	v_mfma_f32_16x16x32_bf16 v[104:107], v[100:103], v[184:187], v[104:107]
	v_mfma_f32_16x16x32_bf16 v[96:99], v[112:115], v[184:187], v[96:99]
	v_mfma_f32_16x16x32_bf16 v[80:83], v[100:103], v[192:195], v[80:83]
	v_mfma_f32_16x16x32_bf16 v[76:79], v[112:115], v[192:195], v[76:79]
	s_setprio 0
	s_setprio 1
	v_mfma_f32_16x16x32_bf16 v[152:155], v[116:119], v[160:163], 0
	v_mfma_f32_16x16x32_bf16 v[144:147], v[140:143], v[160:163], 0
	v_mfma_f32_16x16x32_bf16 v[124:127], v[116:119], v[172:175], 0
	v_mfma_f32_16x16x32_bf16 v[120:123], v[140:143], v[172:175], 0
	v_mfma_f32_16x16x32_bf16 v[88:91], v[116:119], v[180:183], 0
	v_mfma_f32_16x16x32_bf16 v[84:87], v[140:143], v[180:183], 0
	v_mfma_f32_16x16x32_bf16 v[72:75], v[116:119], v[188:191], 0
	v_mfma_f32_16x16x32_bf16 v[68:71], v[140:143], v[188:191], 0
	v_mfma_f32_16x16x32_bf16 v[152:155], v[128:131], v[168:171], v[152:155]
	v_mfma_f32_16x16x32_bf16 v[144:147], v[148:151], v[168:171], v[144:147]
	v_mfma_f32_16x16x32_bf16 v[124:127], v[128:131], v[176:179], v[124:127]
	v_mfma_f32_16x16x32_bf16 v[120:123], v[148:151], v[176:179], v[120:123]
	v_mfma_f32_16x16x32_bf16 v[88:91], v[128:131], v[184:187], v[88:91]
	v_mfma_f32_16x16x32_bf16 v[84:87], v[148:151], v[184:187], v[84:87]
	v_mfma_f32_16x16x32_bf16 v[72:75], v[128:131], v[192:195], v[72:75]
	v_mfma_f32_16x16x32_bf16 v[68:71], v[148:151], v[192:195], v[68:71]
	s_barrier
	s_setprio 0
	s_add_i32 s8, s8, s82
	v_lshl_add_u64 v[196:197], s[42:43], 0, v[2:3]
	s_mov_b32 m0, s8
	ds_read_b128 v[160:163], v245 offset:16384
	ds_read_b128 v[168:171], v245 offset:17408
	ds_read_b128 v[172:175], v245 offset:18432
	ds_read_b128 v[176:179], v245 offset:19456
	ds_read_b128 v[180:183], v245 offset:20480
	ds_read_b128 v[184:187], v245 offset:21504
	ds_read_b128 v[188:191], v245 offset:22528
	ds_read_b128 v[192:195], v245 offset:23552
	global_load_lds_dwordx4 v[196:197], off
	s_add_i32 m0, s8, 0x2000
	s_add_u32 s8, s42, 0x160000
	v_lshl_add_u64 v[198:199], s[42:43], 0, v[218:219]
	s_addc_u32 s9, s43, 0
	s_add_i32 s10, s10, s82
	global_load_lds_dwordx4 v[198:199], off
	v_lshl_add_u64 v[200:201], s[8:9], 0, v[2:3]
	s_mov_b32 m0, s10
	v_lshl_add_u64 v[202:203], s[44:45], 0, v[216:217]
	global_load_lds_dwordx4 v[200:201], off
	v_lshl_add_u64 v[200:201], s[8:9], 0, v[218:219]
	s_add_i32 m0, s10, 0x2000
	s_nop 0
	global_load_lds_dwordx4 v[200:201], off
	v_lshl_add_u64 v[200:201], s[44:45], 0, v[0:1]
	s_mov_b32 m0, s83
	s_nop 0
	global_load_lds_dwordx4 v[200:201], off
	s_mov_b32 m0, s84
	s_nop 0
	global_load_lds_dwordx4 v[202:203], off
	s_waitcnt vmcnt(8)
	s_waitcnt lgkmcnt(0)
	s_setprio 1
	s_barrier
	v_mfma_f32_16x16x32_bf16 v[64:67], v[92:95], v[160:163], 0
	v_mfma_f32_16x16x32_bf16 v[60:63], v[108:111], v[160:163], 0
	v_mfma_f32_16x16x32_bf16 v[48:51], v[92:95], v[172:175], 0
	v_mfma_f32_16x16x32_bf16 v[44:47], v[108:111], v[172:175], 0
	v_mfma_f32_16x16x32_bf16 v[32:35], v[92:95], v[180:183], 0
	v_mfma_f32_16x16x32_bf16 v[28:31], v[108:111], v[180:183], 0
	v_mfma_f32_16x16x32_bf16 v[16:19], v[92:95], v[188:191], 0
	v_mfma_f32_16x16x32_bf16 v[12:15], v[108:111], v[188:191], 0
	v_mfma_f32_16x16x32_bf16 v[64:67], v[100:103], v[168:171], v[64:67]
	v_mfma_f32_16x16x32_bf16 v[60:63], v[112:115], v[168:171], v[60:63]
	v_mfma_f32_16x16x32_bf16 v[48:51], v[100:103], v[176:179], v[48:51]
	v_mfma_f32_16x16x32_bf16 v[44:47], v[112:115], v[176:179], v[44:47]
	v_mfma_f32_16x16x32_bf16 v[32:35], v[100:103], v[184:187], v[32:35]
	v_mfma_f32_16x16x32_bf16 v[28:31], v[112:115], v[184:187], v[28:31]
	v_mfma_f32_16x16x32_bf16 v[16:19], v[100:103], v[192:195], v[16:19]
	v_mfma_f32_16x16x32_bf16 v[12:15], v[112:115], v[192:195], v[12:15]
	s_setprio 0
	s_setprio 1
	v_mfma_f32_16x16x32_bf16 v[56:59], v[116:119], v[160:163], 0
	v_mfma_f32_16x16x32_bf16 v[52:55], v[140:143], v[160:163], 0
	v_mfma_f32_16x16x32_bf16 v[40:43], v[116:119], v[172:175], 0
	v_mfma_f32_16x16x32_bf16 v[36:39], v[140:143], v[172:175], 0
	v_mfma_f32_16x16x32_bf16 v[24:27], v[116:119], v[180:183], 0
	v_mfma_f32_16x16x32_bf16 v[20:23], v[140:143], v[180:183], 0
	v_mfma_f32_16x16x32_bf16 v[8:11], v[116:119], v[188:191], 0
	v_mfma_f32_16x16x32_bf16 v[4:7], v[140:143], v[188:191], 0
	v_mfma_f32_16x16x32_bf16 v[56:59], v[128:131], v[168:171], v[56:59]
	v_mfma_f32_16x16x32_bf16 v[52:55], v[148:151], v[168:171], v[52:55]
	v_mfma_f32_16x16x32_bf16 v[40:43], v[128:131], v[176:179], v[40:43]
	v_mfma_f32_16x16x32_bf16 v[36:39], v[148:151], v[176:179], v[36:39]
	v_mfma_f32_16x16x32_bf16 v[24:27], v[128:131], v[184:187], v[24:27]
	v_mfma_f32_16x16x32_bf16 v[20:23], v[148:151], v[184:187], v[20:23]
	v_mfma_f32_16x16x32_bf16 v[8:11], v[128:131], v[192:195], v[8:11]
	v_mfma_f32_16x16x32_bf16 v[4:7], v[148:151], v[192:195], v[4:7]
	s_barrier
	s_setprio 0
	s_add_i32 s10, 0, 0x18000
	s_add_i32 s11, 0, 0x1c000
	v_add_u32_e32 v112, s10, v242
	v_add_u32_e32 v148, s11, v242
	ds_read_b128 v[92:95], v112
	ds_read_b128 v[100:103], v112 offset:1024
	ds_read_b128 v[108:111], v112 offset:2048
	ds_read_b128 v[112:115], v112 offset:3072
	ds_read_b128 v[116:119], v148
	ds_read_b128 v[128:131], v148 offset:1024
	ds_read_b128 v[140:143], v148 offset:2048
	ds_read_b128 v[148:151], v148 offset:3072
	s_add_u32 s8, s44, 0x160000
	s_addc_u32 s9, s45, 0
	s_mov_b32 m0, s85
	v_lshl_add_u64 v[204:205], s[8:9], 0, v[0:1]
	ds_read_b128 v[160:163], v245 offset:32768
	ds_read_b128 v[168:171], v245 offset:33792
	ds_read_b128 v[172:175], v245 offset:34816
	ds_read_b128 v[176:179], v245 offset:35840
	ds_read_b128 v[180:183], v245 offset:36864
	ds_read_b128 v[184:187], v245 offset:37888
	ds_read_b128 v[188:191], v245 offset:38912
	ds_read_b128 v[192:195], v245 offset:39936
	global_load_lds_dwordx4 v[204:205], off
	v_lshl_add_u64 v[204:205], s[8:9], 0, v[216:217]
	s_mov_b32 m0, s87
	s_nop 0
	global_load_lds_dwordx4 v[204:205], off
	s_waitcnt vmcnt(8)
	s_waitcnt lgkmcnt(0)
	s_setprio 1
	s_barrier
	v_mfma_f32_16x16x32_bf16 v[164:167], v[92:95], v[160:163], v[164:167]
	v_mfma_f32_16x16x32_bf16 v[156:159], v[108:111], v[160:163], v[156:159]
	v_mfma_f32_16x16x32_bf16 v[136:139], v[92:95], v[172:175], v[136:139]
	v_mfma_f32_16x16x32_bf16 v[132:135], v[108:111], v[172:175], v[132:135]
	v_mfma_f32_16x16x32_bf16 v[104:107], v[92:95], v[180:183], v[104:107]
	v_mfma_f32_16x16x32_bf16 v[96:99], v[108:111], v[180:183], v[96:99]
	v_mfma_f32_16x16x32_bf16 v[80:83], v[92:95], v[188:191], v[80:83]
	v_mfma_f32_16x16x32_bf16 v[76:79], v[108:111], v[188:191], v[76:79]
	v_mfma_f32_16x16x32_bf16 v[164:167], v[100:103], v[168:171], v[164:167]
	v_mfma_f32_16x16x32_bf16 v[156:159], v[112:115], v[168:171], v[156:159]
	v_mfma_f32_16x16x32_bf16 v[136:139], v[100:103], v[176:179], v[136:139]
	v_mfma_f32_16x16x32_bf16 v[132:135], v[112:115], v[176:179], v[132:135]
	v_mfma_f32_16x16x32_bf16 v[104:107], v[100:103], v[184:187], v[104:107]
	v_mfma_f32_16x16x32_bf16 v[96:99], v[112:115], v[184:187], v[96:99]
	v_mfma_f32_16x16x32_bf16 v[80:83], v[100:103], v[192:195], v[80:83]
	v_mfma_f32_16x16x32_bf16 v[76:79], v[112:115], v[192:195], v[76:79]
	s_setprio 0
	s_setprio 1
	v_mfma_f32_16x16x32_bf16 v[152:155], v[116:119], v[160:163], v[152:155]
	v_mfma_f32_16x16x32_bf16 v[144:147], v[140:143], v[160:163], v[144:147]
	v_mfma_f32_16x16x32_bf16 v[124:127], v[116:119], v[172:175], v[124:127]
	v_mfma_f32_16x16x32_bf16 v[120:123], v[140:143], v[172:175], v[120:123]
	v_mfma_f32_16x16x32_bf16 v[88:91], v[116:119], v[180:183], v[88:91]
	v_mfma_f32_16x16x32_bf16 v[84:87], v[140:143], v[180:183], v[84:87]
	v_mfma_f32_16x16x32_bf16 v[72:75], v[116:119], v[188:191], v[72:75]
	v_mfma_f32_16x16x32_bf16 v[68:71], v[140:143], v[188:191], v[68:71]
	v_mfma_f32_16x16x32_bf16 v[152:155], v[128:131], v[168:171], v[152:155]
	v_mfma_f32_16x16x32_bf16 v[144:147], v[148:151], v[168:171], v[144:147]
	v_mfma_f32_16x16x32_bf16 v[124:127], v[128:131], v[176:179], v[124:127]
	v_mfma_f32_16x16x32_bf16 v[120:123], v[148:151], v[176:179], v[120:123]
	v_mfma_f32_16x16x32_bf16 v[88:91], v[128:131], v[184:187], v[88:91]
	v_mfma_f32_16x16x32_bf16 v[84:87], v[148:151], v[184:187], v[84:87]
	v_mfma_f32_16x16x32_bf16 v[72:75], v[128:131], v[192:195], v[72:75]
	v_mfma_f32_16x16x32_bf16 v[68:71], v[148:151], v[192:195], v[68:71]
	s_barrier
	s_setprio 0
	s_add_i32 s8, s10, s82
	v_lshl_add_u64 v[196:197], v[196:197], 0, s[68:69]
	s_mov_b32 m0, s8
	ds_read_b128 v[160:163], v245 offset:49152
	ds_read_b128 v[168:171], v245 offset:50176
	ds_read_b128 v[172:175], v245 offset:51200
	ds_read_b128 v[176:179], v245 offset:52224
	ds_read_b128 v[180:183], v245 offset:53248
	ds_read_b128 v[184:187], v245 offset:54272
	ds_read_b128 v[188:191], v245 offset:55296
	ds_read_b128 v[192:195], v245 offset:56320
	global_load_lds_dwordx4 v[196:197], off
	s_add_i32 m0, s8, 0x2000
	s_add_u32 s8, s42, 0x160080
	v_lshl_add_u64 v[196:197], v[198:199], 0, s[68:69]
	s_addc_u32 s9, s43, 0
	s_add_i32 s10, s11, s82
	global_load_lds_dwordx4 v[196:197], off
	v_lshl_add_u64 v[196:197], s[8:9], 0, v[2:3]
	s_mov_b32 m0, s10
	s_nop 0
	global_load_lds_dwordx4 v[196:197], off
	v_lshl_add_u64 v[196:197], s[8:9], 0, v[218:219]
	s_add_i32 m0, s10, 0x2000
	s_nop 0
	global_load_lds_dwordx4 v[196:197], off
	v_lshl_add_u64 v[196:197], v[200:201], 0, s[68:69]
	s_mov_b32 m0, s72
	s_nop 0
	global_load_lds_dwordx4 v[196:197], off
	v_lshl_add_u64 v[196:197], v[202:203], 0, s[68:69]
	s_mov_b32 m0, s88
	s_nop 0
	global_load_lds_dwordx4 v[196:197], off
	s_waitcnt vmcnt(8)
	s_waitcnt lgkmcnt(0)
	s_setprio 1
	s_barrier
	v_mfma_f32_16x16x32_bf16 v[64:67], v[92:95], v[160:163], v[64:67]
	v_mfma_f32_16x16x32_bf16 v[60:63], v[108:111], v[160:163], v[60:63]
	v_mfma_f32_16x16x32_bf16 v[48:51], v[92:95], v[172:175], v[48:51]
	v_mfma_f32_16x16x32_bf16 v[44:47], v[108:111], v[172:175], v[44:47]
	v_mfma_f32_16x16x32_bf16 v[32:35], v[92:95], v[180:183], v[32:35]
	v_mfma_f32_16x16x32_bf16 v[28:31], v[108:111], v[180:183], v[28:31]
	v_mfma_f32_16x16x32_bf16 v[16:19], v[92:95], v[188:191], v[16:19]
	v_mfma_f32_16x16x32_bf16 v[12:15], v[108:111], v[188:191], v[12:15]
	v_mfma_f32_16x16x32_bf16 v[64:67], v[100:103], v[168:171], v[64:67]
	v_mfma_f32_16x16x32_bf16 v[60:63], v[112:115], v[168:171], v[60:63]
	v_mfma_f32_16x16x32_bf16 v[48:51], v[100:103], v[176:179], v[48:51]
	v_mfma_f32_16x16x32_bf16 v[44:47], v[112:115], v[176:179], v[44:47]
	v_mfma_f32_16x16x32_bf16 v[32:35], v[100:103], v[184:187], v[32:35]
	v_mfma_f32_16x16x32_bf16 v[28:31], v[112:115], v[184:187], v[28:31]
	v_mfma_f32_16x16x32_bf16 v[16:19], v[100:103], v[192:195], v[16:19]
	v_mfma_f32_16x16x32_bf16 v[12:15], v[112:115], v[192:195], v[12:15]
	s_setprio 0
	s_setprio 1
	v_mfma_f32_16x16x32_bf16 v[56:59], v[116:119], v[160:163], v[56:59]
	v_mfma_f32_16x16x32_bf16 v[52:55], v[140:143], v[160:163], v[52:55]
	v_mfma_f32_16x16x32_bf16 v[40:43], v[116:119], v[172:175], v[40:43]
	v_mfma_f32_16x16x32_bf16 v[36:39], v[140:143], v[172:175], v[36:39]
	v_mfma_f32_16x16x32_bf16 v[24:27], v[116:119], v[180:183], v[24:27]
	v_mfma_f32_16x16x32_bf16 v[20:23], v[140:143], v[180:183], v[20:23]
	v_mfma_f32_16x16x32_bf16 v[8:11], v[116:119], v[188:191], v[8:11]
	v_mfma_f32_16x16x32_bf16 v[4:7], v[140:143], v[188:191], v[4:7]
	v_mfma_f32_16x16x32_bf16 v[56:59], v[128:131], v[168:171], v[56:59]
	v_mfma_f32_16x16x32_bf16 v[52:55], v[148:151], v[168:171], v[52:55]
	v_mfma_f32_16x16x32_bf16 v[40:43], v[128:131], v[176:179], v[40:43]
	v_mfma_f32_16x16x32_bf16 v[36:39], v[148:151], v[176:179], v[36:39]
	v_mfma_f32_16x16x32_bf16 v[24:27], v[128:131], v[184:187], v[24:27]
	v_mfma_f32_16x16x32_bf16 v[20:23], v[148:151], v[184:187], v[20:23]
	v_mfma_f32_16x16x32_bf16 v[8:11], v[128:131], v[192:195], v[8:11]
	v_mfma_f32_16x16x32_bf16 v[4:7], v[148:151], v[192:195], v[4:7]
	s_barrier
	s_setprio 0
	s_add_i32 s7, s7, 2
	s_add_u32 s5, s5, 0x100
	s_addc_u32 s6, s6, 0
	s_cmpk_gt_u32 s7, 0x55
	s_mov_b64 s[38:39], s[40:41]
.LBB0_1134:
	s_add_u32 s40, s38, 0x100
	s_addc_u32 s41, s39, 0
	s_add_i32 s8, 0, 0x10000
	s_cmpk_eq_i32 s7, 0x54
	s_cselect_b32 s45, s61, s41
	s_cselect_b32 s44, s60, s40
	s_cselect_b32 s43, s63, s6
	s_cselect_b32 s42, s62, s5
	s_add_i32 s10, 0, 0x14000
	v_add_u32_e32 v112, s8, v242
	v_add_u32_e32 v148, s10, v242
	ds_read_b128 v[92:95], v112
	ds_read_b128 v[100:103], v112 offset:1024
	ds_read_b128 v[108:111], v112 offset:2048
	ds_read_b128 v[112:115], v112 offset:3072
	ds_read_b128 v[116:119], v148
	ds_read_b128 v[128:131], v148 offset:1024
	ds_read_b128 v[140:143], v148 offset:2048
	ds_read_b128 v[148:151], v148 offset:3072
	v_lshl_add_u64 v[196:197], s[38:39], 0, v[222:223]
	s_add_i32 m0, s83, 0xc000
	ds_read_b128 v[160:163], v245
	ds_read_b128 v[168:171], v245 offset:1024
	ds_read_b128 v[172:175], v245 offset:2048
	ds_read_b128 v[176:179], v245 offset:3072
	ds_read_b128 v[180:183], v245 offset:4096
	ds_read_b128 v[184:187], v245 offset:5120
	ds_read_b128 v[188:191], v245 offset:6144
	ds_read_b128 v[192:195], v245 offset:7168
	global_load_lds_dwordx4 v[196:197], off
	v_lshl_add_u64 v[196:197], s[38:39], 0, v[220:221]
	s_add_i32 m0, s83, 0xe000
	s_nop 0
	global_load_lds_dwordx4 v[196:197], off
	s_waitcnt vmcnt(8)
	s_waitcnt lgkmcnt(0)
	s_setprio 1
	s_barrier
	v_mfma_f32_16x16x32_bf16 v[164:167], v[92:95], v[160:163], v[164:167]
	v_mfma_f32_16x16x32_bf16 v[156:159], v[108:111], v[160:163], v[156:159]
	v_mfma_f32_16x16x32_bf16 v[136:139], v[92:95], v[172:175], v[136:139]
	v_mfma_f32_16x16x32_bf16 v[132:135], v[108:111], v[172:175], v[132:135]
	v_mfma_f32_16x16x32_bf16 v[104:107], v[92:95], v[180:183], v[104:107]
	v_mfma_f32_16x16x32_bf16 v[96:99], v[108:111], v[180:183], v[96:99]
	v_mfma_f32_16x16x32_bf16 v[80:83], v[92:95], v[188:191], v[80:83]
	v_mfma_f32_16x16x32_bf16 v[76:79], v[108:111], v[188:191], v[76:79]
	v_mfma_f32_16x16x32_bf16 v[164:167], v[100:103], v[168:171], v[164:167]
	v_mfma_f32_16x16x32_bf16 v[156:159], v[112:115], v[168:171], v[156:159]
	v_mfma_f32_16x16x32_bf16 v[136:139], v[100:103], v[176:179], v[136:139]
	v_mfma_f32_16x16x32_bf16 v[132:135], v[112:115], v[176:179], v[132:135]
	v_mfma_f32_16x16x32_bf16 v[104:107], v[100:103], v[184:187], v[104:107]
	v_mfma_f32_16x16x32_bf16 v[96:99], v[112:115], v[184:187], v[96:99]
	v_mfma_f32_16x16x32_bf16 v[80:83], v[100:103], v[192:195], v[80:83]
	v_mfma_f32_16x16x32_bf16 v[76:79], v[112:115], v[192:195], v[76:79]
	s_setprio 0
	s_setprio 1
	v_mfma_f32_16x16x32_bf16 v[152:155], v[116:119], v[160:163], v[152:155]
	v_mfma_f32_16x16x32_bf16 v[144:147], v[140:143], v[160:163], v[144:147]
	v_mfma_f32_16x16x32_bf16 v[124:127], v[116:119], v[172:175], v[124:127]
	v_mfma_f32_16x16x32_bf16 v[120:123], v[140:143], v[172:175], v[120:123]
	v_mfma_f32_16x16x32_bf16 v[88:91], v[116:119], v[180:183], v[88:91]
	v_mfma_f32_16x16x32_bf16 v[84:87], v[140:143], v[180:183], v[84:87]
	v_mfma_f32_16x16x32_bf16 v[72:75], v[116:119], v[188:191], v[72:75]
	v_mfma_f32_16x16x32_bf16 v[68:71], v[140:143], v[188:191], v[68:71]
	v_mfma_f32_16x16x32_bf16 v[152:155], v[128:131], v[168:171], v[152:155]
	v_mfma_f32_16x16x32_bf16 v[144:147], v[148:151], v[168:171], v[144:147]
	v_mfma_f32_16x16x32_bf16 v[124:127], v[128:131], v[176:179], v[124:127]
	v_mfma_f32_16x16x32_bf16 v[120:123], v[148:151], v[176:179], v[120:123]
	v_mfma_f32_16x16x32_bf16 v[88:91], v[128:131], v[184:187], v[88:91]
	v_mfma_f32_16x16x32_bf16 v[84:87], v[148:151], v[184:187], v[84:87]
	v_mfma_f32_16x16x32_bf16 v[72:75], v[128:131], v[192:195], v[72:75]
	v_mfma_f32_16x16x32_bf16 v[68:71], v[148:151], v[192:195], v[68:71]
	s_barrier
	s_setprio 0
	s_add_i32 s8, s8, s82
	v_lshl_add_u64 v[196:197], s[42:43], 0, v[2:3]
	s_mov_b32 m0, s8
	ds_read_b128 v[160:163], v245 offset:16384
	ds_read_b128 v[168:171], v245 offset:17408
	ds_read_b128 v[172:175], v245 offset:18432
	ds_read_b128 v[176:179], v245 offset:19456
	ds_read_b128 v[180:183], v245 offset:20480
	ds_read_b128 v[184:187], v245 offset:21504
	ds_read_b128 v[188:191], v245 offset:22528
	ds_read_b128 v[192:195], v245 offset:23552
	global_load_lds_dwordx4 v[196:197], off
	s_add_i32 m0, s8, 0x2000
	s_add_u32 s8, s42, 0x160000
	v_lshl_add_u64 v[198:199], s[42:43], 0, v[218:219]
	s_addc_u32 s9, s43, 0
	s_add_i32 s10, s10, s82
	global_load_lds_dwordx4 v[198:199], off
	v_lshl_add_u64 v[200:201], s[8:9], 0, v[2:3]
	s_mov_b32 m0, s10
	v_lshl_add_u64 v[202:203], s[44:45], 0, v[216:217]
	global_load_lds_dwordx4 v[200:201], off
	v_lshl_add_u64 v[200:201], s[8:9], 0, v[218:219]
	s_add_i32 m0, s10, 0x2000
	s_nop 0
	global_load_lds_dwordx4 v[200:201], off
	v_lshl_add_u64 v[200:201], s[44:45], 0, v[0:1]
	s_mov_b32 m0, s83
	s_nop 0
	global_load_lds_dwordx4 v[200:201], off
	s_mov_b32 m0, s84
	s_nop 0
	global_load_lds_dwordx4 v[202:203], off
	s_waitcnt vmcnt(8)
	s_waitcnt lgkmcnt(0)
	s_setprio 1
	s_barrier
	v_mfma_f32_16x16x32_bf16 v[64:67], v[92:95], v[160:163], v[64:67]
	v_mfma_f32_16x16x32_bf16 v[60:63], v[108:111], v[160:163], v[60:63]
	v_mfma_f32_16x16x32_bf16 v[48:51], v[92:95], v[172:175], v[48:51]
	v_mfma_f32_16x16x32_bf16 v[44:47], v[108:111], v[172:175], v[44:47]
	v_mfma_f32_16x16x32_bf16 v[32:35], v[92:95], v[180:183], v[32:35]
	v_mfma_f32_16x16x32_bf16 v[28:31], v[108:111], v[180:183], v[28:31]
	v_mfma_f32_16x16x32_bf16 v[16:19], v[92:95], v[188:191], v[16:19]
	v_mfma_f32_16x16x32_bf16 v[12:15], v[108:111], v[188:191], v[12:15]
	v_mfma_f32_16x16x32_bf16 v[64:67], v[100:103], v[168:171], v[64:67]
	v_mfma_f32_16x16x32_bf16 v[60:63], v[112:115], v[168:171], v[60:63]
	v_mfma_f32_16x16x32_bf16 v[48:51], v[100:103], v[176:179], v[48:51]
	v_mfma_f32_16x16x32_bf16 v[44:47], v[112:115], v[176:179], v[44:47]
	v_mfma_f32_16x16x32_bf16 v[32:35], v[100:103], v[184:187], v[32:35]
	v_mfma_f32_16x16x32_bf16 v[28:31], v[112:115], v[184:187], v[28:31]
	v_mfma_f32_16x16x32_bf16 v[16:19], v[100:103], v[192:195], v[16:19]
	v_mfma_f32_16x16x32_bf16 v[12:15], v[112:115], v[192:195], v[12:15]
	s_setprio 0
	s_setprio 1
	v_mfma_f32_16x16x32_bf16 v[56:59], v[116:119], v[160:163], v[56:59]
	v_mfma_f32_16x16x32_bf16 v[52:55], v[140:143], v[160:163], v[52:55]
	v_mfma_f32_16x16x32_bf16 v[40:43], v[116:119], v[172:175], v[40:43]
	v_mfma_f32_16x16x32_bf16 v[36:39], v[140:143], v[172:175], v[36:39]
	v_mfma_f32_16x16x32_bf16 v[24:27], v[116:119], v[180:183], v[24:27]
	v_mfma_f32_16x16x32_bf16 v[20:23], v[140:143], v[180:183], v[20:23]
	v_mfma_f32_16x16x32_bf16 v[8:11], v[116:119], v[188:191], v[8:11]
	v_mfma_f32_16x16x32_bf16 v[4:7], v[140:143], v[188:191], v[4:7]
	v_mfma_f32_16x16x32_bf16 v[56:59], v[128:131], v[168:171], v[56:59]
	v_mfma_f32_16x16x32_bf16 v[52:55], v[148:151], v[168:171], v[52:55]
	v_mfma_f32_16x16x32_bf16 v[40:43], v[128:131], v[176:179], v[40:43]
	v_mfma_f32_16x16x32_bf16 v[36:39], v[148:151], v[176:179], v[36:39]
	v_mfma_f32_16x16x32_bf16 v[24:27], v[128:131], v[184:187], v[24:27]
	v_mfma_f32_16x16x32_bf16 v[20:23], v[148:151], v[184:187], v[20:23]
	v_mfma_f32_16x16x32_bf16 v[8:11], v[128:131], v[192:195], v[8:11]
	v_mfma_f32_16x16x32_bf16 v[4:7], v[148:151], v[192:195], v[4:7]
	s_barrier
	s_setprio 0
	s_add_i32 s10, 0, 0x18000
	s_add_i32 s11, 0, 0x1c000
	v_add_u32_e32 v112, s10, v242
	v_add_u32_e32 v148, s11, v242
	ds_read_b128 v[92:95], v112
	ds_read_b128 v[100:103], v112 offset:1024
	ds_read_b128 v[108:111], v112 offset:2048
	ds_read_b128 v[112:115], v112 offset:3072
	ds_read_b128 v[116:119], v148
	ds_read_b128 v[128:131], v148 offset:1024
	ds_read_b128 v[140:143], v148 offset:2048
	ds_read_b128 v[148:151], v148 offset:3072
	s_add_u32 s8, s44, 0x160000
	s_addc_u32 s9, s45, 0
	s_mov_b32 m0, s85
	v_lshl_add_u64 v[204:205], s[8:9], 0, v[0:1]
	ds_read_b128 v[160:163], v245 offset:32768
	ds_read_b128 v[168:171], v245 offset:33792
	ds_read_b128 v[172:175], v245 offset:34816
	ds_read_b128 v[176:179], v245 offset:35840
	ds_read_b128 v[180:183], v245 offset:36864
	ds_read_b128 v[184:187], v245 offset:37888
	ds_read_b128 v[188:191], v245 offset:38912
	ds_read_b128 v[192:195], v245 offset:39936
	global_load_lds_dwordx4 v[204:205], off
	v_lshl_add_u64 v[204:205], s[8:9], 0, v[216:217]
	s_mov_b32 m0, s87
	s_nop 0
	global_load_lds_dwordx4 v[204:205], off
	s_waitcnt vmcnt(8)
	s_waitcnt lgkmcnt(0)
	s_setprio 1
	s_barrier
	v_mfma_f32_16x16x32_bf16 v[164:167], v[92:95], v[160:163], v[164:167]
	v_mfma_f32_16x16x32_bf16 v[156:159], v[108:111], v[160:163], v[156:159]
	v_mfma_f32_16x16x32_bf16 v[136:139], v[92:95], v[172:175], v[136:139]
	v_mfma_f32_16x16x32_bf16 v[132:135], v[108:111], v[172:175], v[132:135]
	v_mfma_f32_16x16x32_bf16 v[104:107], v[92:95], v[180:183], v[104:107]
	v_mfma_f32_16x16x32_bf16 v[96:99], v[108:111], v[180:183], v[96:99]
	v_mfma_f32_16x16x32_bf16 v[80:83], v[92:95], v[188:191], v[80:83]
	v_mfma_f32_16x16x32_bf16 v[76:79], v[108:111], v[188:191], v[76:79]
	v_mfma_f32_16x16x32_bf16 v[164:167], v[100:103], v[168:171], v[164:167]
	v_mfma_f32_16x16x32_bf16 v[156:159], v[112:115], v[168:171], v[156:159]
	v_mfma_f32_16x16x32_bf16 v[136:139], v[100:103], v[176:179], v[136:139]
	v_mfma_f32_16x16x32_bf16 v[132:135], v[112:115], v[176:179], v[132:135]
	v_mfma_f32_16x16x32_bf16 v[104:107], v[100:103], v[184:187], v[104:107]
	v_mfma_f32_16x16x32_bf16 v[96:99], v[112:115], v[184:187], v[96:99]
	v_mfma_f32_16x16x32_bf16 v[80:83], v[100:103], v[192:195], v[80:83]
	v_mfma_f32_16x16x32_bf16 v[76:79], v[112:115], v[192:195], v[76:79]
	s_setprio 0
	s_setprio 1
	v_mfma_f32_16x16x32_bf16 v[152:155], v[116:119], v[160:163], v[152:155]
	v_mfma_f32_16x16x32_bf16 v[144:147], v[140:143], v[160:163], v[144:147]
	v_mfma_f32_16x16x32_bf16 v[124:127], v[116:119], v[172:175], v[124:127]
	v_mfma_f32_16x16x32_bf16 v[120:123], v[140:143], v[172:175], v[120:123]
	v_mfma_f32_16x16x32_bf16 v[88:91], v[116:119], v[180:183], v[88:91]
	v_mfma_f32_16x16x32_bf16 v[84:87], v[140:143], v[180:183], v[84:87]
	v_mfma_f32_16x16x32_bf16 v[72:75], v[116:119], v[188:191], v[72:75]
	v_mfma_f32_16x16x32_bf16 v[68:71], v[140:143], v[188:191], v[68:71]
	v_mfma_f32_16x16x32_bf16 v[152:155], v[128:131], v[168:171], v[152:155]
	v_mfma_f32_16x16x32_bf16 v[144:147], v[148:151], v[168:171], v[144:147]
	v_mfma_f32_16x16x32_bf16 v[124:127], v[128:131], v[176:179], v[124:127]
	v_mfma_f32_16x16x32_bf16 v[120:123], v[148:151], v[176:179], v[120:123]
	v_mfma_f32_16x16x32_bf16 v[88:91], v[128:131], v[184:187], v[88:91]
	v_mfma_f32_16x16x32_bf16 v[84:87], v[148:151], v[184:187], v[84:87]
	v_mfma_f32_16x16x32_bf16 v[72:75], v[128:131], v[192:195], v[72:75]
	v_mfma_f32_16x16x32_bf16 v[68:71], v[148:151], v[192:195], v[68:71]
	s_barrier
	s_setprio 0
	s_add_i32 s8, s10, s82
	v_lshl_add_u64 v[196:197], v[196:197], 0, s[68:69]
	s_mov_b32 m0, s8
	ds_read_b128 v[160:163], v245 offset:49152
	ds_read_b128 v[168:171], v245 offset:50176
	ds_read_b128 v[172:175], v245 offset:51200
	ds_read_b128 v[176:179], v245 offset:52224
	ds_read_b128 v[180:183], v245 offset:53248
	ds_read_b128 v[184:187], v245 offset:54272
	ds_read_b128 v[188:191], v245 offset:55296
	ds_read_b128 v[192:195], v245 offset:56320
	global_load_lds_dwordx4 v[196:197], off
	s_add_i32 m0, s8, 0x2000
	s_add_u32 s8, s42, 0x160080
	v_lshl_add_u64 v[196:197], v[198:199], 0, s[68:69]
	s_addc_u32 s9, s43, 0
	s_add_i32 s10, s11, s82
	global_load_lds_dwordx4 v[196:197], off
	v_lshl_add_u64 v[196:197], s[8:9], 0, v[2:3]
	s_mov_b32 m0, s10
	s_nop 0
	global_load_lds_dwordx4 v[196:197], off
	v_lshl_add_u64 v[196:197], s[8:9], 0, v[218:219]
	s_add_i32 m0, s10, 0x2000
	s_nop 0
	global_load_lds_dwordx4 v[196:197], off
	v_lshl_add_u64 v[196:197], v[200:201], 0, s[68:69]
	s_mov_b32 m0, s72
	s_nop 0
	global_load_lds_dwordx4 v[196:197], off
	v_lshl_add_u64 v[196:197], v[202:203], 0, s[68:69]
	s_mov_b32 m0, s88
	s_nop 0
	global_load_lds_dwordx4 v[196:197], off
	s_waitcnt vmcnt(8)
	s_waitcnt lgkmcnt(0)
	s_setprio 1
	s_barrier
	v_mfma_f32_16x16x32_bf16 v[64:67], v[92:95], v[160:163], v[64:67]
	v_mfma_f32_16x16x32_bf16 v[60:63], v[108:111], v[160:163], v[60:63]
	v_mfma_f32_16x16x32_bf16 v[48:51], v[92:95], v[172:175], v[48:51]
	v_mfma_f32_16x16x32_bf16 v[44:47], v[108:111], v[172:175], v[44:47]
	v_mfma_f32_16x16x32_bf16 v[32:35], v[92:95], v[180:183], v[32:35]
	v_mfma_f32_16x16x32_bf16 v[28:31], v[108:111], v[180:183], v[28:31]
	v_mfma_f32_16x16x32_bf16 v[16:19], v[92:95], v[188:191], v[16:19]
	v_mfma_f32_16x16x32_bf16 v[12:15], v[108:111], v[188:191], v[12:15]
	v_mfma_f32_16x16x32_bf16 v[64:67], v[100:103], v[168:171], v[64:67]
	v_mfma_f32_16x16x32_bf16 v[60:63], v[112:115], v[168:171], v[60:63]
	v_mfma_f32_16x16x32_bf16 v[48:51], v[100:103], v[176:179], v[48:51]
	v_mfma_f32_16x16x32_bf16 v[44:47], v[112:115], v[176:179], v[44:47]
	v_mfma_f32_16x16x32_bf16 v[32:35], v[100:103], v[184:187], v[32:35]
	v_mfma_f32_16x16x32_bf16 v[28:31], v[112:115], v[184:187], v[28:31]
	v_mfma_f32_16x16x32_bf16 v[16:19], v[100:103], v[192:195], v[16:19]
	v_mfma_f32_16x16x32_bf16 v[12:15], v[112:115], v[192:195], v[12:15]
	s_setprio 0
	s_setprio 1
	v_mfma_f32_16x16x32_bf16 v[56:59], v[116:119], v[160:163], v[56:59]
	v_mfma_f32_16x16x32_bf16 v[52:55], v[140:143], v[160:163], v[52:55]
	v_mfma_f32_16x16x32_bf16 v[40:43], v[116:119], v[172:175], v[40:43]
	v_mfma_f32_16x16x32_bf16 v[36:39], v[140:143], v[172:175], v[36:39]
	v_mfma_f32_16x16x32_bf16 v[24:27], v[116:119], v[180:183], v[24:27]
	v_mfma_f32_16x16x32_bf16 v[20:23], v[140:143], v[180:183], v[20:23]
	v_mfma_f32_16x16x32_bf16 v[8:11], v[116:119], v[188:191], v[8:11]
	v_mfma_f32_16x16x32_bf16 v[4:7], v[140:143], v[188:191], v[4:7]
	v_mfma_f32_16x16x32_bf16 v[56:59], v[128:131], v[168:171], v[56:59]
	v_mfma_f32_16x16x32_bf16 v[52:55], v[148:151], v[168:171], v[52:55]
	v_mfma_f32_16x16x32_bf16 v[40:43], v[128:131], v[176:179], v[40:43]
	v_mfma_f32_16x16x32_bf16 v[36:39], v[148:151], v[176:179], v[36:39]
	v_mfma_f32_16x16x32_bf16 v[24:27], v[128:131], v[184:187], v[24:27]
	v_mfma_f32_16x16x32_bf16 v[20:23], v[148:151], v[184:187], v[20:23]
	v_mfma_f32_16x16x32_bf16 v[8:11], v[128:131], v[192:195], v[8:11]
	v_mfma_f32_16x16x32_bf16 v[4:7], v[148:151], v[192:195], v[4:7]
	s_barrier
	s_setprio 0
	s_add_i32 s7, s7, 2
	s_add_u32 s5, s5, 0x100
	s_addc_u32 s6, s6, 0
	s_cmpk_gt_u32 s7, 0x55
	s_mov_b64 s[38:39], s[40:41]
	s_cbranch_scc0 .LBB0_1134
	s_and_b64 vcc, exec, s[52:53]
	s_cbranch_vccz .LBB0_1137
	s_barrier
